# baseline (speedup 1.0000x reference)
; #define PG8_STAGE(bufoff, gbase, voff) do { _Pragma("unroll") for (int _i = 0; _i < 2; ++_i) \
;         __builtin_amdgcn_global_load_lds((const unsigned*)((const char*)(gbase) + (voff)[_i]), (PG8_LAS unsigned*)(lds + (bufoff) + ldsw + _i * 8192), 16, 0, 0); } while (0)
; #define PG8_LDA(dst, b, h) do { _Pragma("unroll") for (int m = 0; m < 4; ++m) _Pragma("unroll") for (int k = 0; k < 2; ++k) dst[m][k] = *(const PG8_LAS bf16x8*)(lds + PG8_SA(b, h) + aoff + m * 2048 + k * 1024); } while (0)
; #define PG8_LDB(dst, b, h) do { _Pragma("unroll") for (int n = 0; n < 2; ++n) _Pragma("unroll") for (int k = 0; k < 2; ++k) dst[n][k] = *(const PG8_LAS bf16x8*)(lds + PG8_SB(b, h) + boff + n * 2048 + k * 1024); } while (0)
; #define PG8_MMA(ai, bj, At, Bt) do { __builtin_amdgcn_s_setprio(1); _Pragma("unroll") for (int m = 0; m < 4; ++m) _Pragma("unroll") for (int n = 0; n < 2; ++n) _Pragma("unroll") for (int k = 0; k < 2; ++k) \
;         acc[ai][bj][m][n] = __builtin_amdgcn_mfma_f32_16x16x32_bf16(Bt[n][k], At[m][k], acc[ai][bj][m][n], 0, 0, 0); __builtin_amdgcn_s_setprio(0); } while (0)
; #define PG8_BAR __builtin_amdgcn_s_barrier()
; template <class Epi, class Sched, bool ALIGN_EPI = false, bool SP2 = false>
; __device__ __forceinline__ void gemm_phase(PG8_LAS unsigned char* lds, const Gemm g, const Sched& S, const Epi& E, const int wid) {
;     ...
;             PG8_LDB(B0, 0, 0); PG8_LDB(B1, 0, 1); PG8_SCHED; PG8_LDA(At, 0, 0); PG8_STAGE(PG8_SA(1, 1), a1 + hstep, voffA);
;             PG8_WAIT_V(8); PG8_WAIT_L(0); PG8_BAR; PG8_MMA(0, 0, At, B0); PG8_MMA(0, 1, At, B1); PG8_BAR; PG8_SCHED;
;             PG8_LDA(At, 0, 1); PG8_STAGE(PG8_SB(0, 0), b2, voffB); PG8_STAGE(PG8_SB(0, 1), b2 + hstep, voffB); PG8_STAGE(PG8_SA(0, 0), a2, voffA);
;             PG8_WAIT_V(8); PG8_WAIT_L(0); PG8_BAR; PG8_MMA(1, 0, At, B0); PG8_MMA(1, 1, At, B1); PG8_BAR; PG8_SCHED;
;             PG8_LDB(B0, 1, 0); PG8_LDB(B1, 1, 1); PG8_SCHED; PG8_LDA(At, 1, 0); PG8_STAGE(PG8_SA(0, 1), a2 + hstep, voffA);
;             PG8_WAIT_V(8); PG8_WAIT_L(0); PG8_BAR; PG8_MMA(0, 0, At, B0); PG8_MMA(0, 1, At, B1); PG8_BAR; PG8_SCHED;
;             PG8_LDA(At, 1, 1); PG8_STAGE(PG8_SB(1, 0), b3, voffB); PG8_STAGE(PG8_SB(1, 1), b3 + hstep, voffB); PG8_STAGE(PG8_SA(1, 0), a3, voffA);
;             PG8_WAIT_V(8); PG8_WAIT_L(0); PG8_BAR; PG8_MMA(1, 0, At, B0); PG8_MMA(1, 1, At, B1); PG8_BAR; PG8_SCHED;
.LBB0_269:
	ds_read_b128 v[144:147], v151
	ds_read_b128 v[154:157], v151 offset:1024
	ds_read_b128 v[158:161], v151 offset:2048
	ds_read_b128 v[162:165], v151 offset:3072
	ds_read_b128 v[166:169], v152
	ds_read_b128 v[170:173], v152 offset:1024
	ds_read_b128 v[174:177], v152 offset:2048
	ds_read_b128 v[178:181], v152 offset:3072
	s_add_u32 s24, s22, 0xfffc0080
	s_addc_u32 s25, s23, -1
	s_cmp_eq_u32 s48, 12
	s_cselect_b32 s27, s15, s25
	s_cselect_b32 s26, s44, s24
	s_cselect_b32 s25, s13, s47
	s_cselect_b32 s24, s45, s46
	v_lshl_add_u64 v[206:207], s[22:23], 0, v[136:137]
	s_add_i32 m0, s21, 0xc000
	ds_read_b128 v[182:185], v153
	ds_read_b128 v[186:189], v153 offset:1024
	ds_read_b128 v[190:193], v153 offset:2048
	ds_read_b128 v[194:197], v153 offset:3072
	ds_read_b128 v[198:201], v153 offset:4096
	ds_read_b128 v[202:205], v153 offset:5120
	ds_read_b128 v[212:215], v153 offset:6144
	ds_read_b128 v[216:219], v153 offset:7168
	global_load_lds_dwordx4 v[206:207], off
	v_lshl_add_u64 v[206:207], s[22:23], 0, v[138:139]
	s_add_i32 m0, s21, 0xe000
	s_nop 0
	global_load_lds_dwordx4 v[206:207], off
	s_waitcnt vmcnt(8)
	s_waitcnt lgkmcnt(0)
	s_barrier
	s_setprio 1
	s_waitcnt lgkmcnt(0)
	v_mfma_f32_16x16x32_bf16 v[124:127], v[144:147], v[182:185], v[124:127]
	v_mfma_f32_16x16x32_bf16 v[116:119], v[158:161], v[182:185], v[116:119]
	v_mfma_f32_16x16x32_bf16 v[108:111], v[144:147], v[190:193], v[108:111]
	v_mfma_f32_16x16x32_bf16 v[100:103], v[158:161], v[190:193], v[100:103]
	v_mfma_f32_16x16x32_bf16 v[92:95], v[144:147], v[198:201], v[92:95]
	v_mfma_f32_16x16x32_bf16 v[84:87], v[158:161], v[198:201], v[84:87]
	v_mfma_f32_16x16x32_bf16 v[76:79], v[144:147], v[212:215], v[76:79]
	v_mfma_f32_16x16x32_bf16 v[68:71], v[158:161], v[212:215], v[68:71]
	v_mfma_f32_16x16x32_bf16 v[124:127], v[154:157], v[186:189], v[124:127]
	v_mfma_f32_16x16x32_bf16 v[116:119], v[162:165], v[186:189], v[116:119]
	v_mfma_f32_16x16x32_bf16 v[108:111], v[154:157], v[194:197], v[108:111]
	v_mfma_f32_16x16x32_bf16 v[100:103], v[162:165], v[194:197], v[100:103]
	v_mfma_f32_16x16x32_bf16 v[92:95], v[154:157], v[202:205], v[92:95]
	v_mfma_f32_16x16x32_bf16 v[84:87], v[162:165], v[202:205], v[84:87]
	v_mfma_f32_16x16x32_bf16 v[76:79], v[154:157], v[216:219], v[76:79]
	v_mfma_f32_16x16x32_bf16 v[68:71], v[162:165], v[216:219], v[68:71]
	s_setprio 0
	s_setprio 1
	v_mfma_f32_16x16x32_bf16 v[120:123], v[166:169], v[182:185], v[120:123]
	v_mfma_f32_16x16x32_bf16 v[112:115], v[174:177], v[182:185], v[112:115]
	v_mfma_f32_16x16x32_bf16 v[104:107], v[166:169], v[190:193], v[104:107]
	v_mfma_f32_16x16x32_bf16 v[96:99], v[174:177], v[190:193], v[96:99]
	v_mfma_f32_16x16x32_bf16 v[88:91], v[166:169], v[198:201], v[88:91]
	v_mfma_f32_16x16x32_bf16 v[80:83], v[174:177], v[198:201], v[80:83]
	v_mfma_f32_16x16x32_bf16 v[72:75], v[166:169], v[212:215], v[72:75]
	v_mfma_f32_16x16x32_bf16 v[64:67], v[174:177], v[212:215], v[64:67]
	v_mfma_f32_16x16x32_bf16 v[120:123], v[170:173], v[186:189], v[120:123]
	v_mfma_f32_16x16x32_bf16 v[112:115], v[178:181], v[186:189], v[112:115]
	v_mfma_f32_16x16x32_bf16 v[104:107], v[170:173], v[194:197], v[104:107]
	v_mfma_f32_16x16x32_bf16 v[96:99], v[178:181], v[194:197], v[96:99]
	v_mfma_f32_16x16x32_bf16 v[88:91], v[170:173], v[202:205], v[88:91]
	v_mfma_f32_16x16x32_bf16 v[80:83], v[178:181], v[202:205], v[80:83]
	v_mfma_f32_16x16x32_bf16 v[72:75], v[170:173], v[216:219], v[72:75]
	v_mfma_f32_16x16x32_bf16 v[64:67], v[178:181], v[216:219], v[64:67]
	s_setprio 0
	s_barrier
	s_add_i32 s49, s40, s9
	v_lshl_add_u64 v[206:207], s[24:25], 0, v[132:133]
	s_mov_b32 m0, s49
	ds_read_b128 v[182:185], v153 offset:16384
	ds_read_b128 v[186:189], v153 offset:17408
	ds_read_b128 v[190:193], v153 offset:18432
	ds_read_b128 v[194:197], v153 offset:19456
	ds_read_b128 v[198:201], v153 offset:20480
	ds_read_b128 v[202:205], v153 offset:21504
	ds_read_b128 v[212:215], v153 offset:22528
	ds_read_b128 v[216:219], v153 offset:23552
	global_load_lds_dwordx4 v[206:207], off
	s_add_i32 m0, s49, 0x2000
	s_add_u32 s50, s24, 0x40000
	v_lshl_add_u64 v[220:221], s[24:25], 0, v[128:129]
	s_addc_u32 s51, s25, 0
	s_add_i32 s49, s41, s9
	global_load_lds_dwordx4 v[220:221], off
	v_lshl_add_u64 v[222:223], s[50:51], 0, v[132:133]
	s_mov_b32 m0, s49
	v_lshl_add_u64 v[224:225], s[26:27], 0, v[130:131]
	global_load_lds_dwordx4 v[222:223], off
	v_lshl_add_u64 v[222:223], s[50:51], 0, v[128:129]
	s_add_i32 m0, s49, 0x2000
	s_nop 0
	global_load_lds_dwordx4 v[222:223], off
	v_lshl_add_u64 v[222:223], s[26:27], 0, v[134:135]
	s_mov_b32 m0, s21
	s_nop 0
	global_load_lds_dwordx4 v[222:223], off
	s_mov_b32 m0, s30
	s_nop 0
	global_load_lds_dwordx4 v[224:225], off
	s_waitcnt vmcnt(8)
	s_waitcnt lgkmcnt(0)
	s_barrier
; #define PG8_STAGE(bufoff, gbase, voff) do { _Pragma("unroll") for (int _i = 0; _i < 2; ++_i) \
;         __builtin_amdgcn_global_load_lds((const unsigned*)((const char*)(gbase) + (voff)[_i]), (PG8_LAS unsigned*)(lds + (bufoff) + ldsw + _i * 8192), 16, 0, 0); } while (0)
; #define PG8_LDA(dst, b, h) do { _Pragma("unroll") for (int m = 0; m < 4; ++m) _Pragma("unroll") for (int k = 0; k < 2; ++k) dst[m][k] = *(const PG8_LAS bf16x8*)(lds + PG8_SA(b, h) + aoff + m * 2048 + k * 1024); } while (0)
; #define PG8_LDB(dst, b, h) do { _Pragma("unroll") for (int n = 0; n < 2; ++n) _Pragma("unroll") for (int k = 0; k < 2; ++k) dst[n][k] = *(const PG8_LAS bf16x8*)(lds + PG8_SB(b, h) + boff + n * 2048 + k * 1024); } while (0)
; #define PG8_MMA(ai, bj, At, Bt) do { __builtin_amdgcn_s_setprio(1); _Pragma("unroll") for (int m = 0; m < 4; ++m) _Pragma("unroll") for (int n = 0; n < 2; ++n) _Pragma("unroll") for (int k = 0; k < 2; ++k) \
;         acc[ai][bj][m][n] = __builtin_amdgcn_mfma_f32_16x16x32_bf16(Bt[n][k], At[m][k], acc[ai][bj][m][n], 0, 0, 0); __builtin_amdgcn_s_setprio(0); } while (0)
; #define PG8_BAR __builtin_amdgcn_s_barrier()
; template <class Epi, class Sched, bool ALIGN_EPI = false, bool SP2 = false>
; __device__ __forceinline__ void gemm_phase(PG8_LAS unsigned char* lds, const Gemm g, const Sched& S, const Epi& E, const int wid) {
;     ...
;             PG8_LDB(B0, 0, 0); PG8_LDB(B1, 0, 1); PG8_SCHED; PG8_LDA(At, 0, 0); PG8_STAGE(PG8_SA(1, 1), a1 + hstep, voffA);
;             PG8_WAIT_V(8); PG8_WAIT_L(0); PG8_BAR; PG8_MMA(0, 0, At, B0); PG8_MMA(0, 1, At, B1); PG8_BAR; PG8_SCHED;
;             PG8_LDA(At, 0, 1); PG8_STAGE(PG8_SB(0, 0), b2, voffB); PG8_STAGE(PG8_SB(0, 1), b2 + hstep, voffB); PG8_STAGE(PG8_SA(0, 0), a2, voffA);
;             PG8_WAIT_V(8); PG8_WAIT_L(0); PG8_BAR; PG8_MMA(1, 0, At, B0); PG8_MMA(1, 1, At, B1); PG8_BAR; PG8_SCHED;
;             PG8_LDB(B0, 1, 0); PG8_LDB(B1, 1, 1); PG8_SCHED; PG8_LDA(At, 1, 0); PG8_STAGE(PG8_SA(0, 1), a2 + hstep, voffA);
;             PG8_WAIT_V(8); PG8_WAIT_L(0); PG8_BAR; PG8_MMA(0, 0, At, B0); PG8_MMA(0, 1, At, B1); PG8_BAR; PG8_SCHED;
;             PG8_LDA(At, 1, 1); PG8_STAGE(PG8_SB(1, 0), b3, voffB); PG8_STAGE(PG8_SB(1, 1), b3 + hstep, voffB); PG8_STAGE(PG8_SA(1, 0), a3, voffA);
;             PG8_WAIT_V(8); PG8_WAIT_L(0); PG8_BAR; PG8_MMA(1, 0, At, B0); PG8_MMA(1, 1, At, B1); PG8_BAR; PG8_SCHED;
	s_setprio 1
	s_waitcnt lgkmcnt(0)
	v_mfma_f32_16x16x32_bf16 v[60:63], v[144:147], v[182:185], v[60:63]
	v_mfma_f32_16x16x32_bf16 v[52:55], v[158:161], v[182:185], v[52:55]
	v_mfma_f32_16x16x32_bf16 v[44:47], v[144:147], v[190:193], v[44:47]
	v_mfma_f32_16x16x32_bf16 v[36:39], v[158:161], v[190:193], v[36:39]
	v_mfma_f32_16x16x32_bf16 v[28:31], v[144:147], v[198:201], v[28:31]
	v_mfma_f32_16x16x32_bf16 v[20:23], v[158:161], v[198:201], v[20:23]
	v_mfma_f32_16x16x32_bf16 v[12:15], v[144:147], v[212:215], v[12:15]
	v_mfma_f32_16x16x32_bf16 v[4:7], v[158:161], v[212:215], v[4:7]
	v_mfma_f32_16x16x32_bf16 v[60:63], v[154:157], v[186:189], v[60:63]
	v_mfma_f32_16x16x32_bf16 v[52:55], v[162:165], v[186:189], v[52:55]
	v_mfma_f32_16x16x32_bf16 v[44:47], v[154:157], v[194:197], v[44:47]
	v_mfma_f32_16x16x32_bf16 v[36:39], v[162:165], v[194:197], v[36:39]
	v_mfma_f32_16x16x32_bf16 v[28:31], v[154:157], v[202:205], v[28:31]
	v_mfma_f32_16x16x32_bf16 v[20:23], v[162:165], v[202:205], v[20:23]
	v_mfma_f32_16x16x32_bf16 v[12:15], v[154:157], v[216:219], v[12:15]
	v_mfma_f32_16x16x32_bf16 v[4:7], v[162:165], v[216:219], v[4:7]
	s_setprio 0
	s_setprio 1
	v_mfma_f32_16x16x32_bf16 v[56:59], v[166:169], v[182:185], v[56:59]
	v_mfma_f32_16x16x32_bf16 v[48:51], v[174:177], v[182:185], v[48:51]
	v_mfma_f32_16x16x32_bf16 v[40:43], v[166:169], v[190:193], v[40:43]
	v_mfma_f32_16x16x32_bf16 v[32:35], v[174:177], v[190:193], v[32:35]
	v_mfma_f32_16x16x32_bf16 v[24:27], v[166:169], v[198:201], v[24:27]
	v_mfma_f32_16x16x32_bf16 v[16:19], v[174:177], v[198:201], v[16:19]
	v_mfma_f32_16x16x32_bf16 v[8:11], v[166:169], v[212:215], v[8:11]
	v_mfma_f32_16x16x32_bf16 v[0:3], v[174:177], v[212:215], v[0:3]
	v_mfma_f32_16x16x32_bf16 v[56:59], v[170:173], v[186:189], v[56:59]
	v_mfma_f32_16x16x32_bf16 v[48:51], v[178:181], v[186:189], v[48:51]
	v_mfma_f32_16x16x32_bf16 v[40:43], v[170:173], v[194:197], v[40:43]
	v_mfma_f32_16x16x32_bf16 v[32:35], v[178:181], v[194:197], v[32:35]
	v_mfma_f32_16x16x32_bf16 v[24:27], v[170:173], v[202:205], v[24:27]
	v_mfma_f32_16x16x32_bf16 v[16:19], v[178:181], v[202:205], v[16:19]
	v_mfma_f32_16x16x32_bf16 v[8:11], v[170:173], v[216:219], v[8:11]
	v_mfma_f32_16x16x32_bf16 v[0:3], v[178:181], v[216:219], v[0:3]
	s_setprio 0
	s_barrier
	s_add_i32 s49, 0, 0x18000
	s_add_i32 s50, 0, 0x1c000
	v_add_u32_e32 v162, s49, v149
	v_add_u32_e32 v178, s50, v149
	ds_read_b128 v[144:147], v162
	ds_read_b128 v[154:157], v162 offset:1024
	ds_read_b128 v[158:161], v162 offset:2048
	ds_read_b128 v[162:165], v162 offset:3072
	ds_read_b128 v[166:169], v178
	ds_read_b128 v[170:173], v178 offset:1024
	ds_read_b128 v[174:177], v178 offset:2048
	ds_read_b128 v[178:181], v178 offset:3072
	s_add_u32 s26, s26, 0x40000
	s_addc_u32 s27, s27, 0
	s_mov_b32 m0, s31
	v_lshl_add_u64 v[226:227], s[26:27], 0, v[134:135]
	ds_read_b128 v[182:185], v153 offset:32768
	ds_read_b128 v[186:189], v153 offset:33792
	ds_read_b128 v[190:193], v153 offset:34816
	ds_read_b128 v[194:197], v153 offset:35840
	ds_read_b128 v[198:201], v153 offset:36864
	ds_read_b128 v[202:205], v153 offset:37888
	ds_read_b128 v[212:215], v153 offset:38912
	ds_read_b128 v[216:219], v153 offset:39936
	global_load_lds_dwordx4 v[226:227], off
	v_lshl_add_u64 v[226:227], s[26:27], 0, v[130:131]
	s_mov_b32 m0, s33
	s_nop 0
	global_load_lds_dwordx4 v[226:227], off
	s_waitcnt vmcnt(8)
	s_waitcnt lgkmcnt(0)
	s_barrier
	s_setprio 1
	s_waitcnt lgkmcnt(0)
	v_mfma_f32_16x16x32_bf16 v[124:127], v[144:147], v[182:185], v[124:127]
	v_mfma_f32_16x16x32_bf16 v[116:119], v[158:161], v[182:185], v[116:119]
	v_mfma_f32_16x16x32_bf16 v[108:111], v[144:147], v[190:193], v[108:111]
	v_mfma_f32_16x16x32_bf16 v[100:103], v[158:161], v[190:193], v[100:103]
	v_mfma_f32_16x16x32_bf16 v[92:95], v[144:147], v[198:201], v[92:95]
	v_mfma_f32_16x16x32_bf16 v[84:87], v[158:161], v[198:201], v[84:87]
	v_mfma_f32_16x16x32_bf16 v[76:79], v[144:147], v[212:215], v[76:79]
	v_mfma_f32_16x16x32_bf16 v[68:71], v[158:161], v[212:215], v[68:71]
	v_mfma_f32_16x16x32_bf16 v[124:127], v[154:157], v[186:189], v[124:127]
	v_mfma_f32_16x16x32_bf16 v[116:119], v[162:165], v[186:189], v[116:119]
	v_mfma_f32_16x16x32_bf16 v[108:111], v[154:157], v[194:197], v[108:111]
	v_mfma_f32_16x16x32_bf16 v[100:103], v[162:165], v[194:197], v[100:103]
	v_mfma_f32_16x16x32_bf16 v[92:95], v[154:157], v[202:205], v[92:95]
	v_mfma_f32_16x16x32_bf16 v[84:87], v[162:165], v[202:205], v[84:87]
	v_mfma_f32_16x16x32_bf16 v[76:79], v[154:157], v[216:219], v[76:79]
	v_mfma_f32_16x16x32_bf16 v[68:71], v[162:165], v[216:219], v[68:71]
	s_setprio 0
	s_setprio 1
	v_mfma_f32_16x16x32_bf16 v[120:123], v[166:169], v[182:185], v[120:123]
	v_mfma_f32_16x16x32_bf16 v[112:115], v[174:177], v[182:185], v[112:115]
	v_mfma_f32_16x16x32_bf16 v[104:107], v[166:169], v[190:193], v[104:107]
	v_mfma_f32_16x16x32_bf16 v[96:99], v[174:177], v[190:193], v[96:99]
	v_mfma_f32_16x16x32_bf16 v[88:91], v[166:169], v[198:201], v[88:91]
	v_mfma_f32_16x16x32_bf16 v[80:83], v[174:177], v[198:201], v[80:83]
	v_mfma_f32_16x16x32_bf16 v[72:75], v[166:169], v[212:215], v[72:75]
	v_mfma_f32_16x16x32_bf16 v[64:67], v[174:177], v[212:215], v[64:67]
	v_mfma_f32_16x16x32_bf16 v[120:123], v[170:173], v[186:189], v[120:123]
	v_mfma_f32_16x16x32_bf16 v[112:115], v[178:181], v[186:189], v[112:115]
	v_mfma_f32_16x16x32_bf16 v[104:107], v[170:173], v[194:197], v[104:107]
	v_mfma_f32_16x16x32_bf16 v[96:99], v[178:181], v[194:197], v[96:99]
	v_mfma_f32_16x16x32_bf16 v[88:91], v[170:173], v[202:205], v[88:91]
	v_mfma_f32_16x16x32_bf16 v[80:83], v[178:181], v[202:205], v[80:83]
	v_mfma_f32_16x16x32_bf16 v[72:75], v[170:173], v[216:219], v[72:75]
	v_mfma_f32_16x16x32_bf16 v[64:67], v[178:181], v[216:219], v[64:67]
	s_setprio 0
	s_barrier
; #define PG8_STAGE(bufoff, gbase, voff) do { _Pragma("unroll") for (int _i = 0; _i < 2; ++_i) \
;         __builtin_amdgcn_global_load_lds((const unsigned*)((const char*)(gbase) + (voff)[_i]), (PG8_LAS unsigned*)(lds + (bufoff) + ldsw + _i * 8192), 16, 0, 0); } while (0)
; #define PG8_LDA(dst, b, h) do { _Pragma("unroll") for (int m = 0; m < 4; ++m) _Pragma("unroll") for (int k = 0; k < 2; ++k) dst[m][k] = *(const PG8_LAS bf16x8*)(lds + PG8_SA(b, h) + aoff + m * 2048 + k * 1024); } while (0)
; #define PG8_LDB(dst, b, h) do { _Pragma("unroll") for (int n = 0; n < 2; ++n) _Pragma("unroll") for (int k = 0; k < 2; ++k) dst[n][k] = *(const PG8_LAS bf16x8*)(lds + PG8_SB(b, h) + boff + n * 2048 + k * 1024); } while (0)
; #define PG8_MMA(ai, bj, At, Bt) do { __builtin_amdgcn_s_setprio(1); _Pragma("unroll") for (int m = 0; m < 4; ++m) _Pragma("unroll") for (int n = 0; n < 2; ++n) _Pragma("unroll") for (int k = 0; k < 2; ++k) \
;         acc[ai][bj][m][n] = __builtin_amdgcn_mfma_f32_16x16x32_bf16(Bt[n][k], At[m][k], acc[ai][bj][m][n], 0, 0, 0); __builtin_amdgcn_s_setprio(0); } while (0)
; #define PG8_BAR __builtin_amdgcn_s_barrier()
; template <class Epi, class Sched, bool ALIGN_EPI = false, bool SP2 = false>
; __device__ __forceinline__ void gemm_phase(PG8_LAS unsigned char* lds, const Gemm g, const Sched& S, const Epi& E, const int wid) {
;     ...
;             PG8_LDB(B0, 0, 0); PG8_LDB(B1, 0, 1); PG8_SCHED; PG8_LDA(At, 0, 0); PG8_STAGE(PG8_SA(1, 1), a1 + hstep, voffA);
;             PG8_WAIT_V(8); PG8_WAIT_L(0); PG8_BAR; PG8_MMA(0, 0, At, B0); PG8_MMA(0, 1, At, B1); PG8_BAR; PG8_SCHED;
;             PG8_LDA(At, 0, 1); PG8_STAGE(PG8_SB(0, 0), b2, voffB); PG8_STAGE(PG8_SB(0, 1), b2 + hstep, voffB); PG8_STAGE(PG8_SA(0, 0), a2, voffA);
;             PG8_WAIT_V(8); PG8_WAIT_L(0); PG8_BAR; PG8_MMA(1, 0, At, B0); PG8_MMA(1, 1, At, B1); PG8_BAR; PG8_SCHED;
;             PG8_LDB(B0, 1, 0); PG8_LDB(B1, 1, 1); PG8_SCHED; PG8_LDA(At, 1, 0); PG8_STAGE(PG8_SA(0, 1), a2 + hstep, voffA);
;             PG8_WAIT_V(8); PG8_WAIT_L(0); PG8_BAR; PG8_MMA(0, 0, At, B0); PG8_MMA(0, 1, At, B1); PG8_BAR; PG8_SCHED;
;             PG8_LDA(At, 1, 1); PG8_STAGE(PG8_SB(1, 0), b3, voffB); PG8_STAGE(PG8_SB(1, 1), b3 + hstep, voffB); PG8_STAGE(PG8_SA(1, 0), a3, voffA);
;             PG8_WAIT_V(8); PG8_WAIT_L(0); PG8_BAR; PG8_MMA(1, 0, At, B0); PG8_MMA(1, 1, At, B1); PG8_BAR; PG8_SCHED;
	s_add_i32 s26, s49, s9
	v_lshl_add_u64 v[206:207], v[206:207], 0, s[6:7]
	s_mov_b32 m0, s26
	ds_read_b128 v[182:185], v153 offset:49152
	ds_read_b128 v[186:189], v153 offset:50176
	ds_read_b128 v[190:193], v153 offset:51200
	ds_read_b128 v[194:197], v153 offset:52224
	ds_read_b128 v[198:201], v153 offset:53248
	ds_read_b128 v[202:205], v153 offset:54272
	ds_read_b128 v[212:215], v153 offset:55296
	ds_read_b128 v[216:219], v153 offset:56320
	global_load_lds_dwordx4 v[206:207], off
	s_add_i32 m0, s26, 0x2000
	s_add_u32 s24, s24, 0x40080
	v_lshl_add_u64 v[206:207], v[220:221], 0, s[6:7]
	s_addc_u32 s25, s25, 0
	s_add_i32 s26, s50, s9
	global_load_lds_dwordx4 v[206:207], off
	v_lshl_add_u64 v[206:207], s[24:25], 0, v[132:133]
	s_mov_b32 m0, s26
	s_nop 0
	global_load_lds_dwordx4 v[206:207], off
	v_lshl_add_u64 v[206:207], s[24:25], 0, v[128:129]
	s_add_i32 m0, s26, 0x2000
	s_nop 0
	global_load_lds_dwordx4 v[206:207], off
	v_lshl_add_u64 v[206:207], v[222:223], 0, s[6:7]
	s_mov_b32 m0, s38
	s_nop 0
	global_load_lds_dwordx4 v[206:207], off
	v_lshl_add_u64 v[206:207], v[224:225], 0, s[6:7]
	s_mov_b32 m0, s39
	s_nop 0
	global_load_lds_dwordx4 v[206:207], off
	s_waitcnt vmcnt(8)
	s_waitcnt lgkmcnt(0)
	s_barrier
	s_setprio 1
	s_waitcnt lgkmcnt(0)
	v_mfma_f32_16x16x32_bf16 v[60:63], v[144:147], v[182:185], v[60:63]
	v_mfma_f32_16x16x32_bf16 v[52:55], v[158:161], v[182:185], v[52:55]
	v_mfma_f32_16x16x32_bf16 v[44:47], v[144:147], v[190:193], v[44:47]
	v_mfma_f32_16x16x32_bf16 v[36:39], v[158:161], v[190:193], v[36:39]
	v_mfma_f32_16x16x32_bf16 v[28:31], v[144:147], v[198:201], v[28:31]
	v_mfma_f32_16x16x32_bf16 v[20:23], v[158:161], v[198:201], v[20:23]
	v_mfma_f32_16x16x32_bf16 v[12:15], v[144:147], v[212:215], v[12:15]
	v_mfma_f32_16x16x32_bf16 v[4:7], v[158:161], v[212:215], v[4:7]
	v_mfma_f32_16x16x32_bf16 v[60:63], v[154:157], v[186:189], v[60:63]
	v_mfma_f32_16x16x32_bf16 v[52:55], v[162:165], v[186:189], v[52:55]
	v_mfma_f32_16x16x32_bf16 v[44:47], v[154:157], v[194:197], v[44:47]
	v_mfma_f32_16x16x32_bf16 v[36:39], v[162:165], v[194:197], v[36:39]
	v_mfma_f32_16x16x32_bf16 v[28:31], v[154:157], v[202:205], v[28:31]
	v_mfma_f32_16x16x32_bf16 v[20:23], v[162:165], v[202:205], v[20:23]
	v_mfma_f32_16x16x32_bf16 v[12:15], v[154:157], v[216:219], v[12:15]
	v_mfma_f32_16x16x32_bf16 v[4:7], v[162:165], v[216:219], v[4:7]
	s_setprio 0
	s_setprio 1
	v_mfma_f32_16x16x32_bf16 v[56:59], v[166:169], v[182:185], v[56:59]
	v_mfma_f32_16x16x32_bf16 v[48:51], v[174:177], v[182:185], v[48:51]
	v_mfma_f32_16x16x32_bf16 v[40:43], v[166:169], v[190:193], v[40:43]
	v_mfma_f32_16x16x32_bf16 v[32:35], v[174:177], v[190:193], v[32:35]
	v_mfma_f32_16x16x32_bf16 v[24:27], v[166:169], v[198:201], v[24:27]
	v_mfma_f32_16x16x32_bf16 v[16:19], v[174:177], v[198:201], v[16:19]
	v_mfma_f32_16x16x32_bf16 v[8:11], v[166:169], v[212:215], v[8:11]
	v_mfma_f32_16x16x32_bf16 v[0:3], v[174:177], v[212:215], v[0:3]
	v_mfma_f32_16x16x32_bf16 v[56:59], v[170:173], v[186:189], v[56:59]
	v_mfma_f32_16x16x32_bf16 v[48:51], v[178:181], v[186:189], v[48:51]
	v_mfma_f32_16x16x32_bf16 v[40:43], v[170:173], v[194:197], v[40:43]
	v_mfma_f32_16x16x32_bf16 v[32:35], v[178:181], v[194:197], v[32:35]
	v_mfma_f32_16x16x32_bf16 v[24:27], v[170:173], v[202:205], v[24:27]
	v_mfma_f32_16x16x32_bf16 v[16:19], v[178:181], v[202:205], v[16:19]
	v_mfma_f32_16x16x32_bf16 v[8:11], v[170:173], v[216:219], v[8:11]
	v_mfma_f32_16x16x32_bf16 v[0:3], v[178:181], v[216:219], v[0:3]
	s_setprio 0
	s_add_i32 s48, s48, 2
	s_add_u32 s22, s22, 0x100
	s_addc_u32 s23, s23, 0
	s_add_u32 s46, s46, 0x100
	s_addc_u32 s47, s47, 0
	s_cmp_gt_u32 s48, 13
	s_barrier
	s_cbranch_scc0 .LBB0_269
	s_and_b64 vcc, exec, s[2:3]
	s_cbranch_vccz .LBB0_272
	s_barrier

; #define PG8_STAGE(bufoff, gbase, voff) do { _Pragma("unroll") for (int _i = 0; _i < 2; ++_i) \
;         __builtin_amdgcn_global_load_lds((const unsigned*)((const char*)(gbase) + (voff)[_i]), (PG8_LAS unsigned*)(lds + (bufoff) + ldsw + _i * 8192), 16, 0, 0); } while (0)
; #define PG8_LDA(dst, b, h) do { _Pragma("unroll") for (int m = 0; m < 4; ++m) _Pragma("unroll") for (int k = 0; k < 2; ++k) dst[m][k] = *(const PG8_LAS bf16x8*)(lds + PG8_SA(b, h) + aoff + m * 2048 + k * 1024); } while (0)
; #define PG8_LDB(dst, b, h) do { _Pragma("unroll") for (int n = 0; n < 2; ++n) _Pragma("unroll") for (int k = 0; k < 2; ++k) dst[n][k] = *(const PG8_LAS bf16x8*)(lds + PG8_SB(b, h) + boff + n * 2048 + k * 1024); } while (0)
; #define PG8_MMA(ai, bj, At, Bt) do { __builtin_amdgcn_s_setprio(1); _Pragma("unroll") for (int m = 0; m < 4; ++m) _Pragma("unroll") for (int n = 0; n < 2; ++n) _Pragma("unroll") for (int k = 0; k < 2; ++k) \
;         acc[ai][bj][m][n] = __builtin_amdgcn_mfma_f32_16x16x32_bf16(Bt[n][k], At[m][k], acc[ai][bj][m][n], 0, 0, 0); __builtin_amdgcn_s_setprio(0); } while (0)
; #define PG8_BAR __builtin_amdgcn_s_barrier()
; template <class Epi, class Sched, bool ALIGN_EPI = false, bool SP2 = false>
; __device__ __forceinline__ void gemm_phase(PG8_LAS unsigned char* lds, const Gemm g, const Sched& S, const Epi& E, const int wid) {
;     ...
;             PG8_LDB(B0, 0, 0); PG8_LDB(B1, 0, 1); PG8_SCHED; PG8_LDA(At, 0, 0); PG8_STAGE(PG8_SA(1, 1), a1 + hstep, voffA);
;             PG8_WAIT_V(8); PG8_WAIT_L(0); PG8_BAR; PG8_MMA(0, 0, At, B0); PG8_MMA(0, 1, At, B1); PG8_BAR; PG8_SCHED;
;             PG8_LDA(At, 0, 1); PG8_STAGE(PG8_SB(0, 0), b2, voffB); PG8_STAGE(PG8_SB(0, 1), b2 + hstep, voffB); PG8_STAGE(PG8_SA(0, 0), a2, voffA);
;             PG8_WAIT_V(8); PG8_WAIT_L(0); PG8_BAR; PG8_MMA(1, 0, At, B0); PG8_MMA(1, 1, At, B1); PG8_BAR; PG8_SCHED;
;             PG8_LDB(B0, 1, 0); PG8_LDB(B1, 1, 1); PG8_SCHED; PG8_LDA(At, 1, 0); PG8_STAGE(PG8_SA(0, 1), a2 + hstep, voffA);
;             PG8_WAIT_V(8); PG8_WAIT_L(0); PG8_BAR; PG8_MMA(0, 0, At, B0); PG8_MMA(0, 1, At, B1); PG8_BAR; PG8_SCHED;
;             PG8_LDA(At, 1, 1); PG8_STAGE(PG8_SB(1, 0), b3, voffB); PG8_STAGE(PG8_SB(1, 1), b3 + hstep, voffB); PG8_STAGE(PG8_SA(1, 0), a3, voffA);
;             PG8_WAIT_V(8); PG8_WAIT_L(0); PG8_BAR; PG8_MMA(1, 0, At, B0); PG8_MMA(1, 1, At, B1); PG8_BAR; PG8_SCHED;
.LBB0_756:
	v_add_u32_e32 v151, s35, v149
	ds_read_b128 v[152:155], v151
	ds_read_b128 v[156:159], v151 offset:1024
	ds_read_b128 v[160:163], v151 offset:2048
	ds_read_b128 v[164:167], v151 offset:3072
	v_add_u32_e32 v151, s38, v149
	s_add_u32 s16, s2, s14
	ds_read_b128 v[168:171], v151
	ds_read_b128 v[172:175], v151 offset:1024
	ds_read_b128 v[176:179], v151 offset:2048
	ds_read_b128 v[180:183], v151 offset:3072
	s_addc_u32 s17, s3, s15
	s_add_u32 s16, s16, 0x100
	s_addc_u32 s17, s17, 0
	s_add_u32 s45, s42, s14
	s_addc_u32 s46, s43, s15
	s_cmpk_eq_i32 s14, 0x1500
	s_cselect_b32 s19, s13, s17
	s_cselect_b32 s18, s12, s16
	s_cselect_b32 s17, s9, s46
	s_cselect_b32 s16, s8, s45
	v_lshl_add_u64 v[206:207], v[144:145], 0, s[14:15]
	s_add_i32 m0, s25, 0xc000
	ds_read_b128 v[184:187], v150
	ds_read_b128 v[188:191], v150 offset:1024
	ds_read_b128 v[194:197], v150 offset:2048
	ds_read_b128 v[198:201], v150 offset:3072
	ds_read_b128 v[202:205], v150 offset:4096
	ds_read_b128 v[212:215], v150 offset:5120
	ds_read_b128 v[216:219], v150 offset:6144
	ds_read_b128 v[220:223], v150 offset:7168
	global_load_lds_dwordx4 v[206:207], off
	v_lshl_add_u64 v[206:207], v[146:147], 0, s[14:15]
	s_add_i32 m0, s25, 0xe000
	s_nop 0
	global_load_lds_dwordx4 v[206:207], off
	s_waitcnt vmcnt(8)
	s_waitcnt lgkmcnt(0)
	s_barrier
	s_setprio 1
	s_waitcnt lgkmcnt(0)
	v_mfma_f32_16x16x32_bf16 v[120:123], v[152:155], v[184:187], v[120:123]
	v_mfma_f32_16x16x32_bf16 v[124:127], v[160:163], v[184:187], v[124:127]
	v_mfma_f32_16x16x32_bf16 v[108:111], v[152:155], v[194:197], v[108:111]
	v_mfma_f32_16x16x32_bf16 v[116:119], v[160:163], v[194:197], v[116:119]
	v_mfma_f32_16x16x32_bf16 v[92:95], v[152:155], v[202:205], v[92:95]
	v_mfma_f32_16x16x32_bf16 v[112:115], v[160:163], v[202:205], v[112:115]
	v_mfma_f32_16x16x32_bf16 v[72:75], v[152:155], v[216:219], v[72:75]
	v_mfma_f32_16x16x32_bf16 v[100:103], v[160:163], v[216:219], v[100:103]
	v_mfma_f32_16x16x32_bf16 v[120:123], v[156:159], v[188:191], v[120:123]
	v_mfma_f32_16x16x32_bf16 v[124:127], v[164:167], v[188:191], v[124:127]
	v_mfma_f32_16x16x32_bf16 v[108:111], v[156:159], v[198:201], v[108:111]
	v_mfma_f32_16x16x32_bf16 v[116:119], v[164:167], v[198:201], v[116:119]
	v_mfma_f32_16x16x32_bf16 v[92:95], v[156:159], v[212:215], v[92:95]
	v_mfma_f32_16x16x32_bf16 v[112:115], v[164:167], v[212:215], v[112:115]
	v_mfma_f32_16x16x32_bf16 v[72:75], v[156:159], v[220:223], v[72:75]
	v_mfma_f32_16x16x32_bf16 v[100:103], v[164:167], v[220:223], v[100:103]
	s_setprio 0
	s_setprio 1
	v_mfma_f32_16x16x32_bf16 v[104:107], v[168:171], v[184:187], v[104:107]
	v_mfma_f32_16x16x32_bf16 v[88:91], v[176:179], v[184:187], v[88:91]
	v_mfma_f32_16x16x32_bf16 v[96:99], v[168:171], v[194:197], v[96:99]
	v_mfma_f32_16x16x32_bf16 v[76:79], v[176:179], v[194:197], v[76:79]
	v_mfma_f32_16x16x32_bf16 v[84:87], v[168:171], v[202:205], v[84:87]
	v_mfma_f32_16x16x32_bf16 v[68:71], v[176:179], v[202:205], v[68:71]
	v_mfma_f32_16x16x32_bf16 v[80:83], v[168:171], v[216:219], v[80:83]
	v_mfma_f32_16x16x32_bf16 v[64:67], v[176:179], v[216:219], v[64:67]
	v_mfma_f32_16x16x32_bf16 v[104:107], v[172:175], v[188:191], v[104:107]
	v_mfma_f32_16x16x32_bf16 v[88:91], v[180:183], v[188:191], v[88:91]
	v_mfma_f32_16x16x32_bf16 v[96:99], v[172:175], v[198:201], v[96:99]
	v_mfma_f32_16x16x32_bf16 v[76:79], v[180:183], v[198:201], v[76:79]
	v_mfma_f32_16x16x32_bf16 v[84:87], v[172:175], v[212:215], v[84:87]
	v_mfma_f32_16x16x32_bf16 v[68:71], v[180:183], v[212:215], v[68:71]
	v_mfma_f32_16x16x32_bf16 v[80:83], v[172:175], v[220:223], v[80:83]
	v_mfma_f32_16x16x32_bf16 v[64:67], v[180:183], v[220:223], v[64:67]
	s_setprio 0
	s_barrier
	s_add_i32 s45, s35, s23
	v_lshl_add_u64 v[206:207], s[16:17], 0, v[132:133]
	s_mov_b32 m0, s45
	ds_read_b128 v[184:187], v150 offset:16384
	ds_read_b128 v[188:191], v150 offset:17408
	ds_read_b128 v[194:197], v150 offset:18432
	ds_read_b128 v[198:201], v150 offset:19456
	ds_read_b128 v[202:205], v150 offset:20480
	ds_read_b128 v[212:215], v150 offset:21504
	ds_read_b128 v[216:219], v150 offset:22528
	ds_read_b128 v[220:223], v150 offset:23552
	global_load_lds_dwordx4 v[206:207], off
	s_add_i32 m0, s45, 0x2000
	s_add_u32 s46, s16, 0xb0000
	v_lshl_add_u64 v[224:225], s[16:17], 0, v[128:129]
	s_addc_u32 s47, s17, 0
	s_add_i32 s45, s38, s23
	global_load_lds_dwordx4 v[224:225], off
	v_lshl_add_u64 v[226:227], s[46:47], 0, v[132:133]
	s_mov_b32 m0, s45
	v_lshl_add_u64 v[228:229], s[18:19], 0, v[130:131]
	global_load_lds_dwordx4 v[226:227], off
	v_lshl_add_u64 v[226:227], s[46:47], 0, v[128:129]
	s_add_i32 m0, s45, 0x2000
	s_nop 0
	global_load_lds_dwordx4 v[226:227], off
	v_lshl_add_u64 v[226:227], s[18:19], 0, v[134:135]
	s_mov_b32 m0, s25
	s_nop 0
	global_load_lds_dwordx4 v[226:227], off
	s_mov_b32 m0, s27
	s_nop 0
	global_load_lds_dwordx4 v[228:229], off
	s_waitcnt vmcnt(8)
	s_waitcnt lgkmcnt(0)
	s_barrier
; #define PG8_STAGE(bufoff, gbase, voff) do { _Pragma("unroll") for (int _i = 0; _i < 2; ++_i) \
;         __builtin_amdgcn_global_load_lds((const unsigned*)((const char*)(gbase) + (voff)[_i]), (PG8_LAS unsigned*)(lds + (bufoff) + ldsw + _i * 8192), 16, 0, 0); } while (0)
; #define PG8_LDA(dst, b, h) do { _Pragma("unroll") for (int m = 0; m < 4; ++m) _Pragma("unroll") for (int k = 0; k < 2; ++k) dst[m][k] = *(const PG8_LAS bf16x8*)(lds + PG8_SA(b, h) + aoff + m * 2048 + k * 1024); } while (0)
; #define PG8_LDB(dst, b, h) do { _Pragma("unroll") for (int n = 0; n < 2; ++n) _Pragma("unroll") for (int k = 0; k < 2; ++k) dst[n][k] = *(const PG8_LAS bf16x8*)(lds + PG8_SB(b, h) + boff + n * 2048 + k * 1024); } while (0)
; #define PG8_MMA(ai, bj, At, Bt) do { __builtin_amdgcn_s_setprio(1); _Pragma("unroll") for (int m = 0; m < 4; ++m) _Pragma("unroll") for (int n = 0; n < 2; ++n) _Pragma("unroll") for (int k = 0; k < 2; ++k) \
;         acc[ai][bj][m][n] = __builtin_amdgcn_mfma_f32_16x16x32_bf16(Bt[n][k], At[m][k], acc[ai][bj][m][n], 0, 0, 0); __builtin_amdgcn_s_setprio(0); } while (0)
; #define PG8_BAR __builtin_amdgcn_s_barrier()
; template <class Epi, class Sched, bool ALIGN_EPI = false, bool SP2 = false>
; __device__ __forceinline__ void gemm_phase(PG8_LAS unsigned char* lds, const Gemm g, const Sched& S, const Epi& E, const int wid) {
;     ...
;             PG8_LDB(B0, 0, 0); PG8_LDB(B1, 0, 1); PG8_SCHED; PG8_LDA(At, 0, 0); PG8_STAGE(PG8_SA(1, 1), a1 + hstep, voffA);
;             PG8_WAIT_V(8); PG8_WAIT_L(0); PG8_BAR; PG8_MMA(0, 0, At, B0); PG8_MMA(0, 1, At, B1); PG8_BAR; PG8_SCHED;
;             PG8_LDA(At, 0, 1); PG8_STAGE(PG8_SB(0, 0), b2, voffB); PG8_STAGE(PG8_SB(0, 1), b2 + hstep, voffB); PG8_STAGE(PG8_SA(0, 0), a2, voffA);
;             PG8_WAIT_V(8); PG8_WAIT_L(0); PG8_BAR; PG8_MMA(1, 0, At, B0); PG8_MMA(1, 1, At, B1); PG8_BAR; PG8_SCHED;
;             PG8_LDB(B0, 1, 0); PG8_LDB(B1, 1, 1); PG8_SCHED; PG8_LDA(At, 1, 0); PG8_STAGE(PG8_SA(0, 1), a2 + hstep, voffA);
;             PG8_WAIT_V(8); PG8_WAIT_L(0); PG8_BAR; PG8_MMA(0, 0, At, B0); PG8_MMA(0, 1, At, B1); PG8_BAR; PG8_SCHED;
;             PG8_LDA(At, 1, 1); PG8_STAGE(PG8_SB(1, 0), b3, voffB); PG8_STAGE(PG8_SB(1, 1), b3 + hstep, voffB); PG8_STAGE(PG8_SA(1, 0), a3, voffA);
;             PG8_WAIT_V(8); PG8_WAIT_L(0); PG8_BAR; PG8_MMA(1, 0, At, B0); PG8_MMA(1, 1, At, B1); PG8_BAR; PG8_SCHED;
	s_setprio 1
	s_waitcnt lgkmcnt(0)
	v_mfma_f32_16x16x32_bf16 v[60:63], v[152:155], v[184:187], v[60:63]
	v_mfma_f32_16x16x32_bf16 v[56:59], v[160:163], v[184:187], v[56:59]
	v_mfma_f32_16x16x32_bf16 v[44:47], v[152:155], v[194:197], v[44:47]
	v_mfma_f32_16x16x32_bf16 v[40:43], v[160:163], v[194:197], v[40:43]
	v_mfma_f32_16x16x32_bf16 v[28:31], v[152:155], v[202:205], v[28:31]
	v_mfma_f32_16x16x32_bf16 v[24:27], v[160:163], v[202:205], v[24:27]
	v_mfma_f32_16x16x32_bf16 v[4:7], v[152:155], v[216:219], v[4:7]
	v_mfma_f32_16x16x32_bf16 v[12:15], v[160:163], v[216:219], v[12:15]
	v_mfma_f32_16x16x32_bf16 v[60:63], v[156:159], v[188:191], v[60:63]
	v_mfma_f32_16x16x32_bf16 v[56:59], v[164:167], v[188:191], v[56:59]
	v_mfma_f32_16x16x32_bf16 v[44:47], v[156:159], v[198:201], v[44:47]
	v_mfma_f32_16x16x32_bf16 v[40:43], v[164:167], v[198:201], v[40:43]
	v_mfma_f32_16x16x32_bf16 v[28:31], v[156:159], v[212:215], v[28:31]
	v_mfma_f32_16x16x32_bf16 v[24:27], v[164:167], v[212:215], v[24:27]
	v_mfma_f32_16x16x32_bf16 v[4:7], v[156:159], v[220:223], v[4:7]
	v_mfma_f32_16x16x32_bf16 v[12:15], v[164:167], v[220:223], v[12:15]
	s_setprio 0
	s_setprio 1
	v_mfma_f32_16x16x32_bf16 v[52:55], v[168:171], v[184:187], v[52:55]
	v_mfma_f32_16x16x32_bf16 v[48:51], v[176:179], v[184:187], v[48:51]
	v_mfma_f32_16x16x32_bf16 v[36:39], v[168:171], v[194:197], v[36:39]
	v_mfma_f32_16x16x32_bf16 v[32:35], v[176:179], v[194:197], v[32:35]
	v_mfma_f32_16x16x32_bf16 v[20:23], v[168:171], v[202:205], v[20:23]
	v_mfma_f32_16x16x32_bf16 v[16:19], v[176:179], v[202:205], v[16:19]
	v_mfma_f32_16x16x32_bf16 v[8:11], v[168:171], v[216:219], v[8:11]
	v_mfma_f32_16x16x32_bf16 v[0:3], v[176:179], v[216:219], v[0:3]
	v_mfma_f32_16x16x32_bf16 v[52:55], v[172:175], v[188:191], v[52:55]
	v_mfma_f32_16x16x32_bf16 v[48:51], v[180:183], v[188:191], v[48:51]
	v_mfma_f32_16x16x32_bf16 v[36:39], v[172:175], v[198:201], v[36:39]
	v_mfma_f32_16x16x32_bf16 v[32:35], v[180:183], v[198:201], v[32:35]
	v_mfma_f32_16x16x32_bf16 v[20:23], v[172:175], v[212:215], v[20:23]
	v_mfma_f32_16x16x32_bf16 v[16:19], v[180:183], v[212:215], v[16:19]
	v_mfma_f32_16x16x32_bf16 v[8:11], v[172:175], v[220:223], v[8:11]
	v_mfma_f32_16x16x32_bf16 v[0:3], v[180:183], v[220:223], v[0:3]
	s_setprio 0
	s_barrier
	s_add_i32 s45, 0, 0x18000
	v_add_u32_e32 v151, s45, v149
	s_add_i32 s46, 0, 0x1c000
	ds_read_b128 v[152:155], v151
	ds_read_b128 v[156:159], v151 offset:1024
	ds_read_b128 v[160:163], v151 offset:2048
	ds_read_b128 v[164:167], v151 offset:3072
	v_add_u32_e32 v151, s46, v149
	ds_read_b128 v[168:171], v151
	ds_read_b128 v[172:175], v151 offset:1024
	ds_read_b128 v[176:179], v151 offset:2048
	ds_read_b128 v[180:183], v151 offset:3072
	s_add_u32 s18, s18, 0xb0000
	s_addc_u32 s19, s19, 0
	s_mov_b32 m0, s28
	v_lshl_add_u64 v[230:231], s[18:19], 0, v[134:135]
	ds_read_b128 v[184:187], v150 offset:32768
	ds_read_b128 v[188:191], v150 offset:33792
	ds_read_b128 v[194:197], v150 offset:34816
	ds_read_b128 v[198:201], v150 offset:35840
	ds_read_b128 v[202:205], v150 offset:36864
	ds_read_b128 v[212:215], v150 offset:37888
	ds_read_b128 v[216:219], v150 offset:38912
	ds_read_b128 v[220:223], v150 offset:39936
	global_load_lds_dwordx4 v[230:231], off
	v_lshl_add_u64 v[230:231], s[18:19], 0, v[130:131]
	s_mov_b32 m0, s29
	s_nop 0
	global_load_lds_dwordx4 v[230:231], off
	s_waitcnt vmcnt(8)
	s_waitcnt lgkmcnt(0)
	s_barrier
	s_setprio 1
	s_waitcnt lgkmcnt(0)
	v_mfma_f32_16x16x32_bf16 v[120:123], v[152:155], v[184:187], v[120:123]
	v_mfma_f32_16x16x32_bf16 v[124:127], v[160:163], v[184:187], v[124:127]
	v_mfma_f32_16x16x32_bf16 v[108:111], v[152:155], v[194:197], v[108:111]
	v_mfma_f32_16x16x32_bf16 v[116:119], v[160:163], v[194:197], v[116:119]
	v_mfma_f32_16x16x32_bf16 v[92:95], v[152:155], v[202:205], v[92:95]
	v_mfma_f32_16x16x32_bf16 v[112:115], v[160:163], v[202:205], v[112:115]
	v_mfma_f32_16x16x32_bf16 v[72:75], v[152:155], v[216:219], v[72:75]
	v_mfma_f32_16x16x32_bf16 v[100:103], v[160:163], v[216:219], v[100:103]
	v_mfma_f32_16x16x32_bf16 v[120:123], v[156:159], v[188:191], v[120:123]
	v_mfma_f32_16x16x32_bf16 v[124:127], v[164:167], v[188:191], v[124:127]
	v_mfma_f32_16x16x32_bf16 v[108:111], v[156:159], v[198:201], v[108:111]
	v_mfma_f32_16x16x32_bf16 v[116:119], v[164:167], v[198:201], v[116:119]
	v_mfma_f32_16x16x32_bf16 v[92:95], v[156:159], v[212:215], v[92:95]
	v_mfma_f32_16x16x32_bf16 v[112:115], v[164:167], v[212:215], v[112:115]
	v_mfma_f32_16x16x32_bf16 v[72:75], v[156:159], v[220:223], v[72:75]
	v_mfma_f32_16x16x32_bf16 v[100:103], v[164:167], v[220:223], v[100:103]
	s_setprio 0
	s_setprio 1
	v_mfma_f32_16x16x32_bf16 v[104:107], v[168:171], v[184:187], v[104:107]
	v_mfma_f32_16x16x32_bf16 v[88:91], v[176:179], v[184:187], v[88:91]
	v_mfma_f32_16x16x32_bf16 v[96:99], v[168:171], v[194:197], v[96:99]
	v_mfma_f32_16x16x32_bf16 v[76:79], v[176:179], v[194:197], v[76:79]
	v_mfma_f32_16x16x32_bf16 v[84:87], v[168:171], v[202:205], v[84:87]
	v_mfma_f32_16x16x32_bf16 v[68:71], v[176:179], v[202:205], v[68:71]
	v_mfma_f32_16x16x32_bf16 v[80:83], v[168:171], v[216:219], v[80:83]
	v_mfma_f32_16x16x32_bf16 v[64:67], v[176:179], v[216:219], v[64:67]
	v_mfma_f32_16x16x32_bf16 v[104:107], v[172:175], v[188:191], v[104:107]
	v_mfma_f32_16x16x32_bf16 v[88:91], v[180:183], v[188:191], v[88:91]
	v_mfma_f32_16x16x32_bf16 v[96:99], v[172:175], v[198:201], v[96:99]
	v_mfma_f32_16x16x32_bf16 v[76:79], v[180:183], v[198:201], v[76:79]
	v_mfma_f32_16x16x32_bf16 v[84:87], v[172:175], v[212:215], v[84:87]
	v_mfma_f32_16x16x32_bf16 v[68:71], v[180:183], v[212:215], v[68:71]
	v_mfma_f32_16x16x32_bf16 v[80:83], v[172:175], v[220:223], v[80:83]
	v_mfma_f32_16x16x32_bf16 v[64:67], v[180:183], v[220:223], v[64:67]
	s_setprio 0
	s_barrier
; #define PG8_STAGE(bufoff, gbase, voff) do { _Pragma("unroll") for (int _i = 0; _i < 2; ++_i) \
;         __builtin_amdgcn_global_load_lds((const unsigned*)((const char*)(gbase) + (voff)[_i]), (PG8_LAS unsigned*)(lds + (bufoff) + ldsw + _i * 8192), 16, 0, 0); } while (0)
; #define PG8_LDA(dst, b, h) do { _Pragma("unroll") for (int m = 0; m < 4; ++m) _Pragma("unroll") for (int k = 0; k < 2; ++k) dst[m][k] = *(const PG8_LAS bf16x8*)(lds + PG8_SA(b, h) + aoff + m * 2048 + k * 1024); } while (0)
; #define PG8_MMA(ai, bj, At, Bt) do { __builtin_amdgcn_s_setprio(1); _Pragma("unroll") for (int m = 0; m < 4; ++m) _Pragma("unroll") for (int n = 0; n < 2; ++n) _Pragma("unroll") for (int k = 0; k < 2; ++k) \
;         acc[ai][bj][m][n] = __builtin_amdgcn_mfma_f32_16x16x32_bf16(Bt[n][k], At[m][k], acc[ai][bj][m][n], 0, 0, 0); __builtin_amdgcn_s_setprio(0); } while (0)
; #define PG8_WAIT_V(n) asm volatile("s_waitcnt vmcnt(" #n ")" ::: "memory")
; #define PG8_WAIT_L(n) asm volatile("s_waitcnt lgkmcnt(" #n ")" ::: "memory")
; #define PG8_BAR __builtin_amdgcn_s_barrier()
; #define PG8_SCHED __builtin_amdgcn_sched_barrier(0)
; template <class Epi, class Sched, bool ALIGN_EPI = false, bool SP2 = false>
; __device__ __forceinline__ void gemm_phase(PG8_LAS unsigned char* lds, const Gemm g, const Sched& S, const Epi& E, const int wid) {
;     ...
;             PG8_LDA(At, 1, 1); PG8_STAGE(PG8_SB(1, 0), b3, voffB); PG8_STAGE(PG8_SB(1, 1), b3 + hstep, voffB); PG8_STAGE(PG8_SA(1, 0), a3, voffA);
;             PG8_WAIT_V(8); PG8_WAIT_L(0); PG8_BAR; PG8_MMA(1, 0, At, B0); PG8_MMA(1, 1, At, B1); PG8_BAR; PG8_SCHED;
;     ...
; #pragma unroll
;         for (int a = 0; a < 2; ++a)
; #pragma unroll
;             for (int b = 0; b < 2; ++b)
; #pragma unroll
;                 for (int m = 0; m < 4; ++m)
; #pragma unroll
;                     for (int n = 0; n < 2; ++n) acc[a][b][m][n] = (f32x4){0.f, 0.f, 0.f, 0.f};
	s_add_i32 s18, s45, s23
	v_lshl_add_u64 v[206:207], v[206:207], 0, s[10:11]
	s_mov_b32 m0, s18
	ds_read_b128 v[184:187], v150 offset:49152
	ds_read_b128 v[188:191], v150 offset:50176
	ds_read_b128 v[194:197], v150 offset:51200
	ds_read_b128 v[198:201], v150 offset:52224
	ds_read_b128 v[202:205], v150 offset:53248
	ds_read_b128 v[212:215], v150 offset:54272
	ds_read_b128 v[216:219], v150 offset:55296
	ds_read_b128 v[220:223], v150 offset:56320
	global_load_lds_dwordx4 v[206:207], off
	s_add_i32 m0, s18, 0x2000
	s_add_u32 s16, s16, 0xb0080
	v_lshl_add_u64 v[206:207], v[224:225], 0, s[10:11]
	s_addc_u32 s17, s17, 0
	s_add_i32 s18, s46, s23
	global_load_lds_dwordx4 v[206:207], off
	v_lshl_add_u64 v[206:207], s[16:17], 0, v[132:133]
	s_mov_b32 m0, s18
	s_nop 0
	global_load_lds_dwordx4 v[206:207], off
	v_lshl_add_u64 v[206:207], s[16:17], 0, v[128:129]
	s_add_i32 m0, s18, 0x2000
	s_nop 0
	global_load_lds_dwordx4 v[206:207], off
	v_lshl_add_u64 v[206:207], v[226:227], 0, s[10:11]
	s_mov_b32 m0, s31
	s_nop 0
	global_load_lds_dwordx4 v[206:207], off
	v_lshl_add_u64 v[206:207], v[228:229], 0, s[10:11]
	s_mov_b32 m0, s33
	s_nop 0
	global_load_lds_dwordx4 v[206:207], off
	s_waitcnt vmcnt(8)
	s_waitcnt lgkmcnt(0)
	s_barrier
	s_setprio 1
	s_waitcnt lgkmcnt(0)
	v_mfma_f32_16x16x32_bf16 v[60:63], v[152:155], v[184:187], v[60:63]
	v_mfma_f32_16x16x32_bf16 v[56:59], v[160:163], v[184:187], v[56:59]
	v_mfma_f32_16x16x32_bf16 v[44:47], v[152:155], v[194:197], v[44:47]
	v_mfma_f32_16x16x32_bf16 v[40:43], v[160:163], v[194:197], v[40:43]
	v_mfma_f32_16x16x32_bf16 v[28:31], v[152:155], v[202:205], v[28:31]
	v_mfma_f32_16x16x32_bf16 v[24:27], v[160:163], v[202:205], v[24:27]
	v_mfma_f32_16x16x32_bf16 v[4:7], v[152:155], v[216:219], v[4:7]
	v_mfma_f32_16x16x32_bf16 v[12:15], v[160:163], v[216:219], v[12:15]
	v_mfma_f32_16x16x32_bf16 v[60:63], v[156:159], v[188:191], v[60:63]
	v_mfma_f32_16x16x32_bf16 v[56:59], v[164:167], v[188:191], v[56:59]
	v_mfma_f32_16x16x32_bf16 v[44:47], v[156:159], v[198:201], v[44:47]
	v_mfma_f32_16x16x32_bf16 v[40:43], v[164:167], v[198:201], v[40:43]
	v_mfma_f32_16x16x32_bf16 v[28:31], v[156:159], v[212:215], v[28:31]
	v_mfma_f32_16x16x32_bf16 v[24:27], v[164:167], v[212:215], v[24:27]
	v_mfma_f32_16x16x32_bf16 v[4:7], v[156:159], v[220:223], v[4:7]
	v_mfma_f32_16x16x32_bf16 v[12:15], v[164:167], v[220:223], v[12:15]
	s_setprio 0
	s_setprio 1
	v_mfma_f32_16x16x32_bf16 v[52:55], v[168:171], v[184:187], v[52:55]
	v_mfma_f32_16x16x32_bf16 v[48:51], v[176:179], v[184:187], v[48:51]
	v_mfma_f32_16x16x32_bf16 v[36:39], v[168:171], v[194:197], v[36:39]
	v_mfma_f32_16x16x32_bf16 v[32:35], v[176:179], v[194:197], v[32:35]
	v_mfma_f32_16x16x32_bf16 v[20:23], v[168:171], v[202:205], v[20:23]
	v_mfma_f32_16x16x32_bf16 v[16:19], v[176:179], v[202:205], v[16:19]
	v_mfma_f32_16x16x32_bf16 v[8:11], v[168:171], v[216:219], v[8:11]
	v_mfma_f32_16x16x32_bf16 v[0:3], v[176:179], v[216:219], v[0:3]
	v_mfma_f32_16x16x32_bf16 v[52:55], v[172:175], v[188:191], v[52:55]
	v_mfma_f32_16x16x32_bf16 v[48:51], v[180:183], v[188:191], v[48:51]
	v_mfma_f32_16x16x32_bf16 v[36:39], v[172:175], v[198:201], v[36:39]
	v_mfma_f32_16x16x32_bf16 v[32:35], v[180:183], v[198:201], v[32:35]
	v_mfma_f32_16x16x32_bf16 v[20:23], v[172:175], v[212:215], v[20:23]
	v_mfma_f32_16x16x32_bf16 v[16:19], v[180:183], v[212:215], v[16:19]
	v_mfma_f32_16x16x32_bf16 v[8:11], v[172:175], v[220:223], v[8:11]
	v_mfma_f32_16x16x32_bf16 v[0:3], v[180:183], v[220:223], v[0:3]
	s_setprio 0
	s_add_i32 s44, s44, 2
	s_add_u32 s14, s14, 0x100
	s_addc_u32 s15, s15, 0
	s_cmp_gt_u32 s44, 41
	s_barrier
	s_cbranch_scc0 .LBB0_756
	s_add_u32 s14, s42, 0xffffff00
	s_addc_u32 s15, s43, -1
	s_and_b64 vcc, exec, s[6:7]
	s_cbranch_vccnz .LBB0_743
	v_mov_b32_e32 v0, 0
	s_mov_b32 s0, s39
	s_mov_b32 s20, s40
	s_mov_b64 s[2:3], s[12:13]
	s_mov_b32 s34, s41
	v_mov_b32_e32 v1, v0
	v_mov_b32_e32 v2, v0
	v_mov_b32_e32 v3, v0
	v_mov_b32_e32 v8, v0
	v_mov_b32_e32 v9, v0
	v_mov_b32_e32 v10, v0
	v_mov_b32_e32 v11, v0
	v_mov_b32_e32 v16, v0
	v_mov_b32_e32 v17, v0
	v_mov_b32_e32 v18, v0
	v_mov_b32_e32 v19, v0
	v_mov_b32_e32 v20, v0
	v_mov_b32_e32 v21, v0
	v_mov_b32_e32 v22, v0
	v_mov_b32_e32 v23, v0
	v_mov_b32_e32 v32, v0
	v_mov_b32_e32 v33, v0
	v_mov_b32_e32 v34, v0
	v_mov_b32_e32 v35, v0
	v_mov_b32_e32 v36, v0
	v_mov_b32_e32 v37, v0
	v_mov_b32_e32 v38, v0
	v_mov_b32_e32 v39, v0
	v_mov_b32_e32 v48, v0
	v_mov_b32_e32 v49, v0
	v_mov_b32_e32 v50, v0
	v_mov_b32_e32 v51, v0
	v_mov_b32_e32 v52, v0
	v_mov_b32_e32 v53, v0
	v_mov_b32_e32 v54, v0
	v_mov_b32_e32 v55, v0
	v_mov_b32_e32 v12, v0
	v_mov_b32_e32 v13, v0
	v_mov_b32_e32 v14, v0
	v_mov_b32_e32 v15, v0
	v_mov_b32_e32 v4, v0
	v_mov_b32_e32 v5, v0
	v_mov_b32_e32 v6, v0
	v_mov_b32_e32 v7, v0
	v_mov_b32_e32 v24, v0
	v_mov_b32_e32 v25, v0
	v_mov_b32_e32 v26, v0
	v_mov_b32_e32 v27, v0
	v_mov_b32_e32 v28, v0
	v_mov_b32_e32 v29, v0
	v_mov_b32_e32 v30, v0
	v_mov_b32_e32 v31, v0
	v_mov_b32_e32 v40, v0
	v_mov_b32_e32 v41, v0
	v_mov_b32_e32 v42, v0
	v_mov_b32_e32 v43, v0
	v_mov_b32_e32 v44, v0
	v_mov_b32_e32 v45, v0
	v_mov_b32_e32 v46, v0
	v_mov_b32_e32 v47, v0
	v_mov_b32_e32 v56, v0
	v_mov_b32_e32 v57, v0
	v_mov_b32_e32 v58, v0
	v_mov_b32_e32 v59, v0
	v_mov_b32_e32 v60, v0
	v_mov_b32_e32 v61, v0
	v_mov_b32_e32 v62, v0
	v_mov_b32_e32 v63, v0
	v_mov_b32_e32 v64, v0
	v_mov_b32_e32 v65, v0
	v_mov_b32_e32 v66, v0
	v_mov_b32_e32 v67, v0
	v_mov_b32_e32 v80, v0
	v_mov_b32_e32 v81, v0
	v_mov_b32_e32 v82, v0
	v_mov_b32_e32 v83, v0
	v_mov_b32_e32 v68, v0
	v_mov_b32_e32 v69, v0
	v_mov_b32_e32 v70, v0
	v_mov_b32_e32 v71, v0
	v_mov_b32_e32 v84, v0
	v_mov_b32_e32 v85, v0
	v_mov_b32_e32 v86, v0
	v_mov_b32_e32 v87, v0
	v_mov_b32_e32 v76, v0
	v_mov_b32_e32 v77, v0
	v_mov_b32_e32 v78, v0
	v_mov_b32_e32 v79, v0
	v_mov_b32_e32 v96, v0
	v_mov_b32_e32 v97, v0
	v_mov_b32_e32 v98, v0
	v_mov_b32_e32 v99, v0
	v_mov_b32_e32 v88, v0
	v_mov_b32_e32 v89, v0
	v_mov_b32_e32 v90, v0
	v_mov_b32_e32 v91, v0
	v_mov_b32_e32 v104, v0
	v_mov_b32_e32 v105, v0
	v_mov_b32_e32 v106, v0
	v_mov_b32_e32 v107, v0
	v_mov_b32_e32 v100, v0
	v_mov_b32_e32 v101, v0
	v_mov_b32_e32 v102, v0
	v_mov_b32_e32 v103, v0
	v_mov_b32_e32 v72, v0
	v_mov_b32_e32 v73, v0
	v_mov_b32_e32 v74, v0
	v_mov_b32_e32 v75, v0
	v_mov_b32_e32 v112, v0
	v_mov_b32_e32 v113, v0
	v_mov_b32_e32 v114, v0
	v_mov_b32_e32 v115, v0
	v_mov_b32_e32 v92, v0
	v_mov_b32_e32 v93, v0
	v_mov_b32_e32 v94, v0
	v_mov_b32_e32 v95, v0
	v_mov_b32_e32 v116, v0
	v_mov_b32_e32 v117, v0
	v_mov_b32_e32 v118, v0
	v_mov_b32_e32 v119, v0
	v_mov_b32_e32 v108, v0
	v_mov_b32_e32 v109, v0
	v_mov_b32_e32 v110, v0
	v_mov_b32_e32 v111, v0
	v_mov_b32_e32 v124, v0
	v_mov_b32_e32 v125, v0
	v_mov_b32_e32 v126, v0
	v_mov_b32_e32 v127, v0
	v_mov_b32_e32 v120, v0
	v_mov_b32_e32 v121, v0
	v_mov_b32_e32 v122, v0
	v_mov_b32_e32 v123, v0
	s_andn2_b64 vcc, exec, s[4:5]
	s_cbranch_vccnz .LBB0_744

; #define PG8_STAGE(bufoff, gbase, voff) do { _Pragma("unroll") for (int _i = 0; _i < 2; ++_i) \
;         __builtin_amdgcn_global_load_lds((const unsigned*)((const char*)(gbase) + (voff)[_i]), (PG8_LAS unsigned*)(lds + (bufoff) + ldsw + _i * 8192), 16, 0, 0); } while (0)
; #define PG8_LDA(dst, b, h) do { _Pragma("unroll") for (int m = 0; m < 4; ++m) _Pragma("unroll") for (int k = 0; k < 2; ++k) dst[m][k] = *(const PG8_LAS bf16x8*)(lds + PG8_SA(b, h) + aoff + m * 2048 + k * 1024); } while (0)
; #define PG8_LDB(dst, b, h) do { _Pragma("unroll") for (int n = 0; n < 2; ++n) _Pragma("unroll") for (int k = 0; k < 2; ++k) dst[n][k] = *(const PG8_LAS bf16x8*)(lds + PG8_SB(b, h) + boff + n * 2048 + k * 1024); } while (0)
; #define PG8_MMA(ai, bj, At, Bt) do { __builtin_amdgcn_s_setprio(1); _Pragma("unroll") for (int m = 0; m < 4; ++m) _Pragma("unroll") for (int n = 0; n < 2; ++n) _Pragma("unroll") for (int k = 0; k < 2; ++k) \
;         acc[ai][bj][m][n] = __builtin_amdgcn_mfma_f32_16x16x32_bf16(Bt[n][k], At[m][k], acc[ai][bj][m][n], 0, 0, 0); __builtin_amdgcn_s_setprio(0); } while (0)
; #define PG8_WAIT_V(n) asm volatile("s_waitcnt vmcnt(" #n ")" ::: "memory")
; #define PG8_WAIT_L(n) asm volatile("s_waitcnt lgkmcnt(" #n ")" ::: "memory")
; #define PG8_BAR __builtin_amdgcn_s_barrier()
; #define PG8_SCHED __builtin_amdgcn_sched_barrier(0)
; template <class Epi, class Sched, bool ALIGN_EPI = false, bool SP2 = false>
; __device__ __forceinline__ void gemm_phase(PG8_LAS unsigned char* lds, const Gemm g, const Sched& S, const Epi& E, const int wid) {
;     ...
;             PG8_LDB(B0, 0, 0); PG8_LDB(B1, 0, 1); PG8_SCHED; PG8_LDA(At, 0, 0); PG8_STAGE(PG8_SA(1, 1), a1 + hstep, voffA);
;             PG8_WAIT_V(8); PG8_WAIT_L(0); PG8_BAR; PG8_MMA(0, 0, At, B0); PG8_MMA(0, 1, At, B1); PG8_BAR; PG8_SCHED;
;             PG8_LDA(At, 0, 1); PG8_STAGE(PG8_SB(0, 0), b2, voffB); PG8_STAGE(PG8_SB(0, 1), b2 + hstep, voffB); PG8_STAGE(PG8_SA(0, 0), a2, voffA);
;             PG8_WAIT_V(8); PG8_WAIT_L(0); PG8_BAR; PG8_MMA(1, 0, At, B0); PG8_MMA(1, 1, At, B1); PG8_BAR; PG8_SCHED;
.LBB0_882:
	ds_read_b128 v[152:155], v149
	ds_read_b128 v[156:159], v149 offset:1024
	ds_read_b128 v[160:163], v149 offset:2048
	ds_read_b128 v[164:167], v149 offset:3072
	ds_read_b128 v[168:171], v150
	ds_read_b128 v[172:175], v150 offset:1024
	ds_read_b128 v[176:179], v150 offset:2048
	ds_read_b128 v[180:183], v150 offset:3072
	s_add_u32 s22, s20, 0xfffc0080
	s_addc_u32 s23, s21, -1
	s_cmp_eq_u32 s47, 12
	s_cselect_b32 s25, s13, s23
	s_cselect_b32 s24, s43, s22
	s_cselect_b32 s23, s9, s46
	s_cselect_b32 s22, s44, s45
	v_lshl_add_u64 v[144:145], s[20:21], 0, v[136:137]
	s_add_i32 m0, s17, 0xc000
	ds_read_b128 v[184:187], v151
	ds_read_b128 v[188:191], v151 offset:1024
	ds_read_b128 v[192:195], v151 offset:2048
	ds_read_b128 v[196:199], v151 offset:3072
	ds_read_b128 v[200:203], v151 offset:4096
	ds_read_b128 v[204:207], v151 offset:5120
	ds_read_b128 v[212:215], v151 offset:6144
	ds_read_b128 v[216:219], v151 offset:7168
	global_load_lds_dwordx4 v[144:145], off
	v_lshl_add_u64 v[144:145], s[20:21], 0, v[138:139]
	s_add_i32 m0, s17, 0xe000
	s_nop 0
	global_load_lds_dwordx4 v[144:145], off
	s_waitcnt vmcnt(8)
	s_waitcnt lgkmcnt(0)
	s_barrier
	s_setprio 1
	s_waitcnt lgkmcnt(0)
	v_mfma_f32_16x16x32_bf16 v[124:127], v[152:155], v[184:187], v[124:127]
	v_mfma_f32_16x16x32_bf16 v[120:123], v[160:163], v[184:187], v[120:123]
	v_mfma_f32_16x16x32_bf16 v[116:119], v[152:155], v[192:195], v[116:119]
	v_mfma_f32_16x16x32_bf16 v[108:111], v[160:163], v[192:195], v[108:111]
	v_mfma_f32_16x16x32_bf16 v[100:103], v[152:155], v[200:203], v[100:103]
	v_mfma_f32_16x16x32_bf16 v[92:95], v[160:163], v[200:203], v[92:95]
	v_mfma_f32_16x16x32_bf16 v[84:87], v[152:155], v[212:215], v[84:87]
	v_mfma_f32_16x16x32_bf16 v[76:79], v[160:163], v[212:215], v[76:79]
	v_mfma_f32_16x16x32_bf16 v[124:127], v[156:159], v[188:191], v[124:127]
	v_mfma_f32_16x16x32_bf16 v[120:123], v[164:167], v[188:191], v[120:123]
	v_mfma_f32_16x16x32_bf16 v[116:119], v[156:159], v[196:199], v[116:119]
	v_mfma_f32_16x16x32_bf16 v[108:111], v[164:167], v[196:199], v[108:111]
	v_mfma_f32_16x16x32_bf16 v[100:103], v[156:159], v[204:207], v[100:103]
	v_mfma_f32_16x16x32_bf16 v[92:95], v[164:167], v[204:207], v[92:95]
	v_mfma_f32_16x16x32_bf16 v[84:87], v[156:159], v[216:219], v[84:87]
	v_mfma_f32_16x16x32_bf16 v[76:79], v[164:167], v[216:219], v[76:79]
	s_setprio 0
	s_setprio 1
	v_mfma_f32_16x16x32_bf16 v[112:115], v[168:171], v[184:187], v[112:115]
	v_mfma_f32_16x16x32_bf16 v[104:107], v[176:179], v[184:187], v[104:107]
	v_mfma_f32_16x16x32_bf16 v[96:99], v[168:171], v[192:195], v[96:99]
	v_mfma_f32_16x16x32_bf16 v[88:91], v[176:179], v[192:195], v[88:91]
	v_mfma_f32_16x16x32_bf16 v[80:83], v[168:171], v[200:203], v[80:83]
	v_mfma_f32_16x16x32_bf16 v[72:75], v[176:179], v[200:203], v[72:75]
	v_mfma_f32_16x16x32_bf16 v[68:71], v[168:171], v[212:215], v[68:71]
	v_mfma_f32_16x16x32_bf16 v[64:67], v[176:179], v[212:215], v[64:67]
	v_mfma_f32_16x16x32_bf16 v[112:115], v[172:175], v[188:191], v[112:115]
	v_mfma_f32_16x16x32_bf16 v[104:107], v[180:183], v[188:191], v[104:107]
	v_mfma_f32_16x16x32_bf16 v[96:99], v[172:175], v[196:199], v[96:99]
	v_mfma_f32_16x16x32_bf16 v[88:91], v[180:183], v[196:199], v[88:91]
	v_mfma_f32_16x16x32_bf16 v[80:83], v[172:175], v[204:207], v[80:83]
	v_mfma_f32_16x16x32_bf16 v[72:75], v[180:183], v[204:207], v[72:75]
	v_mfma_f32_16x16x32_bf16 v[68:71], v[172:175], v[216:219], v[68:71]
	v_mfma_f32_16x16x32_bf16 v[64:67], v[180:183], v[216:219], v[64:67]
	s_setprio 0
	s_barrier
	s_add_i32 s48, s39, s26
	v_lshl_add_u64 v[144:145], s[22:23], 0, v[132:133]
	s_mov_b32 m0, s48
	ds_read_b128 v[184:187], v151 offset:16384
	ds_read_b128 v[188:191], v151 offset:17408
	ds_read_b128 v[192:195], v151 offset:18432
	ds_read_b128 v[196:199], v151 offset:19456
	ds_read_b128 v[200:203], v151 offset:20480
	ds_read_b128 v[204:207], v151 offset:21504
	ds_read_b128 v[212:215], v151 offset:22528
	ds_read_b128 v[216:219], v151 offset:23552
	global_load_lds_dwordx4 v[144:145], off
	s_add_i32 m0, s48, 0x2000
	s_add_u32 s48, s22, 0x40000
	v_lshl_add_u64 v[220:221], s[22:23], 0, v[128:129]
	s_addc_u32 s49, s23, 0
	s_add_i32 s50, s40, s26
	global_load_lds_dwordx4 v[220:221], off
	v_lshl_add_u64 v[222:223], s[48:49], 0, v[132:133]
	s_mov_b32 m0, s50
	v_lshl_add_u64 v[224:225], s[24:25], 0, v[130:131]
	global_load_lds_dwordx4 v[222:223], off
	v_lshl_add_u64 v[222:223], s[48:49], 0, v[128:129]
	s_add_i32 m0, s50, 0x2000
	s_nop 0
	global_load_lds_dwordx4 v[222:223], off
	v_lshl_add_u64 v[222:223], s[24:25], 0, v[134:135]
	s_mov_b32 m0, s17
	s_nop 0
	global_load_lds_dwordx4 v[222:223], off
	s_mov_b32 m0, s29
	s_nop 0
	global_load_lds_dwordx4 v[224:225], off
	s_waitcnt vmcnt(8)
	s_waitcnt lgkmcnt(0)
	s_barrier
; #define PG8_STAGE(bufoff, gbase, voff) do { _Pragma("unroll") for (int _i = 0; _i < 2; ++_i) \
;         __builtin_amdgcn_global_load_lds((const unsigned*)((const char*)(gbase) + (voff)[_i]), (PG8_LAS unsigned*)(lds + (bufoff) + ldsw + _i * 8192), 16, 0, 0); } while (0)
; #define PG8_LDA(dst, b, h) do { _Pragma("unroll") for (int m = 0; m < 4; ++m) _Pragma("unroll") for (int k = 0; k < 2; ++k) dst[m][k] = *(const PG8_LAS bf16x8*)(lds + PG8_SA(b, h) + aoff + m * 2048 + k * 1024); } while (0)
; #define PG8_LDB(dst, b, h) do { _Pragma("unroll") for (int n = 0; n < 2; ++n) _Pragma("unroll") for (int k = 0; k < 2; ++k) dst[n][k] = *(const PG8_LAS bf16x8*)(lds + PG8_SB(b, h) + boff + n * 2048 + k * 1024); } while (0)
; #define PG8_MMA(ai, bj, At, Bt) do { __builtin_amdgcn_s_setprio(1); _Pragma("unroll") for (int m = 0; m < 4; ++m) _Pragma("unroll") for (int n = 0; n < 2; ++n) _Pragma("unroll") for (int k = 0; k < 2; ++k) \
;         acc[ai][bj][m][n] = __builtin_amdgcn_mfma_f32_16x16x32_bf16(Bt[n][k], At[m][k], acc[ai][bj][m][n], 0, 0, 0); __builtin_amdgcn_s_setprio(0); } while (0)
; #define PG8_WAIT_V(n) asm volatile("s_waitcnt vmcnt(" #n ")" ::: "memory")
; #define PG8_WAIT_L(n) asm volatile("s_waitcnt lgkmcnt(" #n ")" ::: "memory")
; #define PG8_BAR __builtin_amdgcn_s_barrier()
; #define PG8_SCHED __builtin_amdgcn_sched_barrier(0)
; template <class Epi, class Sched, bool ALIGN_EPI = false, bool SP2 = false>
; __device__ __forceinline__ void gemm_phase(PG8_LAS unsigned char* lds, const Gemm g, const Sched& S, const Epi& E, const int wid) {
;     ...
;             PG8_WAIT_V(8); PG8_WAIT_L(0); PG8_BAR; PG8_MMA(1, 0, At, B0); PG8_MMA(1, 1, At, B1); PG8_BAR; PG8_SCHED;
;             PG8_LDB(B0, 1, 0); PG8_LDB(B1, 1, 1); PG8_SCHED; PG8_LDA(At, 1, 0); PG8_STAGE(PG8_SA(0, 1), a2 + hstep, voffA);
;             PG8_WAIT_V(8); PG8_WAIT_L(0); PG8_BAR; PG8_MMA(0, 0, At, B0); PG8_MMA(0, 1, At, B1); PG8_BAR; PG8_SCHED;
	s_setprio 1
	s_waitcnt lgkmcnt(0)
	v_mfma_f32_16x16x32_bf16 v[60:63], v[152:155], v[184:187], v[60:63]
	v_mfma_f32_16x16x32_bf16 v[56:59], v[160:163], v[184:187], v[56:59]
	v_mfma_f32_16x16x32_bf16 v[52:55], v[152:155], v[192:195], v[52:55]
	v_mfma_f32_16x16x32_bf16 v[44:47], v[160:163], v[192:195], v[44:47]
	v_mfma_f32_16x16x32_bf16 v[36:39], v[152:155], v[200:203], v[36:39]
	v_mfma_f32_16x16x32_bf16 v[28:31], v[160:163], v[200:203], v[28:31]
	v_mfma_f32_16x16x32_bf16 v[20:23], v[152:155], v[212:215], v[20:23]
	v_mfma_f32_16x16x32_bf16 v[12:15], v[160:163], v[212:215], v[12:15]
	v_mfma_f32_16x16x32_bf16 v[60:63], v[156:159], v[188:191], v[60:63]
	v_mfma_f32_16x16x32_bf16 v[56:59], v[164:167], v[188:191], v[56:59]
	v_mfma_f32_16x16x32_bf16 v[52:55], v[156:159], v[196:199], v[52:55]
	v_mfma_f32_16x16x32_bf16 v[44:47], v[164:167], v[196:199], v[44:47]
	v_mfma_f32_16x16x32_bf16 v[36:39], v[156:159], v[204:207], v[36:39]
	v_mfma_f32_16x16x32_bf16 v[28:31], v[164:167], v[204:207], v[28:31]
	v_mfma_f32_16x16x32_bf16 v[20:23], v[156:159], v[216:219], v[20:23]
	v_mfma_f32_16x16x32_bf16 v[12:15], v[164:167], v[216:219], v[12:15]
	s_setprio 0
	s_setprio 1
	v_mfma_f32_16x16x32_bf16 v[48:51], v[168:171], v[184:187], v[48:51]
	v_mfma_f32_16x16x32_bf16 v[40:43], v[176:179], v[184:187], v[40:43]
	v_mfma_f32_16x16x32_bf16 v[32:35], v[168:171], v[192:195], v[32:35]
	v_mfma_f32_16x16x32_bf16 v[24:27], v[176:179], v[192:195], v[24:27]
	v_mfma_f32_16x16x32_bf16 v[16:19], v[168:171], v[200:203], v[16:19]
	v_mfma_f32_16x16x32_bf16 v[8:11], v[176:179], v[200:203], v[8:11]
	v_mfma_f32_16x16x32_bf16 v[4:7], v[168:171], v[212:215], v[4:7]
	v_mfma_f32_16x16x32_bf16 v[0:3], v[176:179], v[212:215], v[0:3]
	v_mfma_f32_16x16x32_bf16 v[48:51], v[172:175], v[188:191], v[48:51]
	v_mfma_f32_16x16x32_bf16 v[40:43], v[180:183], v[188:191], v[40:43]
	v_mfma_f32_16x16x32_bf16 v[32:35], v[172:175], v[196:199], v[32:35]
	v_mfma_f32_16x16x32_bf16 v[24:27], v[180:183], v[196:199], v[24:27]
	v_mfma_f32_16x16x32_bf16 v[16:19], v[172:175], v[204:207], v[16:19]
	v_mfma_f32_16x16x32_bf16 v[8:11], v[180:183], v[204:207], v[8:11]
	v_mfma_f32_16x16x32_bf16 v[4:7], v[172:175], v[216:219], v[4:7]
	v_mfma_f32_16x16x32_bf16 v[0:3], v[180:183], v[216:219], v[0:3]
	s_setprio 0
	s_barrier
	s_add_i32 s48, 0, 0x18000
	s_add_i32 s49, 0, 0x1c000
	v_add_u32_e32 v164, s48, v147
	v_add_u32_e32 v180, s49, v147
	ds_read_b128 v[152:155], v164
	ds_read_b128 v[156:159], v164 offset:1024
	ds_read_b128 v[160:163], v164 offset:2048
	ds_read_b128 v[164:167], v164 offset:3072
	ds_read_b128 v[168:171], v180
	ds_read_b128 v[172:175], v180 offset:1024
	ds_read_b128 v[176:179], v180 offset:2048
	ds_read_b128 v[180:183], v180 offset:3072
	s_add_u32 s24, s24, 0x40000
	s_addc_u32 s25, s25, 0
	s_mov_b32 m0, s30
	v_lshl_add_u64 v[226:227], s[24:25], 0, v[134:135]
	ds_read_b128 v[184:187], v151 offset:32768
	ds_read_b128 v[188:191], v151 offset:33792
	ds_read_b128 v[192:195], v151 offset:34816
	ds_read_b128 v[196:199], v151 offset:35840
	ds_read_b128 v[200:203], v151 offset:36864
	ds_read_b128 v[204:207], v151 offset:37888
	ds_read_b128 v[212:215], v151 offset:38912
	ds_read_b128 v[216:219], v151 offset:39936
	global_load_lds_dwordx4 v[226:227], off
	v_lshl_add_u64 v[226:227], s[24:25], 0, v[130:131]
	s_mov_b32 m0, s31
	s_nop 0
	global_load_lds_dwordx4 v[226:227], off
	s_waitcnt vmcnt(8)
	s_waitcnt lgkmcnt(0)
	s_barrier
	s_setprio 1
	s_waitcnt lgkmcnt(0)
	v_mfma_f32_16x16x32_bf16 v[124:127], v[152:155], v[184:187], v[124:127]
	v_mfma_f32_16x16x32_bf16 v[120:123], v[160:163], v[184:187], v[120:123]
	v_mfma_f32_16x16x32_bf16 v[116:119], v[152:155], v[192:195], v[116:119]
	v_mfma_f32_16x16x32_bf16 v[108:111], v[160:163], v[192:195], v[108:111]
	v_mfma_f32_16x16x32_bf16 v[100:103], v[152:155], v[200:203], v[100:103]
	v_mfma_f32_16x16x32_bf16 v[92:95], v[160:163], v[200:203], v[92:95]
	v_mfma_f32_16x16x32_bf16 v[84:87], v[152:155], v[212:215], v[84:87]
	v_mfma_f32_16x16x32_bf16 v[76:79], v[160:163], v[212:215], v[76:79]
	v_mfma_f32_16x16x32_bf16 v[124:127], v[156:159], v[188:191], v[124:127]
	v_mfma_f32_16x16x32_bf16 v[120:123], v[164:167], v[188:191], v[120:123]
	v_mfma_f32_16x16x32_bf16 v[116:119], v[156:159], v[196:199], v[116:119]
	v_mfma_f32_16x16x32_bf16 v[108:111], v[164:167], v[196:199], v[108:111]
	v_mfma_f32_16x16x32_bf16 v[100:103], v[156:159], v[204:207], v[100:103]
	v_mfma_f32_16x16x32_bf16 v[92:95], v[164:167], v[204:207], v[92:95]
	v_mfma_f32_16x16x32_bf16 v[84:87], v[156:159], v[216:219], v[84:87]
	v_mfma_f32_16x16x32_bf16 v[76:79], v[164:167], v[216:219], v[76:79]
	s_setprio 0
	s_setprio 1
	v_mfma_f32_16x16x32_bf16 v[112:115], v[168:171], v[184:187], v[112:115]
	v_mfma_f32_16x16x32_bf16 v[104:107], v[176:179], v[184:187], v[104:107]
	v_mfma_f32_16x16x32_bf16 v[96:99], v[168:171], v[192:195], v[96:99]
	v_mfma_f32_16x16x32_bf16 v[88:91], v[176:179], v[192:195], v[88:91]
	v_mfma_f32_16x16x32_bf16 v[80:83], v[168:171], v[200:203], v[80:83]
	v_mfma_f32_16x16x32_bf16 v[72:75], v[176:179], v[200:203], v[72:75]
	v_mfma_f32_16x16x32_bf16 v[68:71], v[168:171], v[212:215], v[68:71]
	v_mfma_f32_16x16x32_bf16 v[64:67], v[176:179], v[212:215], v[64:67]
	v_mfma_f32_16x16x32_bf16 v[112:115], v[172:175], v[188:191], v[112:115]
	v_mfma_f32_16x16x32_bf16 v[104:107], v[180:183], v[188:191], v[104:107]
	v_mfma_f32_16x16x32_bf16 v[96:99], v[172:175], v[196:199], v[96:99]
	v_mfma_f32_16x16x32_bf16 v[88:91], v[180:183], v[196:199], v[88:91]
	v_mfma_f32_16x16x32_bf16 v[80:83], v[172:175], v[204:207], v[80:83]
	v_mfma_f32_16x16x32_bf16 v[72:75], v[180:183], v[204:207], v[72:75]
	v_mfma_f32_16x16x32_bf16 v[68:71], v[172:175], v[216:219], v[68:71]
	v_mfma_f32_16x16x32_bf16 v[64:67], v[180:183], v[216:219], v[64:67]
	s_setprio 0
	s_barrier
; #define PG8_STAGE(bufoff, gbase, voff) do { _Pragma("unroll") for (int _i = 0; _i < 2; ++_i) \
;         __builtin_amdgcn_global_load_lds((const unsigned*)((const char*)(gbase) + (voff)[_i]), (PG8_LAS unsigned*)(lds + (bufoff) + ldsw + _i * 8192), 16, 0, 0); } while (0)
; #define PG8_LDA(dst, b, h) do { _Pragma("unroll") for (int m = 0; m < 4; ++m) _Pragma("unroll") for (int k = 0; k < 2; ++k) dst[m][k] = *(const PG8_LAS bf16x8*)(lds + PG8_SA(b, h) + aoff + m * 2048 + k * 1024); } while (0)
; #define PG8_MMA(ai, bj, At, Bt) do { __builtin_amdgcn_s_setprio(1); _Pragma("unroll") for (int m = 0; m < 4; ++m) _Pragma("unroll") for (int n = 0; n < 2; ++n) _Pragma("unroll") for (int k = 0; k < 2; ++k) \
;         acc[ai][bj][m][n] = __builtin_amdgcn_mfma_f32_16x16x32_bf16(Bt[n][k], At[m][k], acc[ai][bj][m][n], 0, 0, 0); __builtin_amdgcn_s_setprio(0); } while (0)
; #define PG8_WAIT_V(n) asm volatile("s_waitcnt vmcnt(" #n ")" ::: "memory")
; #define PG8_WAIT_L(n) asm volatile("s_waitcnt lgkmcnt(" #n ")" ::: "memory")
; #define PG8_BAR __builtin_amdgcn_s_barrier()
; #define PG8_SCHED __builtin_amdgcn_sched_barrier(0)
; template <class Epi, class Sched, bool ALIGN_EPI = false, bool SP2 = false>
; __device__ __forceinline__ void gemm_phase(PG8_LAS unsigned char* lds, const Gemm g, const Sched& S, const Epi& E, const int wid) {
;     ...
;             PG8_LDA(At, 1, 1); PG8_STAGE(PG8_SB(1, 0), b3, voffB); PG8_STAGE(PG8_SB(1, 1), b3 + hstep, voffB); PG8_STAGE(PG8_SA(1, 0), a3, voffA);
;             PG8_WAIT_V(8); PG8_WAIT_L(0); PG8_BAR; PG8_MMA(1, 0, At, B0); PG8_MMA(1, 1, At, B1); PG8_BAR; PG8_SCHED;
;     ...
;         if constexpr (ALIGN_EPI) { if (wr == 0) PG8_BAR; }
	s_add_i32 s24, s48, s26
	v_lshl_add_u64 v[144:145], v[144:145], 0, s[6:7]
	s_mov_b32 m0, s24
	ds_read_b128 v[184:187], v151 offset:49152
	ds_read_b128 v[188:191], v151 offset:50176
	ds_read_b128 v[192:195], v151 offset:51200
	ds_read_b128 v[196:199], v151 offset:52224
	ds_read_b128 v[200:203], v151 offset:53248
	ds_read_b128 v[204:207], v151 offset:54272
	ds_read_b128 v[212:215], v151 offset:55296
	ds_read_b128 v[216:219], v151 offset:56320
	global_load_lds_dwordx4 v[144:145], off
	s_add_i32 m0, s24, 0x2000
	s_add_u32 s22, s22, 0x40080
	v_lshl_add_u64 v[144:145], v[220:221], 0, s[6:7]
	s_addc_u32 s23, s23, 0
	s_add_i32 s24, s49, s26
	global_load_lds_dwordx4 v[144:145], off
	v_lshl_add_u64 v[144:145], s[22:23], 0, v[132:133]
	s_mov_b32 m0, s24
	s_nop 0
	global_load_lds_dwordx4 v[144:145], off
	v_lshl_add_u64 v[144:145], s[22:23], 0, v[128:129]
	s_add_i32 m0, s24, 0x2000
	s_nop 0
	global_load_lds_dwordx4 v[144:145], off
	v_lshl_add_u64 v[144:145], v[222:223], 0, s[6:7]
	s_mov_b32 m0, s37
	s_nop 0
	global_load_lds_dwordx4 v[144:145], off
	v_lshl_add_u64 v[144:145], v[224:225], 0, s[6:7]
	s_mov_b32 m0, s38
	s_nop 0
	global_load_lds_dwordx4 v[144:145], off
	s_waitcnt vmcnt(8)
	s_waitcnt lgkmcnt(0)
	s_barrier
	s_setprio 1
	s_waitcnt lgkmcnt(0)
	v_mfma_f32_16x16x32_bf16 v[60:63], v[152:155], v[184:187], v[60:63]
	v_mfma_f32_16x16x32_bf16 v[56:59], v[160:163], v[184:187], v[56:59]
	v_mfma_f32_16x16x32_bf16 v[52:55], v[152:155], v[192:195], v[52:55]
	v_mfma_f32_16x16x32_bf16 v[44:47], v[160:163], v[192:195], v[44:47]
	v_mfma_f32_16x16x32_bf16 v[36:39], v[152:155], v[200:203], v[36:39]
	v_mfma_f32_16x16x32_bf16 v[28:31], v[160:163], v[200:203], v[28:31]
	v_mfma_f32_16x16x32_bf16 v[20:23], v[152:155], v[212:215], v[20:23]
	v_mfma_f32_16x16x32_bf16 v[12:15], v[160:163], v[212:215], v[12:15]
	v_mfma_f32_16x16x32_bf16 v[60:63], v[156:159], v[188:191], v[60:63]
	v_mfma_f32_16x16x32_bf16 v[56:59], v[164:167], v[188:191], v[56:59]
	v_mfma_f32_16x16x32_bf16 v[52:55], v[156:159], v[196:199], v[52:55]
	v_mfma_f32_16x16x32_bf16 v[44:47], v[164:167], v[196:199], v[44:47]
	v_mfma_f32_16x16x32_bf16 v[36:39], v[156:159], v[204:207], v[36:39]
	v_mfma_f32_16x16x32_bf16 v[28:31], v[164:167], v[204:207], v[28:31]
	v_mfma_f32_16x16x32_bf16 v[20:23], v[156:159], v[216:219], v[20:23]
	v_mfma_f32_16x16x32_bf16 v[12:15], v[164:167], v[216:219], v[12:15]
	s_setprio 0
	s_setprio 1
	v_mfma_f32_16x16x32_bf16 v[48:51], v[168:171], v[184:187], v[48:51]
	v_mfma_f32_16x16x32_bf16 v[40:43], v[176:179], v[184:187], v[40:43]
	v_mfma_f32_16x16x32_bf16 v[32:35], v[168:171], v[192:195], v[32:35]
	v_mfma_f32_16x16x32_bf16 v[24:27], v[176:179], v[192:195], v[24:27]
	v_mfma_f32_16x16x32_bf16 v[16:19], v[168:171], v[200:203], v[16:19]
	v_mfma_f32_16x16x32_bf16 v[8:11], v[176:179], v[200:203], v[8:11]
	v_mfma_f32_16x16x32_bf16 v[4:7], v[168:171], v[212:215], v[4:7]
	v_mfma_f32_16x16x32_bf16 v[0:3], v[176:179], v[212:215], v[0:3]
	v_mfma_f32_16x16x32_bf16 v[48:51], v[172:175], v[188:191], v[48:51]
	v_mfma_f32_16x16x32_bf16 v[40:43], v[180:183], v[188:191], v[40:43]
	v_mfma_f32_16x16x32_bf16 v[32:35], v[172:175], v[196:199], v[32:35]
	v_mfma_f32_16x16x32_bf16 v[24:27], v[180:183], v[196:199], v[24:27]
	v_mfma_f32_16x16x32_bf16 v[16:19], v[172:175], v[204:207], v[16:19]
	v_mfma_f32_16x16x32_bf16 v[8:11], v[180:183], v[204:207], v[8:11]
	v_mfma_f32_16x16x32_bf16 v[4:7], v[172:175], v[216:219], v[4:7]
	v_mfma_f32_16x16x32_bf16 v[0:3], v[180:183], v[216:219], v[0:3]
	s_setprio 0
	s_add_i32 s47, s47, 2
	s_add_u32 s20, s20, 0x100
	s_addc_u32 s21, s21, 0
	s_add_u32 s45, s45, 0x100
	s_addc_u32 s46, s46, 0
	s_cmp_gt_u32 s47, 13
	s_barrier
	s_cbranch_scc0 .LBB0_882
	s_and_b64 vcc, exec, s[2:3]
	s_cbranch_vccz .LBB0_885
	s_barrier

; #define PG8_STAGE(bufoff, gbase, voff) do { _Pragma("unroll") for (int _i = 0; _i < 2; ++_i) \
;         __builtin_amdgcn_global_load_lds((const unsigned*)((const char*)(gbase) + (voff)[_i]), (PG8_LAS unsigned*)(lds + (bufoff) + ldsw + _i * 8192), 16, 0, 0); } while (0)
; #define PG8_LDA(dst, b, h) do { _Pragma("unroll") for (int m = 0; m < 4; ++m) _Pragma("unroll") for (int k = 0; k < 2; ++k) dst[m][k] = *(const PG8_LAS bf16x8*)(lds + PG8_SA(b, h) + aoff + m * 2048 + k * 1024); } while (0)
; #define PG8_LDB(dst, b, h) do { _Pragma("unroll") for (int n = 0; n < 2; ++n) _Pragma("unroll") for (int k = 0; k < 2; ++k) dst[n][k] = *(const PG8_LAS bf16x8*)(lds + PG8_SB(b, h) + boff + n * 2048 + k * 1024); } while (0)
; #define PG8_MMA(ai, bj, At, Bt) do { __builtin_amdgcn_s_setprio(1); _Pragma("unroll") for (int m = 0; m < 4; ++m) _Pragma("unroll") for (int n = 0; n < 2; ++n) _Pragma("unroll") for (int k = 0; k < 2; ++k) \
;         acc[ai][bj][m][n] = __builtin_amdgcn_mfma_f32_16x16x32_bf16(Bt[n][k], At[m][k], acc[ai][bj][m][n], 0, 0, 0); __builtin_amdgcn_s_setprio(0); } while (0)
; #define PG8_WAIT_V(n) asm volatile("s_waitcnt vmcnt(" #n ")" ::: "memory")
; #define PG8_WAIT_L(n) asm volatile("s_waitcnt lgkmcnt(" #n ")" ::: "memory")
; #define PG8_BAR __builtin_amdgcn_s_barrier()
; #define PG8_SCHED __builtin_amdgcn_sched_barrier(0)
; template <class Epi, class Sched, bool ALIGN_EPI = false, bool SP2 = false>
; __device__ __forceinline__ void gemm_phase(PG8_LAS unsigned char* lds, const Gemm g, const Sched& S, const Epi& E, const int wid) {
;     ...
;             PG8_LDB(B0, 0, 0); PG8_LDB(B1, 0, 1); PG8_SCHED; PG8_LDA(At, 0, 0); PG8_STAGE(PG8_SA(1, 1), a1 + hstep, voffA);
;             PG8_WAIT_V(8); PG8_WAIT_L(0); PG8_BAR; PG8_MMA(0, 0, At, B0); PG8_MMA(0, 1, At, B1); PG8_BAR; PG8_SCHED;
;             PG8_LDA(At, 0, 1); PG8_STAGE(PG8_SB(0, 0), b2, voffB); PG8_STAGE(PG8_SB(0, 1), b2 + hstep, voffB); PG8_STAGE(PG8_SA(0, 0), a2, voffA);
;             PG8_WAIT_V(8); PG8_WAIT_L(0); PG8_BAR; PG8_MMA(1, 0, At, B0); PG8_MMA(1, 1, At, B1); PG8_BAR; PG8_SCHED;
.LBB0_1786:
	v_add_u32_e32 v164, s41, v150
	v_add_u32_e32 v180, s42, v150
	s_add_u32 s22, s8, s20
	ds_read_b128 v[152:155], v164
	ds_read_b128 v[156:159], v164 offset:1024
	ds_read_b128 v[160:163], v164 offset:2048
	ds_read_b128 v[164:167], v164 offset:3072
	ds_read_b128 v[168:171], v180
	ds_read_b128 v[172:175], v180 offset:1024
	ds_read_b128 v[176:179], v180 offset:2048
	ds_read_b128 v[180:183], v180 offset:3072
	s_addc_u32 s23, s9, s21
	s_add_u32 s22, s22, 0x100
	s_addc_u32 s23, s23, 0
	s_add_u32 s49, s44, s20
	s_addc_u32 s50, s45, s21
	s_cmpk_eq_i32 s20, 0x700
	s_cselect_b32 s25, s15, s23
	s_cselect_b32 s24, s46, s22
	s_cselect_b32 s23, s13, s50
	s_cselect_b32 s22, s47, s49
	v_lshl_add_u64 v[206:207], v[144:145], 0, s[20:21]
	s_add_i32 m0, s33, 0xc000
	ds_read_b128 v[186:189], v151
	ds_read_b128 v[190:193], v151 offset:1024
	ds_read_b128 v[194:197], v151 offset:2048
	ds_read_b128 v[198:201], v151 offset:3072
	ds_read_b128 v[202:205], v151 offset:4096
	ds_read_b128 v[210:213], v151 offset:5120
	ds_read_b128 v[214:217], v151 offset:6144
	ds_read_b128 v[218:221], v151 offset:7168
	global_load_lds_dwordx4 v[206:207], off
	v_lshl_add_u64 v[206:207], v[146:147], 0, s[20:21]
	s_add_i32 m0, s33, 0xe000
	s_nop 0
	global_load_lds_dwordx4 v[206:207], off
	s_waitcnt vmcnt(8)
	s_waitcnt lgkmcnt(0)
	s_barrier
	s_setprio 1
	s_waitcnt lgkmcnt(0)
	v_mfma_f32_16x16x32_bf16 v[124:127], v[152:155], v[186:189], v[124:127]
	v_mfma_f32_16x16x32_bf16 v[120:123], v[160:163], v[186:189], v[120:123]
	v_mfma_f32_16x16x32_bf16 v[112:115], v[152:155], v[194:197], v[112:115]
	v_mfma_f32_16x16x32_bf16 v[104:107], v[160:163], v[194:197], v[104:107]
	v_mfma_f32_16x16x32_bf16 v[96:99], v[152:155], v[202:205], v[96:99]
	v_mfma_f32_16x16x32_bf16 v[88:91], v[160:163], v[202:205], v[88:91]
	v_mfma_f32_16x16x32_bf16 v[80:83], v[152:155], v[214:217], v[80:83]
	v_mfma_f32_16x16x32_bf16 v[72:75], v[160:163], v[214:217], v[72:75]
	v_mfma_f32_16x16x32_bf16 v[124:127], v[156:159], v[190:193], v[124:127]
	v_mfma_f32_16x16x32_bf16 v[120:123], v[164:167], v[190:193], v[120:123]
	v_mfma_f32_16x16x32_bf16 v[112:115], v[156:159], v[198:201], v[112:115]
	v_mfma_f32_16x16x32_bf16 v[104:107], v[164:167], v[198:201], v[104:107]
	v_mfma_f32_16x16x32_bf16 v[96:99], v[156:159], v[210:213], v[96:99]
	v_mfma_f32_16x16x32_bf16 v[88:91], v[164:167], v[210:213], v[88:91]
	v_mfma_f32_16x16x32_bf16 v[80:83], v[156:159], v[218:221], v[80:83]
	v_mfma_f32_16x16x32_bf16 v[72:75], v[164:167], v[218:221], v[72:75]
	s_setprio 0
	s_setprio 1
	v_mfma_f32_16x16x32_bf16 v[116:119], v[168:171], v[186:189], v[116:119]
	v_mfma_f32_16x16x32_bf16 v[108:111], v[176:179], v[186:189], v[108:111]
	v_mfma_f32_16x16x32_bf16 v[100:103], v[168:171], v[194:197], v[100:103]
	v_mfma_f32_16x16x32_bf16 v[92:95], v[176:179], v[194:197], v[92:95]
	v_mfma_f32_16x16x32_bf16 v[84:87], v[168:171], v[202:205], v[84:87]
	v_mfma_f32_16x16x32_bf16 v[76:79], v[176:179], v[202:205], v[76:79]
	v_mfma_f32_16x16x32_bf16 v[68:71], v[168:171], v[214:217], v[68:71]
	v_mfma_f32_16x16x32_bf16 v[64:67], v[176:179], v[214:217], v[64:67]
	v_mfma_f32_16x16x32_bf16 v[116:119], v[172:175], v[190:193], v[116:119]
	v_mfma_f32_16x16x32_bf16 v[108:111], v[180:183], v[190:193], v[108:111]
	v_mfma_f32_16x16x32_bf16 v[100:103], v[172:175], v[198:201], v[100:103]
	v_mfma_f32_16x16x32_bf16 v[92:95], v[180:183], v[198:201], v[92:95]
	v_mfma_f32_16x16x32_bf16 v[84:87], v[172:175], v[210:213], v[84:87]
	v_mfma_f32_16x16x32_bf16 v[76:79], v[180:183], v[210:213], v[76:79]
	v_mfma_f32_16x16x32_bf16 v[68:71], v[172:175], v[218:221], v[68:71]
	v_mfma_f32_16x16x32_bf16 v[64:67], v[180:183], v[218:221], v[64:67]
	s_setprio 0
	s_barrier
	s_add_i32 s49, s41, s31
	v_lshl_add_u64 v[206:207], s[22:23], 0, v[130:131]
	s_mov_b32 m0, s49
	ds_read_b128 v[186:189], v151 offset:16384
	ds_read_b128 v[190:193], v151 offset:17408
	ds_read_b128 v[194:197], v151 offset:18432
	ds_read_b128 v[198:201], v151 offset:19456
	ds_read_b128 v[202:205], v151 offset:20480
	ds_read_b128 v[210:213], v151 offset:21504
	ds_read_b128 v[214:217], v151 offset:22528
	ds_read_b128 v[218:221], v151 offset:23552
	global_load_lds_dwordx4 v[206:207], off
	s_add_i32 m0, s49, 0x2000
	s_add_u32 s50, s22, 0x40000
	v_lshl_add_u64 v[222:223], s[22:23], 0, v[134:135]
	s_addc_u32 s51, s23, 0
	s_add_i32 s49, s42, s31
	global_load_lds_dwordx4 v[222:223], off
	v_lshl_add_u64 v[224:225], s[50:51], 0, v[130:131]
	s_mov_b32 m0, s49
	v_lshl_add_u64 v[226:227], s[24:25], 0, v[132:133]
	global_load_lds_dwordx4 v[224:225], off
	v_lshl_add_u64 v[224:225], s[50:51], 0, v[134:135]
	s_add_i32 m0, s49, 0x2000
	s_nop 0
	global_load_lds_dwordx4 v[224:225], off
	v_lshl_add_u64 v[224:225], s[24:25], 0, v[128:129]
	s_mov_b32 m0, s33
	s_nop 0
	global_load_lds_dwordx4 v[224:225], off
	s_mov_b32 m0, s34
	s_nop 0
	global_load_lds_dwordx4 v[226:227], off
	s_waitcnt vmcnt(8)
	s_waitcnt lgkmcnt(0)
	s_barrier
; #define PG8_STAGE(bufoff, gbase, voff) do { _Pragma("unroll") for (int _i = 0; _i < 2; ++_i) \
;         __builtin_amdgcn_global_load_lds((const unsigned*)((const char*)(gbase) + (voff)[_i]), (PG8_LAS unsigned*)(lds + (bufoff) + ldsw + _i * 8192), 16, 0, 0); } while (0)
; #define PG8_LDA(dst, b, h) do { _Pragma("unroll") for (int m = 0; m < 4; ++m) _Pragma("unroll") for (int k = 0; k < 2; ++k) dst[m][k] = *(const PG8_LAS bf16x8*)(lds + PG8_SA(b, h) + aoff + m * 2048 + k * 1024); } while (0)
; #define PG8_LDB(dst, b, h) do { _Pragma("unroll") for (int n = 0; n < 2; ++n) _Pragma("unroll") for (int k = 0; k < 2; ++k) dst[n][k] = *(const PG8_LAS bf16x8*)(lds + PG8_SB(b, h) + boff + n * 2048 + k * 1024); } while (0)
; #define PG8_MMA(ai, bj, At, Bt) do { __builtin_amdgcn_s_setprio(1); _Pragma("unroll") for (int m = 0; m < 4; ++m) _Pragma("unroll") for (int n = 0; n < 2; ++n) _Pragma("unroll") for (int k = 0; k < 2; ++k) \
;         acc[ai][bj][m][n] = __builtin_amdgcn_mfma_f32_16x16x32_bf16(Bt[n][k], At[m][k], acc[ai][bj][m][n], 0, 0, 0); __builtin_amdgcn_s_setprio(0); } while (0)
; #define PG8_WAIT_V(n) asm volatile("s_waitcnt vmcnt(" #n ")" ::: "memory")
; #define PG8_WAIT_L(n) asm volatile("s_waitcnt lgkmcnt(" #n ")" ::: "memory")
; #define PG8_BAR __builtin_amdgcn_s_barrier()
; #define PG8_SCHED __builtin_amdgcn_sched_barrier(0)
; template <class Epi, class Sched, bool ALIGN_EPI = false, bool SP2 = false>
; __device__ __forceinline__ void gemm_phase(PG8_LAS unsigned char* lds, const Gemm g, const Sched& S, const Epi& E, const int wid) {
;     ...
;             PG8_WAIT_V(8); PG8_WAIT_L(0); PG8_BAR; PG8_MMA(1, 0, At, B0); PG8_MMA(1, 1, At, B1); PG8_BAR; PG8_SCHED;
;             PG8_LDB(B0, 1, 0); PG8_LDB(B1, 1, 1); PG8_SCHED; PG8_LDA(At, 1, 0); PG8_STAGE(PG8_SA(0, 1), a2 + hstep, voffA);
;             PG8_WAIT_V(8); PG8_WAIT_L(0); PG8_BAR; PG8_MMA(0, 0, At, B0); PG8_MMA(0, 1, At, B1); PG8_BAR; PG8_SCHED;
	s_setprio 1
	s_waitcnt lgkmcnt(0)
	v_mfma_f32_16x16x32_bf16 v[60:63], v[152:155], v[186:189], v[60:63]
	v_mfma_f32_16x16x32_bf16 v[56:59], v[160:163], v[186:189], v[56:59]
	v_mfma_f32_16x16x32_bf16 v[44:47], v[152:155], v[194:197], v[44:47]
	v_mfma_f32_16x16x32_bf16 v[40:43], v[160:163], v[194:197], v[40:43]
	v_mfma_f32_16x16x32_bf16 v[28:31], v[152:155], v[202:205], v[28:31]
	v_mfma_f32_16x16x32_bf16 v[24:27], v[160:163], v[202:205], v[24:27]
	v_mfma_f32_16x16x32_bf16 v[12:15], v[152:155], v[214:217], v[12:15]
	v_mfma_f32_16x16x32_bf16 v[8:11], v[160:163], v[214:217], v[8:11]
	v_mfma_f32_16x16x32_bf16 v[60:63], v[156:159], v[190:193], v[60:63]
	v_mfma_f32_16x16x32_bf16 v[56:59], v[164:167], v[190:193], v[56:59]
	v_mfma_f32_16x16x32_bf16 v[44:47], v[156:159], v[198:201], v[44:47]
	v_mfma_f32_16x16x32_bf16 v[40:43], v[164:167], v[198:201], v[40:43]
	v_mfma_f32_16x16x32_bf16 v[28:31], v[156:159], v[210:213], v[28:31]
	v_mfma_f32_16x16x32_bf16 v[24:27], v[164:167], v[210:213], v[24:27]
	v_mfma_f32_16x16x32_bf16 v[12:15], v[156:159], v[218:221], v[12:15]
	v_mfma_f32_16x16x32_bf16 v[8:11], v[164:167], v[218:221], v[8:11]
	s_setprio 0
	s_setprio 1
	v_mfma_f32_16x16x32_bf16 v[52:55], v[168:171], v[186:189], v[52:55]
	v_mfma_f32_16x16x32_bf16 v[48:51], v[176:179], v[186:189], v[48:51]
	v_mfma_f32_16x16x32_bf16 v[36:39], v[168:171], v[194:197], v[36:39]
	v_mfma_f32_16x16x32_bf16 v[32:35], v[176:179], v[194:197], v[32:35]
	v_mfma_f32_16x16x32_bf16 v[20:23], v[168:171], v[202:205], v[20:23]
	v_mfma_f32_16x16x32_bf16 v[16:19], v[176:179], v[202:205], v[16:19]
	v_mfma_f32_16x16x32_bf16 v[4:7], v[168:171], v[214:217], v[4:7]
	v_mfma_f32_16x16x32_bf16 v[0:3], v[176:179], v[214:217], v[0:3]
	v_mfma_f32_16x16x32_bf16 v[52:55], v[172:175], v[190:193], v[52:55]
	v_mfma_f32_16x16x32_bf16 v[48:51], v[180:183], v[190:193], v[48:51]
	v_mfma_f32_16x16x32_bf16 v[36:39], v[172:175], v[198:201], v[36:39]
	v_mfma_f32_16x16x32_bf16 v[32:35], v[180:183], v[198:201], v[32:35]
	v_mfma_f32_16x16x32_bf16 v[20:23], v[172:175], v[210:213], v[20:23]
	v_mfma_f32_16x16x32_bf16 v[16:19], v[180:183], v[210:213], v[16:19]
	v_mfma_f32_16x16x32_bf16 v[4:7], v[172:175], v[218:221], v[4:7]
	v_mfma_f32_16x16x32_bf16 v[0:3], v[180:183], v[218:221], v[0:3]
	s_setprio 0
	s_barrier
	s_add_i32 s49, 0, 0x18000
	s_add_i32 s50, 0, 0x1c000
	v_add_u32_e32 v164, s49, v150
	v_add_u32_e32 v180, s50, v150
	ds_read_b128 v[152:155], v164
	ds_read_b128 v[156:159], v164 offset:1024
	ds_read_b128 v[160:163], v164 offset:2048
	ds_read_b128 v[164:167], v164 offset:3072
	ds_read_b128 v[168:171], v180
	ds_read_b128 v[172:175], v180 offset:1024
	ds_read_b128 v[176:179], v180 offset:2048
	ds_read_b128 v[180:183], v180 offset:3072
	s_add_u32 s24, s24, 0x40000
	s_addc_u32 s25, s25, 0
	s_mov_b32 m0, s35
	v_lshl_add_u64 v[228:229], s[24:25], 0, v[128:129]
	ds_read_b128 v[186:189], v151 offset:32768
	ds_read_b128 v[190:193], v151 offset:33792
	ds_read_b128 v[194:197], v151 offset:34816
	ds_read_b128 v[198:201], v151 offset:35840
	ds_read_b128 v[202:205], v151 offset:36864
	ds_read_b128 v[210:213], v151 offset:37888
	ds_read_b128 v[214:217], v151 offset:38912
	ds_read_b128 v[218:221], v151 offset:39936
	global_load_lds_dwordx4 v[228:229], off
	v_lshl_add_u64 v[228:229], s[24:25], 0, v[132:133]
	s_mov_b32 m0, s36
	s_nop 0
	global_load_lds_dwordx4 v[228:229], off
	s_waitcnt vmcnt(8)
	s_waitcnt lgkmcnt(0)
	s_barrier
	s_setprio 1
	s_waitcnt lgkmcnt(0)
	v_mfma_f32_16x16x32_bf16 v[124:127], v[152:155], v[186:189], v[124:127]
	v_mfma_f32_16x16x32_bf16 v[120:123], v[160:163], v[186:189], v[120:123]
	v_mfma_f32_16x16x32_bf16 v[112:115], v[152:155], v[194:197], v[112:115]
	v_mfma_f32_16x16x32_bf16 v[104:107], v[160:163], v[194:197], v[104:107]
	v_mfma_f32_16x16x32_bf16 v[96:99], v[152:155], v[202:205], v[96:99]
	v_mfma_f32_16x16x32_bf16 v[88:91], v[160:163], v[202:205], v[88:91]
	v_mfma_f32_16x16x32_bf16 v[80:83], v[152:155], v[214:217], v[80:83]
	v_mfma_f32_16x16x32_bf16 v[72:75], v[160:163], v[214:217], v[72:75]
	v_mfma_f32_16x16x32_bf16 v[124:127], v[156:159], v[190:193], v[124:127]
	v_mfma_f32_16x16x32_bf16 v[120:123], v[164:167], v[190:193], v[120:123]
	v_mfma_f32_16x16x32_bf16 v[112:115], v[156:159], v[198:201], v[112:115]
	v_mfma_f32_16x16x32_bf16 v[104:107], v[164:167], v[198:201], v[104:107]
	v_mfma_f32_16x16x32_bf16 v[96:99], v[156:159], v[210:213], v[96:99]
	v_mfma_f32_16x16x32_bf16 v[88:91], v[164:167], v[210:213], v[88:91]
	v_mfma_f32_16x16x32_bf16 v[80:83], v[156:159], v[218:221], v[80:83]
	v_mfma_f32_16x16x32_bf16 v[72:75], v[164:167], v[218:221], v[72:75]
	s_setprio 0
	s_setprio 1
	v_mfma_f32_16x16x32_bf16 v[116:119], v[168:171], v[186:189], v[116:119]
	v_mfma_f32_16x16x32_bf16 v[108:111], v[176:179], v[186:189], v[108:111]
	v_mfma_f32_16x16x32_bf16 v[100:103], v[168:171], v[194:197], v[100:103]
	v_mfma_f32_16x16x32_bf16 v[92:95], v[176:179], v[194:197], v[92:95]
	v_mfma_f32_16x16x32_bf16 v[84:87], v[168:171], v[202:205], v[84:87]
	v_mfma_f32_16x16x32_bf16 v[76:79], v[176:179], v[202:205], v[76:79]
	v_mfma_f32_16x16x32_bf16 v[68:71], v[168:171], v[214:217], v[68:71]
	v_mfma_f32_16x16x32_bf16 v[64:67], v[176:179], v[214:217], v[64:67]
	v_mfma_f32_16x16x32_bf16 v[116:119], v[172:175], v[190:193], v[116:119]
	v_mfma_f32_16x16x32_bf16 v[108:111], v[180:183], v[190:193], v[108:111]
	v_mfma_f32_16x16x32_bf16 v[100:103], v[172:175], v[198:201], v[100:103]
	v_mfma_f32_16x16x32_bf16 v[92:95], v[180:183], v[198:201], v[92:95]
	v_mfma_f32_16x16x32_bf16 v[84:87], v[172:175], v[210:213], v[84:87]
	v_mfma_f32_16x16x32_bf16 v[76:79], v[180:183], v[210:213], v[76:79]
	v_mfma_f32_16x16x32_bf16 v[68:71], v[172:175], v[218:221], v[68:71]
	v_mfma_f32_16x16x32_bf16 v[64:67], v[180:183], v[218:221], v[64:67]
	s_setprio 0
	s_barrier
; #define PG8_STAGE(bufoff, gbase, voff) do { _Pragma("unroll") for (int _i = 0; _i < 2; ++_i) \
;         __builtin_amdgcn_global_load_lds((const unsigned*)((const char*)(gbase) + (voff)[_i]), (PG8_LAS unsigned*)(lds + (bufoff) + ldsw + _i * 8192), 16, 0, 0); } while (0)
; #define PG8_LDA(dst, b, h) do { _Pragma("unroll") for (int m = 0; m < 4; ++m) _Pragma("unroll") for (int k = 0; k < 2; ++k) dst[m][k] = *(const PG8_LAS bf16x8*)(lds + PG8_SA(b, h) + aoff + m * 2048 + k * 1024); } while (0)
; #define PG8_MMA(ai, bj, At, Bt) do { __builtin_amdgcn_s_setprio(1); _Pragma("unroll") for (int m = 0; m < 4; ++m) _Pragma("unroll") for (int n = 0; n < 2; ++n) _Pragma("unroll") for (int k = 0; k < 2; ++k) \
;         acc[ai][bj][m][n] = __builtin_amdgcn_mfma_f32_16x16x32_bf16(Bt[n][k], At[m][k], acc[ai][bj][m][n], 0, 0, 0); __builtin_amdgcn_s_setprio(0); } while (0)
; #define PG8_WAIT_V(n) asm volatile("s_waitcnt vmcnt(" #n ")" ::: "memory")
; #define PG8_WAIT_L(n) asm volatile("s_waitcnt lgkmcnt(" #n ")" ::: "memory")
; #define PG8_BAR __builtin_amdgcn_s_barrier()
; #define PG8_SCHED __builtin_amdgcn_sched_barrier(0)
; template <class Epi, class Sched, bool ALIGN_EPI = false, bool SP2 = false>
; __device__ __forceinline__ void gemm_phase(PG8_LAS unsigned char* lds, const Gemm g, const Sched& S, const Epi& E, const int wid) {
;     ...
;             PG8_LDA(At, 1, 1); PG8_STAGE(PG8_SB(1, 0), b3, voffB); PG8_STAGE(PG8_SB(1, 1), b3 + hstep, voffB); PG8_STAGE(PG8_SA(1, 0), a3, voffA);
;             PG8_WAIT_V(8); PG8_WAIT_L(0); PG8_BAR; PG8_MMA(1, 0, At, B0); PG8_MMA(1, 1, At, B1); PG8_BAR; PG8_SCHED;
;     ...
; #pragma unroll
;         for (int a = 0; a < 2; ++a)
; #pragma unroll
;             for (int b = 0; b < 2; ++b)
; #pragma unroll
;                 for (int m = 0; m < 4; ++m)
; #pragma unroll
;                     for (int n = 0; n < 2; ++n) acc[a][b][m][n] = (f32x4){0.f, 0.f, 0.f, 0.f};
	s_add_i32 s24, s49, s31
	v_lshl_add_u64 v[206:207], v[206:207], 0, s[10:11]
	s_mov_b32 m0, s24
	ds_read_b128 v[186:189], v151 offset:49152
	ds_read_b128 v[190:193], v151 offset:50176
	ds_read_b128 v[194:197], v151 offset:51200
	ds_read_b128 v[198:201], v151 offset:52224
	ds_read_b128 v[202:205], v151 offset:53248
	ds_read_b128 v[210:213], v151 offset:54272
	ds_read_b128 v[214:217], v151 offset:55296
	ds_read_b128 v[218:221], v151 offset:56320
	global_load_lds_dwordx4 v[206:207], off
	s_add_i32 m0, s24, 0x2000
	s_add_u32 s22, s22, 0x40080
	v_lshl_add_u64 v[206:207], v[222:223], 0, s[10:11]
	s_addc_u32 s23, s23, 0
	s_add_i32 s24, s50, s31
	global_load_lds_dwordx4 v[206:207], off
	v_lshl_add_u64 v[206:207], s[22:23], 0, v[130:131]
	s_mov_b32 m0, s24
	s_nop 0
	global_load_lds_dwordx4 v[206:207], off
	v_lshl_add_u64 v[206:207], s[22:23], 0, v[134:135]
	s_add_i32 m0, s24, 0x2000
	s_nop 0
	global_load_lds_dwordx4 v[206:207], off
	v_lshl_add_u64 v[206:207], v[224:225], 0, s[10:11]
	s_mov_b32 m0, s38
	s_nop 0
	global_load_lds_dwordx4 v[206:207], off
	v_lshl_add_u64 v[206:207], v[226:227], 0, s[10:11]
	s_mov_b32 m0, s39
	s_nop 0
	global_load_lds_dwordx4 v[206:207], off
	s_waitcnt vmcnt(8)
	s_waitcnt lgkmcnt(0)
	s_barrier
	s_setprio 1
	s_waitcnt lgkmcnt(0)
	v_mfma_f32_16x16x32_bf16 v[60:63], v[152:155], v[186:189], v[60:63]
	v_mfma_f32_16x16x32_bf16 v[56:59], v[160:163], v[186:189], v[56:59]
	v_mfma_f32_16x16x32_bf16 v[44:47], v[152:155], v[194:197], v[44:47]
	v_mfma_f32_16x16x32_bf16 v[40:43], v[160:163], v[194:197], v[40:43]
	v_mfma_f32_16x16x32_bf16 v[28:31], v[152:155], v[202:205], v[28:31]
	v_mfma_f32_16x16x32_bf16 v[24:27], v[160:163], v[202:205], v[24:27]
	v_mfma_f32_16x16x32_bf16 v[12:15], v[152:155], v[214:217], v[12:15]
	v_mfma_f32_16x16x32_bf16 v[8:11], v[160:163], v[214:217], v[8:11]
	v_mfma_f32_16x16x32_bf16 v[60:63], v[156:159], v[190:193], v[60:63]
	v_mfma_f32_16x16x32_bf16 v[56:59], v[164:167], v[190:193], v[56:59]
	v_mfma_f32_16x16x32_bf16 v[44:47], v[156:159], v[198:201], v[44:47]
	v_mfma_f32_16x16x32_bf16 v[40:43], v[164:167], v[198:201], v[40:43]
	v_mfma_f32_16x16x32_bf16 v[28:31], v[156:159], v[210:213], v[28:31]
	v_mfma_f32_16x16x32_bf16 v[24:27], v[164:167], v[210:213], v[24:27]
	v_mfma_f32_16x16x32_bf16 v[12:15], v[156:159], v[218:221], v[12:15]
	v_mfma_f32_16x16x32_bf16 v[8:11], v[164:167], v[218:221], v[8:11]
	s_setprio 0
	s_setprio 1
	v_mfma_f32_16x16x32_bf16 v[52:55], v[168:171], v[186:189], v[52:55]
	v_mfma_f32_16x16x32_bf16 v[48:51], v[176:179], v[186:189], v[48:51]
	v_mfma_f32_16x16x32_bf16 v[36:39], v[168:171], v[194:197], v[36:39]
	v_mfma_f32_16x16x32_bf16 v[32:35], v[176:179], v[194:197], v[32:35]
	v_mfma_f32_16x16x32_bf16 v[20:23], v[168:171], v[202:205], v[20:23]
	v_mfma_f32_16x16x32_bf16 v[16:19], v[176:179], v[202:205], v[16:19]
	v_mfma_f32_16x16x32_bf16 v[4:7], v[168:171], v[214:217], v[4:7]
	v_mfma_f32_16x16x32_bf16 v[0:3], v[176:179], v[214:217], v[0:3]
	v_mfma_f32_16x16x32_bf16 v[52:55], v[172:175], v[190:193], v[52:55]
	v_mfma_f32_16x16x32_bf16 v[48:51], v[180:183], v[190:193], v[48:51]
	v_mfma_f32_16x16x32_bf16 v[36:39], v[172:175], v[198:201], v[36:39]
	v_mfma_f32_16x16x32_bf16 v[32:35], v[180:183], v[198:201], v[32:35]
	v_mfma_f32_16x16x32_bf16 v[20:23], v[172:175], v[210:213], v[20:23]
	v_mfma_f32_16x16x32_bf16 v[16:19], v[180:183], v[210:213], v[16:19]
	v_mfma_f32_16x16x32_bf16 v[4:7], v[172:175], v[218:221], v[4:7]
	v_mfma_f32_16x16x32_bf16 v[0:3], v[180:183], v[218:221], v[0:3]
	s_setprio 0
	s_add_i32 s48, s48, 2
	s_add_u32 s20, s20, 0x100
	s_addc_u32 s21, s21, 0
	s_cmp_gt_u32 s48, 13
	s_barrier
	s_cbranch_scc0 .LBB0_1786
	s_add_u32 s20, s44, 0xffffff00
	s_addc_u32 s21, s45, -1
	s_andn2_b64 vcc, exec, s[6:7]
	s_cbranch_vccnz .LBB0_1777
	v_mov_b32_e32 v0, 0
	s_mov_b32 s2, s12
	s_mov_b32 s0, s14
	s_mov_b64 s[8:9], s[18:19]
	s_mov_b32 s40, s43
	v_mov_b32_e32 v1, v0
	v_mov_b32_e32 v2, v0
	v_mov_b32_e32 v3, v0
	v_mov_b32_e32 v4, v0
	v_mov_b32_e32 v5, v0
	v_mov_b32_e32 v6, v0
	v_mov_b32_e32 v7, v0
	v_mov_b32_e32 v16, v0
	v_mov_b32_e32 v17, v0
	v_mov_b32_e32 v18, v0
	v_mov_b32_e32 v19, v0
	v_mov_b32_e32 v20, v0
	v_mov_b32_e32 v21, v0
	v_mov_b32_e32 v22, v0
	v_mov_b32_e32 v23, v0
	v_mov_b32_e32 v32, v0
	v_mov_b32_e32 v33, v0
	v_mov_b32_e32 v34, v0
	v_mov_b32_e32 v35, v0
	v_mov_b32_e32 v36, v0
	v_mov_b32_e32 v37, v0
	v_mov_b32_e32 v38, v0
	v_mov_b32_e32 v39, v0
	v_mov_b32_e32 v48, v0
	v_mov_b32_e32 v49, v0
	v_mov_b32_e32 v50, v0
	v_mov_b32_e32 v51, v0
	v_mov_b32_e32 v52, v0
	v_mov_b32_e32 v53, v0
	v_mov_b32_e32 v54, v0
	v_mov_b32_e32 v55, v0
	v_mov_b32_e32 v8, v0
	v_mov_b32_e32 v9, v0
	v_mov_b32_e32 v10, v0
	v_mov_b32_e32 v11, v0
	v_mov_b32_e32 v12, v0
	v_mov_b32_e32 v13, v0
	v_mov_b32_e32 v14, v0
	v_mov_b32_e32 v15, v0
	v_mov_b32_e32 v24, v0
	v_mov_b32_e32 v25, v0
	v_mov_b32_e32 v26, v0
	v_mov_b32_e32 v27, v0
	v_mov_b32_e32 v28, v0
	v_mov_b32_e32 v29, v0
	v_mov_b32_e32 v30, v0
	v_mov_b32_e32 v31, v0
	v_mov_b32_e32 v40, v0
	v_mov_b32_e32 v41, v0
	v_mov_b32_e32 v42, v0
	v_mov_b32_e32 v43, v0
	v_mov_b32_e32 v44, v0
	v_mov_b32_e32 v45, v0
	v_mov_b32_e32 v46, v0
	v_mov_b32_e32 v47, v0
	v_mov_b32_e32 v56, v0
	v_mov_b32_e32 v57, v0
	v_mov_b32_e32 v58, v0
	v_mov_b32_e32 v59, v0
	v_mov_b32_e32 v60, v0
	v_mov_b32_e32 v61, v0
	v_mov_b32_e32 v62, v0
	v_mov_b32_e32 v63, v0
	v_mov_b32_e32 v64, v0
	v_mov_b32_e32 v65, v0
	v_mov_b32_e32 v66, v0
	v_mov_b32_e32 v67, v0
	v_mov_b32_e32 v68, v0
	v_mov_b32_e32 v69, v0
	v_mov_b32_e32 v70, v0
	v_mov_b32_e32 v71, v0
	v_mov_b32_e32 v76, v0
	v_mov_b32_e32 v77, v0
	v_mov_b32_e32 v78, v0
	v_mov_b32_e32 v79, v0
	v_mov_b32_e32 v84, v0
	v_mov_b32_e32 v85, v0
	v_mov_b32_e32 v86, v0
	v_mov_b32_e32 v87, v0
	v_mov_b32_e32 v92, v0
	v_mov_b32_e32 v93, v0
	v_mov_b32_e32 v94, v0
	v_mov_b32_e32 v95, v0
	v_mov_b32_e32 v100, v0
	v_mov_b32_e32 v101, v0
	v_mov_b32_e32 v102, v0
	v_mov_b32_e32 v103, v0
	v_mov_b32_e32 v108, v0
	v_mov_b32_e32 v109, v0
	v_mov_b32_e32 v110, v0
	v_mov_b32_e32 v111, v0
	v_mov_b32_e32 v116, v0
	v_mov_b32_e32 v117, v0
	v_mov_b32_e32 v118, v0
	v_mov_b32_e32 v119, v0
	v_mov_b32_e32 v72, v0
	v_mov_b32_e32 v73, v0
	v_mov_b32_e32 v74, v0
	v_mov_b32_e32 v75, v0
	v_mov_b32_e32 v80, v0
	v_mov_b32_e32 v81, v0
	v_mov_b32_e32 v82, v0
	v_mov_b32_e32 v83, v0
	v_mov_b32_e32 v88, v0
	v_mov_b32_e32 v89, v0
	v_mov_b32_e32 v90, v0
	v_mov_b32_e32 v91, v0
	v_mov_b32_e32 v96, v0
	v_mov_b32_e32 v97, v0
	v_mov_b32_e32 v98, v0
	v_mov_b32_e32 v99, v0
	v_mov_b32_e32 v104, v0
	v_mov_b32_e32 v105, v0
	v_mov_b32_e32 v106, v0
	v_mov_b32_e32 v107, v0
	v_mov_b32_e32 v112, v0
	v_mov_b32_e32 v113, v0
	v_mov_b32_e32 v114, v0
	v_mov_b32_e32 v115, v0
	v_mov_b32_e32 v120, v0
	v_mov_b32_e32 v121, v0
	v_mov_b32_e32 v122, v0
	v_mov_b32_e32 v123, v0
	v_mov_b32_e32 v124, v0
	v_mov_b32_e32 v125, v0
	v_mov_b32_e32 v126, v0
	v_mov_b32_e32 v127, v0
	s_andn2_b64 vcc, exec, s[4:5]
	s_cbranch_vccnz .LBB0_1778

; #define PG8_STAGE(bufoff, gbase, voff) do { _Pragma("unroll") for (int _i = 0; _i < 2; ++_i) \
;         __builtin_amdgcn_global_load_lds((const unsigned*)((const char*)(gbase) + (voff)[_i]), (PG8_LAS unsigned*)(lds + (bufoff) + ldsw + _i * 8192), 16, 0, 0); } while (0)
; #define PG8_LDA(dst, b, h) do { _Pragma("unroll") for (int m = 0; m < 4; ++m) _Pragma("unroll") for (int k = 0; k < 2; ++k) dst[m][k] = *(const PG8_LAS bf16x8*)(lds + PG8_SA(b, h) + aoff + m * 2048 + k * 1024); } while (0)
; #define PG8_LDB(dst, b, h) do { _Pragma("unroll") for (int n = 0; n < 2; ++n) _Pragma("unroll") for (int k = 0; k < 2; ++k) dst[n][k] = *(const PG8_LAS bf16x8*)(lds + PG8_SB(b, h) + boff + n * 2048 + k * 1024); } while (0)
; #define PG8_MMA(ai, bj, At, Bt) do { __builtin_amdgcn_s_setprio(1); _Pragma("unroll") for (int m = 0; m < 4; ++m) _Pragma("unroll") for (int n = 0; n < 2; ++n) _Pragma("unroll") for (int k = 0; k < 2; ++k) \
;         acc[ai][bj][m][n] = __builtin_amdgcn_mfma_f32_16x16x32_bf16(Bt[n][k], At[m][k], acc[ai][bj][m][n], 0, 0, 0); __builtin_amdgcn_s_setprio(0); } while (0)
; #define PG8_WAIT_V(n) asm volatile("s_waitcnt vmcnt(" #n ")" ::: "memory")
; #define PG8_WAIT_L(n) asm volatile("s_waitcnt lgkmcnt(" #n ")" ::: "memory")
; #define PG8_BAR __builtin_amdgcn_s_barrier()
; #define PG8_SCHED __builtin_amdgcn_sched_barrier(0)
; template <class Epi, class Sched, bool ALIGN_EPI = false, bool SP2 = false>
; __device__ __forceinline__ void gemm_phase(PG8_LAS unsigned char* lds, const Gemm g, const Sched& S, const Epi& E, const int wid) {
;     ...
;             PG8_LDB(B0, 0, 0); PG8_LDB(B1, 0, 1); PG8_SCHED; PG8_LDA(At, 0, 0); PG8_STAGE(PG8_SA(1, 1), a1 + hstep, voffA);
;             PG8_WAIT_V(8); PG8_WAIT_L(0); PG8_BAR; PG8_MMA(0, 0, At, B0); PG8_MMA(0, 1, At, B1); PG8_BAR; PG8_SCHED;
;             PG8_LDA(At, 0, 1); PG8_STAGE(PG8_SB(0, 0), b2, voffB); PG8_STAGE(PG8_SB(0, 1), b2 + hstep, voffB); PG8_STAGE(PG8_SA(0, 0), a2, voffA);
;             PG8_WAIT_V(8); PG8_WAIT_L(0); PG8_BAR; PG8_MMA(1, 0, At, B0); PG8_MMA(1, 1, At, B1); PG8_BAR; PG8_SCHED;
.LBB0_1912:
	ds_read_b128 v[144:147], v151
	ds_read_b128 v[154:157], v151 offset:1024
	ds_read_b128 v[158:161], v151 offset:2048
	ds_read_b128 v[162:165], v151 offset:3072
	ds_read_b128 v[166:169], v152
	ds_read_b128 v[170:173], v152 offset:1024
	ds_read_b128 v[174:177], v152 offset:2048
	ds_read_b128 v[178:181], v152 offset:3072
	s_add_u32 s24, s22, 0xfffc0080
	s_addc_u32 s25, s23, -1
	s_cmp_eq_u32 s46, 12
	s_cselect_b32 s27, s15, s25
	s_cselect_b32 s26, s42, s24
	s_cselect_b32 s25, s13, s45
	s_cselect_b32 s24, s43, s44
	v_lshl_add_u64 v[206:207], s[22:23], 0, v[136:137]
	s_add_i32 m0, s21, 0xc000
	ds_read_b128 v[182:185], v153
	ds_read_b128 v[186:189], v153 offset:1024
	ds_read_b128 v[190:193], v153 offset:2048
	ds_read_b128 v[194:197], v153 offset:3072
	ds_read_b128 v[198:201], v153 offset:4096
	ds_read_b128 v[202:205], v153 offset:5120
	ds_read_b128 v[210:213], v153 offset:6144
	ds_read_b128 v[214:217], v153 offset:7168
	global_load_lds_dwordx4 v[206:207], off
	v_lshl_add_u64 v[206:207], s[22:23], 0, v[138:139]
	s_add_i32 m0, s21, 0xe000
	s_nop 0
	global_load_lds_dwordx4 v[206:207], off
	s_waitcnt vmcnt(8)
	s_waitcnt lgkmcnt(0)
	s_barrier
	s_setprio 1
	s_waitcnt lgkmcnt(0)
	v_mfma_f32_16x16x32_bf16 v[124:127], v[144:147], v[182:185], v[124:127]
	v_mfma_f32_16x16x32_bf16 v[116:119], v[158:161], v[182:185], v[116:119]
	v_mfma_f32_16x16x32_bf16 v[108:111], v[144:147], v[190:193], v[108:111]
	v_mfma_f32_16x16x32_bf16 v[100:103], v[158:161], v[190:193], v[100:103]
	v_mfma_f32_16x16x32_bf16 v[92:95], v[144:147], v[198:201], v[92:95]
	v_mfma_f32_16x16x32_bf16 v[84:87], v[158:161], v[198:201], v[84:87]
	v_mfma_f32_16x16x32_bf16 v[76:79], v[144:147], v[210:213], v[76:79]
	v_mfma_f32_16x16x32_bf16 v[68:71], v[158:161], v[210:213], v[68:71]
	v_mfma_f32_16x16x32_bf16 v[124:127], v[154:157], v[186:189], v[124:127]
	v_mfma_f32_16x16x32_bf16 v[116:119], v[162:165], v[186:189], v[116:119]
	v_mfma_f32_16x16x32_bf16 v[108:111], v[154:157], v[194:197], v[108:111]
	v_mfma_f32_16x16x32_bf16 v[100:103], v[162:165], v[194:197], v[100:103]
	v_mfma_f32_16x16x32_bf16 v[92:95], v[154:157], v[202:205], v[92:95]
	v_mfma_f32_16x16x32_bf16 v[84:87], v[162:165], v[202:205], v[84:87]
	v_mfma_f32_16x16x32_bf16 v[76:79], v[154:157], v[214:217], v[76:79]
	v_mfma_f32_16x16x32_bf16 v[68:71], v[162:165], v[214:217], v[68:71]
	s_setprio 0
	s_setprio 1
	v_mfma_f32_16x16x32_bf16 v[120:123], v[166:169], v[182:185], v[120:123]
	v_mfma_f32_16x16x32_bf16 v[112:115], v[174:177], v[182:185], v[112:115]
	v_mfma_f32_16x16x32_bf16 v[104:107], v[166:169], v[190:193], v[104:107]
	v_mfma_f32_16x16x32_bf16 v[96:99], v[174:177], v[190:193], v[96:99]
	v_mfma_f32_16x16x32_bf16 v[88:91], v[166:169], v[198:201], v[88:91]
	v_mfma_f32_16x16x32_bf16 v[80:83], v[174:177], v[198:201], v[80:83]
	v_mfma_f32_16x16x32_bf16 v[72:75], v[166:169], v[210:213], v[72:75]
	v_mfma_f32_16x16x32_bf16 v[64:67], v[174:177], v[210:213], v[64:67]
	v_mfma_f32_16x16x32_bf16 v[120:123], v[170:173], v[186:189], v[120:123]
	v_mfma_f32_16x16x32_bf16 v[112:115], v[178:181], v[186:189], v[112:115]
	v_mfma_f32_16x16x32_bf16 v[104:107], v[170:173], v[194:197], v[104:107]
	v_mfma_f32_16x16x32_bf16 v[96:99], v[178:181], v[194:197], v[96:99]
	v_mfma_f32_16x16x32_bf16 v[88:91], v[170:173], v[202:205], v[88:91]
	v_mfma_f32_16x16x32_bf16 v[80:83], v[178:181], v[202:205], v[80:83]
	v_mfma_f32_16x16x32_bf16 v[72:75], v[170:173], v[214:217], v[72:75]
	v_mfma_f32_16x16x32_bf16 v[64:67], v[178:181], v[214:217], v[64:67]
	s_setprio 0
	s_barrier
	s_add_i32 s47, s38, s9
	v_lshl_add_u64 v[206:207], s[24:25], 0, v[132:133]
	s_mov_b32 m0, s47
	ds_read_b128 v[182:185], v153 offset:16384
	ds_read_b128 v[186:189], v153 offset:17408
	ds_read_b128 v[190:193], v153 offset:18432
	ds_read_b128 v[194:197], v153 offset:19456
	ds_read_b128 v[198:201], v153 offset:20480
	ds_read_b128 v[202:205], v153 offset:21504
	ds_read_b128 v[210:213], v153 offset:22528
	ds_read_b128 v[214:217], v153 offset:23552
	global_load_lds_dwordx4 v[206:207], off
	s_add_i32 m0, s47, 0x2000
	s_add_u32 s48, s24, 0x40000
	v_lshl_add_u64 v[218:219], s[24:25], 0, v[128:129]
	s_addc_u32 s49, s25, 0
	s_add_i32 s47, s39, s9
	global_load_lds_dwordx4 v[218:219], off
	v_lshl_add_u64 v[220:221], s[48:49], 0, v[132:133]
	s_mov_b32 m0, s47
	v_lshl_add_u64 v[222:223], s[26:27], 0, v[130:131]
	global_load_lds_dwordx4 v[220:221], off
	v_lshl_add_u64 v[220:221], s[48:49], 0, v[128:129]
	s_add_i32 m0, s47, 0x2000
	s_nop 0
	global_load_lds_dwordx4 v[220:221], off
	v_lshl_add_u64 v[220:221], s[26:27], 0, v[134:135]
	s_mov_b32 m0, s21
	s_nop 0
	global_load_lds_dwordx4 v[220:221], off
	s_mov_b32 m0, s30
	s_nop 0
	global_load_lds_dwordx4 v[222:223], off
	s_waitcnt vmcnt(8)
	s_waitcnt lgkmcnt(0)
	s_barrier
; #define PG8_STAGE(bufoff, gbase, voff) do { _Pragma("unroll") for (int _i = 0; _i < 2; ++_i) \
;         __builtin_amdgcn_global_load_lds((const unsigned*)((const char*)(gbase) + (voff)[_i]), (PG8_LAS unsigned*)(lds + (bufoff) + ldsw + _i * 8192), 16, 0, 0); } while (0)
; #define PG8_LDA(dst, b, h) do { _Pragma("unroll") for (int m = 0; m < 4; ++m) _Pragma("unroll") for (int k = 0; k < 2; ++k) dst[m][k] = *(const PG8_LAS bf16x8*)(lds + PG8_SA(b, h) + aoff + m * 2048 + k * 1024); } while (0)
; #define PG8_LDB(dst, b, h) do { _Pragma("unroll") for (int n = 0; n < 2; ++n) _Pragma("unroll") for (int k = 0; k < 2; ++k) dst[n][k] = *(const PG8_LAS bf16x8*)(lds + PG8_SB(b, h) + boff + n * 2048 + k * 1024); } while (0)
; #define PG8_MMA(ai, bj, At, Bt) do { __builtin_amdgcn_s_setprio(1); _Pragma("unroll") for (int m = 0; m < 4; ++m) _Pragma("unroll") for (int n = 0; n < 2; ++n) _Pragma("unroll") for (int k = 0; k < 2; ++k) \
;         acc[ai][bj][m][n] = __builtin_amdgcn_mfma_f32_16x16x32_bf16(Bt[n][k], At[m][k], acc[ai][bj][m][n], 0, 0, 0); __builtin_amdgcn_s_setprio(0); } while (0)
; #define PG8_WAIT_V(n) asm volatile("s_waitcnt vmcnt(" #n ")" ::: "memory")
; #define PG8_WAIT_L(n) asm volatile("s_waitcnt lgkmcnt(" #n ")" ::: "memory")
; #define PG8_BAR __builtin_amdgcn_s_barrier()
; #define PG8_SCHED __builtin_amdgcn_sched_barrier(0)
; template <class Epi, class Sched, bool ALIGN_EPI = false, bool SP2 = false>
; __device__ __forceinline__ void gemm_phase(PG8_LAS unsigned char* lds, const Gemm g, const Sched& S, const Epi& E, const int wid) {
;     ...
;             PG8_WAIT_V(8); PG8_WAIT_L(0); PG8_BAR; PG8_MMA(1, 0, At, B0); PG8_MMA(1, 1, At, B1); PG8_BAR; PG8_SCHED;
;             PG8_LDB(B0, 1, 0); PG8_LDB(B1, 1, 1); PG8_SCHED; PG8_LDA(At, 1, 0); PG8_STAGE(PG8_SA(0, 1), a2 + hstep, voffA);
;             PG8_WAIT_V(8); PG8_WAIT_L(0); PG8_BAR; PG8_MMA(0, 0, At, B0); PG8_MMA(0, 1, At, B1); PG8_BAR; PG8_SCHED;
	s_setprio 1
	s_waitcnt lgkmcnt(0)
	v_mfma_f32_16x16x32_bf16 v[60:63], v[144:147], v[182:185], v[60:63]
	v_mfma_f32_16x16x32_bf16 v[52:55], v[158:161], v[182:185], v[52:55]
	v_mfma_f32_16x16x32_bf16 v[44:47], v[144:147], v[190:193], v[44:47]
	v_mfma_f32_16x16x32_bf16 v[36:39], v[158:161], v[190:193], v[36:39]
	v_mfma_f32_16x16x32_bf16 v[28:31], v[144:147], v[198:201], v[28:31]
	v_mfma_f32_16x16x32_bf16 v[20:23], v[158:161], v[198:201], v[20:23]
	v_mfma_f32_16x16x32_bf16 v[12:15], v[144:147], v[210:213], v[12:15]
	v_mfma_f32_16x16x32_bf16 v[4:7], v[158:161], v[210:213], v[4:7]
	v_mfma_f32_16x16x32_bf16 v[60:63], v[154:157], v[186:189], v[60:63]
	v_mfma_f32_16x16x32_bf16 v[52:55], v[162:165], v[186:189], v[52:55]
	v_mfma_f32_16x16x32_bf16 v[44:47], v[154:157], v[194:197], v[44:47]
	v_mfma_f32_16x16x32_bf16 v[36:39], v[162:165], v[194:197], v[36:39]
	v_mfma_f32_16x16x32_bf16 v[28:31], v[154:157], v[202:205], v[28:31]
	v_mfma_f32_16x16x32_bf16 v[20:23], v[162:165], v[202:205], v[20:23]
	v_mfma_f32_16x16x32_bf16 v[12:15], v[154:157], v[214:217], v[12:15]
	v_mfma_f32_16x16x32_bf16 v[4:7], v[162:165], v[214:217], v[4:7]
	s_setprio 0
	s_setprio 1
	v_mfma_f32_16x16x32_bf16 v[56:59], v[166:169], v[182:185], v[56:59]
	v_mfma_f32_16x16x32_bf16 v[48:51], v[174:177], v[182:185], v[48:51]
	v_mfma_f32_16x16x32_bf16 v[40:43], v[166:169], v[190:193], v[40:43]
	v_mfma_f32_16x16x32_bf16 v[32:35], v[174:177], v[190:193], v[32:35]
	v_mfma_f32_16x16x32_bf16 v[24:27], v[166:169], v[198:201], v[24:27]
	v_mfma_f32_16x16x32_bf16 v[16:19], v[174:177], v[198:201], v[16:19]
	v_mfma_f32_16x16x32_bf16 v[8:11], v[166:169], v[210:213], v[8:11]
	v_mfma_f32_16x16x32_bf16 v[0:3], v[174:177], v[210:213], v[0:3]
	v_mfma_f32_16x16x32_bf16 v[56:59], v[170:173], v[186:189], v[56:59]
	v_mfma_f32_16x16x32_bf16 v[48:51], v[178:181], v[186:189], v[48:51]
	v_mfma_f32_16x16x32_bf16 v[40:43], v[170:173], v[194:197], v[40:43]
	v_mfma_f32_16x16x32_bf16 v[32:35], v[178:181], v[194:197], v[32:35]
	v_mfma_f32_16x16x32_bf16 v[24:27], v[170:173], v[202:205], v[24:27]
	v_mfma_f32_16x16x32_bf16 v[16:19], v[178:181], v[202:205], v[16:19]
	v_mfma_f32_16x16x32_bf16 v[8:11], v[170:173], v[214:217], v[8:11]
	v_mfma_f32_16x16x32_bf16 v[0:3], v[178:181], v[214:217], v[0:3]
	s_setprio 0
	s_barrier
	s_add_i32 s47, 0, 0x18000
	s_add_i32 s48, 0, 0x1c000
	v_add_u32_e32 v162, s47, v149
	v_add_u32_e32 v178, s48, v149
	ds_read_b128 v[144:147], v162
	ds_read_b128 v[154:157], v162 offset:1024
	ds_read_b128 v[158:161], v162 offset:2048
	ds_read_b128 v[162:165], v162 offset:3072
	ds_read_b128 v[166:169], v178
	ds_read_b128 v[170:173], v178 offset:1024
	ds_read_b128 v[174:177], v178 offset:2048
	ds_read_b128 v[178:181], v178 offset:3072
	s_add_u32 s26, s26, 0x40000
	s_addc_u32 s27, s27, 0
	s_mov_b32 m0, s31
	v_lshl_add_u64 v[224:225], s[26:27], 0, v[134:135]
	ds_read_b128 v[182:185], v153 offset:32768
	ds_read_b128 v[186:189], v153 offset:33792
	ds_read_b128 v[190:193], v153 offset:34816
	ds_read_b128 v[194:197], v153 offset:35840
	ds_read_b128 v[198:201], v153 offset:36864
	ds_read_b128 v[202:205], v153 offset:37888
	ds_read_b128 v[210:213], v153 offset:38912
	ds_read_b128 v[214:217], v153 offset:39936
	global_load_lds_dwordx4 v[224:225], off
	v_lshl_add_u64 v[224:225], s[26:27], 0, v[130:131]
	s_mov_b32 m0, s33
	s_nop 0
	global_load_lds_dwordx4 v[224:225], off
	s_waitcnt vmcnt(8)
	s_waitcnt lgkmcnt(0)
	s_barrier
	s_setprio 1
	s_waitcnt lgkmcnt(0)
	v_mfma_f32_16x16x32_bf16 v[124:127], v[144:147], v[182:185], v[124:127]
	v_mfma_f32_16x16x32_bf16 v[116:119], v[158:161], v[182:185], v[116:119]
	v_mfma_f32_16x16x32_bf16 v[108:111], v[144:147], v[190:193], v[108:111]
	v_mfma_f32_16x16x32_bf16 v[100:103], v[158:161], v[190:193], v[100:103]
	v_mfma_f32_16x16x32_bf16 v[92:95], v[144:147], v[198:201], v[92:95]
	v_mfma_f32_16x16x32_bf16 v[84:87], v[158:161], v[198:201], v[84:87]
	v_mfma_f32_16x16x32_bf16 v[76:79], v[144:147], v[210:213], v[76:79]
	v_mfma_f32_16x16x32_bf16 v[68:71], v[158:161], v[210:213], v[68:71]
	v_mfma_f32_16x16x32_bf16 v[124:127], v[154:157], v[186:189], v[124:127]
	v_mfma_f32_16x16x32_bf16 v[116:119], v[162:165], v[186:189], v[116:119]
	v_mfma_f32_16x16x32_bf16 v[108:111], v[154:157], v[194:197], v[108:111]
	v_mfma_f32_16x16x32_bf16 v[100:103], v[162:165], v[194:197], v[100:103]
	v_mfma_f32_16x16x32_bf16 v[92:95], v[154:157], v[202:205], v[92:95]
	v_mfma_f32_16x16x32_bf16 v[84:87], v[162:165], v[202:205], v[84:87]
	v_mfma_f32_16x16x32_bf16 v[76:79], v[154:157], v[214:217], v[76:79]
	v_mfma_f32_16x16x32_bf16 v[68:71], v[162:165], v[214:217], v[68:71]
	s_setprio 0
	s_setprio 1
	v_mfma_f32_16x16x32_bf16 v[120:123], v[166:169], v[182:185], v[120:123]
	v_mfma_f32_16x16x32_bf16 v[112:115], v[174:177], v[182:185], v[112:115]
	v_mfma_f32_16x16x32_bf16 v[104:107], v[166:169], v[190:193], v[104:107]
	v_mfma_f32_16x16x32_bf16 v[96:99], v[174:177], v[190:193], v[96:99]
	v_mfma_f32_16x16x32_bf16 v[88:91], v[166:169], v[198:201], v[88:91]
	v_mfma_f32_16x16x32_bf16 v[80:83], v[174:177], v[198:201], v[80:83]
	v_mfma_f32_16x16x32_bf16 v[72:75], v[166:169], v[210:213], v[72:75]
	v_mfma_f32_16x16x32_bf16 v[64:67], v[174:177], v[210:213], v[64:67]
	v_mfma_f32_16x16x32_bf16 v[120:123], v[170:173], v[186:189], v[120:123]
	v_mfma_f32_16x16x32_bf16 v[112:115], v[178:181], v[186:189], v[112:115]
	v_mfma_f32_16x16x32_bf16 v[104:107], v[170:173], v[194:197], v[104:107]
	v_mfma_f32_16x16x32_bf16 v[96:99], v[178:181], v[194:197], v[96:99]
	v_mfma_f32_16x16x32_bf16 v[88:91], v[170:173], v[202:205], v[88:91]
	v_mfma_f32_16x16x32_bf16 v[80:83], v[178:181], v[202:205], v[80:83]
	v_mfma_f32_16x16x32_bf16 v[72:75], v[170:173], v[214:217], v[72:75]
	v_mfma_f32_16x16x32_bf16 v[64:67], v[178:181], v[214:217], v[64:67]
	s_setprio 0
	s_barrier
; #define PG8_STAGE(bufoff, gbase, voff) do { _Pragma("unroll") for (int _i = 0; _i < 2; ++_i) \
;         __builtin_amdgcn_global_load_lds((const unsigned*)((const char*)(gbase) + (voff)[_i]), (PG8_LAS unsigned*)(lds + (bufoff) + ldsw + _i * 8192), 16, 0, 0); } while (0)
; #define PG8_LDA(dst, b, h) do { _Pragma("unroll") for (int m = 0; m < 4; ++m) _Pragma("unroll") for (int k = 0; k < 2; ++k) dst[m][k] = *(const PG8_LAS bf16x8*)(lds + PG8_SA(b, h) + aoff + m * 2048 + k * 1024); } while (0)
; #define PG8_MMA(ai, bj, At, Bt) do { __builtin_amdgcn_s_setprio(1); _Pragma("unroll") for (int m = 0; m < 4; ++m) _Pragma("unroll") for (int n = 0; n < 2; ++n) _Pragma("unroll") for (int k = 0; k < 2; ++k) \
;         acc[ai][bj][m][n] = __builtin_amdgcn_mfma_f32_16x16x32_bf16(Bt[n][k], At[m][k], acc[ai][bj][m][n], 0, 0, 0); __builtin_amdgcn_s_setprio(0); } while (0)
; #define PG8_WAIT_V(n) asm volatile("s_waitcnt vmcnt(" #n ")" ::: "memory")
; #define PG8_WAIT_L(n) asm volatile("s_waitcnt lgkmcnt(" #n ")" ::: "memory")
; #define PG8_BAR __builtin_amdgcn_s_barrier()
; #define PG8_SCHED __builtin_amdgcn_sched_barrier(0)
; template <class Epi, class Sched, bool ALIGN_EPI = false, bool SP2 = false>
; __device__ __forceinline__ void gemm_phase(PG8_LAS unsigned char* lds, const Gemm g, const Sched& S, const Epi& E, const int wid) {
;     ...
;             PG8_LDA(At, 1, 1); PG8_STAGE(PG8_SB(1, 0), b3, voffB); PG8_STAGE(PG8_SB(1, 1), b3 + hstep, voffB); PG8_STAGE(PG8_SA(1, 0), a3, voffA);
;             PG8_WAIT_V(8); PG8_WAIT_L(0); PG8_BAR; PG8_MMA(1, 0, At, B0); PG8_MMA(1, 1, At, B1); PG8_BAR; PG8_SCHED;
;     ...
;         if constexpr (ALIGN_EPI) { if (wr == 0) PG8_BAR; }
	s_add_i32 s26, s47, s9
	v_lshl_add_u64 v[206:207], v[206:207], 0, s[2:3]
	s_mov_b32 m0, s26
	ds_read_b128 v[182:185], v153 offset:49152
	ds_read_b128 v[186:189], v153 offset:50176
	ds_read_b128 v[190:193], v153 offset:51200
	ds_read_b128 v[194:197], v153 offset:52224
	ds_read_b128 v[198:201], v153 offset:53248
	ds_read_b128 v[202:205], v153 offset:54272
	ds_read_b128 v[210:213], v153 offset:55296
	ds_read_b128 v[214:217], v153 offset:56320
	global_load_lds_dwordx4 v[206:207], off
	s_add_i32 m0, s26, 0x2000
	s_add_u32 s24, s24, 0x40080
	v_lshl_add_u64 v[206:207], v[218:219], 0, s[2:3]
	s_addc_u32 s25, s25, 0
	s_add_i32 s26, s48, s9
	global_load_lds_dwordx4 v[206:207], off
	v_lshl_add_u64 v[206:207], s[24:25], 0, v[132:133]
	s_mov_b32 m0, s26
	s_nop 0
	global_load_lds_dwordx4 v[206:207], off
	v_lshl_add_u64 v[206:207], s[24:25], 0, v[128:129]
	s_add_i32 m0, s26, 0x2000
	s_nop 0
	global_load_lds_dwordx4 v[206:207], off
	v_lshl_add_u64 v[206:207], v[220:221], 0, s[2:3]
	s_mov_b32 m0, s35
	s_nop 0
	global_load_lds_dwordx4 v[206:207], off
	v_lshl_add_u64 v[206:207], v[222:223], 0, s[2:3]
	s_mov_b32 m0, s36
	s_nop 0
	global_load_lds_dwordx4 v[206:207], off
	s_waitcnt vmcnt(8)
	s_waitcnt lgkmcnt(0)
	s_barrier
	s_setprio 1
	s_waitcnt lgkmcnt(0)
	v_mfma_f32_16x16x32_bf16 v[60:63], v[144:147], v[182:185], v[60:63]
	v_mfma_f32_16x16x32_bf16 v[52:55], v[158:161], v[182:185], v[52:55]
	v_mfma_f32_16x16x32_bf16 v[44:47], v[144:147], v[190:193], v[44:47]
	v_mfma_f32_16x16x32_bf16 v[36:39], v[158:161], v[190:193], v[36:39]
	v_mfma_f32_16x16x32_bf16 v[28:31], v[144:147], v[198:201], v[28:31]
	v_mfma_f32_16x16x32_bf16 v[20:23], v[158:161], v[198:201], v[20:23]
	v_mfma_f32_16x16x32_bf16 v[12:15], v[144:147], v[210:213], v[12:15]
	v_mfma_f32_16x16x32_bf16 v[4:7], v[158:161], v[210:213], v[4:7]
	v_mfma_f32_16x16x32_bf16 v[60:63], v[154:157], v[186:189], v[60:63]
	v_mfma_f32_16x16x32_bf16 v[52:55], v[162:165], v[186:189], v[52:55]
	v_mfma_f32_16x16x32_bf16 v[44:47], v[154:157], v[194:197], v[44:47]
	v_mfma_f32_16x16x32_bf16 v[36:39], v[162:165], v[194:197], v[36:39]
	v_mfma_f32_16x16x32_bf16 v[28:31], v[154:157], v[202:205], v[28:31]
	v_mfma_f32_16x16x32_bf16 v[20:23], v[162:165], v[202:205], v[20:23]
	v_mfma_f32_16x16x32_bf16 v[12:15], v[154:157], v[214:217], v[12:15]
	v_mfma_f32_16x16x32_bf16 v[4:7], v[162:165], v[214:217], v[4:7]
	s_setprio 0
	s_setprio 1
	v_mfma_f32_16x16x32_bf16 v[56:59], v[166:169], v[182:185], v[56:59]
	v_mfma_f32_16x16x32_bf16 v[48:51], v[174:177], v[182:185], v[48:51]
	v_mfma_f32_16x16x32_bf16 v[40:43], v[166:169], v[190:193], v[40:43]
	v_mfma_f32_16x16x32_bf16 v[32:35], v[174:177], v[190:193], v[32:35]
	v_mfma_f32_16x16x32_bf16 v[24:27], v[166:169], v[198:201], v[24:27]
	v_mfma_f32_16x16x32_bf16 v[16:19], v[174:177], v[198:201], v[16:19]
	v_mfma_f32_16x16x32_bf16 v[8:11], v[166:169], v[210:213], v[8:11]
	v_mfma_f32_16x16x32_bf16 v[0:3], v[174:177], v[210:213], v[0:3]
	v_mfma_f32_16x16x32_bf16 v[56:59], v[170:173], v[186:189], v[56:59]
	v_mfma_f32_16x16x32_bf16 v[48:51], v[178:181], v[186:189], v[48:51]
	v_mfma_f32_16x16x32_bf16 v[40:43], v[170:173], v[194:197], v[40:43]
	v_mfma_f32_16x16x32_bf16 v[32:35], v[178:181], v[194:197], v[32:35]
	v_mfma_f32_16x16x32_bf16 v[24:27], v[170:173], v[202:205], v[24:27]
	v_mfma_f32_16x16x32_bf16 v[16:19], v[178:181], v[202:205], v[16:19]
	v_mfma_f32_16x16x32_bf16 v[8:11], v[170:173], v[214:217], v[8:11]
	v_mfma_f32_16x16x32_bf16 v[0:3], v[178:181], v[214:217], v[0:3]
	s_setprio 0
	s_add_i32 s46, s46, 2
	s_add_u32 s22, s22, 0x100
	s_addc_u32 s23, s23, 0
	s_add_u32 s44, s44, 0x100
	s_addc_u32 s45, s45, 0
	s_cmp_gt_u32 s46, 13
	s_barrier
	s_cbranch_scc0 .LBB0_1912
	s_and_b64 vcc, exec, s[6:7]
	s_cbranch_vccz .LBB0_1915
	s_barrier

; #define PG8_STAGE(bufoff, gbase, voff) do { _Pragma("unroll") for (int _i = 0; _i < 2; ++_i) \
;         __builtin_amdgcn_global_load_lds((const unsigned*)((const char*)(gbase) + (voff)[_i]), (PG8_LAS unsigned*)(lds + (bufoff) + ldsw + _i * 8192), 16, 0, 0); } while (0)
; #define PG8_LDA(dst, b, h) do { _Pragma("unroll") for (int m = 0; m < 4; ++m) _Pragma("unroll") for (int k = 0; k < 2; ++k) dst[m][k] = *(const PG8_LAS bf16x8*)(lds + PG8_SA(b, h) + aoff + m * 2048 + k * 1024); } while (0)
; #define PG8_LDB(dst, b, h) do { _Pragma("unroll") for (int n = 0; n < 2; ++n) _Pragma("unroll") for (int k = 0; k < 2; ++k) dst[n][k] = *(const PG8_LAS bf16x8*)(lds + PG8_SB(b, h) + boff + n * 2048 + k * 1024); } while (0)
; #define PG8_MMA(ai, bj, At, Bt) do { __builtin_amdgcn_s_setprio(1); _Pragma("unroll") for (int m = 0; m < 4; ++m) _Pragma("unroll") for (int n = 0; n < 2; ++n) _Pragma("unroll") for (int k = 0; k < 2; ++k) \
;         acc[ai][bj][m][n] = __builtin_amdgcn_mfma_f32_16x16x32_bf16(Bt[n][k], At[m][k], acc[ai][bj][m][n], 0, 0, 0); __builtin_amdgcn_s_setprio(0); } while (0)
; #define PG8_WAIT_V(n) asm volatile("s_waitcnt vmcnt(" #n ")" ::: "memory")
; #define PG8_WAIT_L(n) asm volatile("s_waitcnt lgkmcnt(" #n ")" ::: "memory")
; #define PG8_BAR __builtin_amdgcn_s_barrier()
; #define PG8_SCHED __builtin_amdgcn_sched_barrier(0)
; template <class Epi, class Sched, bool ALIGN_EPI = false, bool SP2 = false>
; __device__ __forceinline__ void gemm_phase(PG8_LAS unsigned char* lds, const Gemm g, const Sched& S, const Epi& E, const int wid) {
;     ...
;             PG8_LDB(B0, 0, 0); PG8_LDB(B1, 0, 1); PG8_SCHED; PG8_LDA(At, 0, 0); PG8_STAGE(PG8_SA(1, 1), a1 + hstep, voffA);
;             PG8_WAIT_V(8); PG8_WAIT_L(0); PG8_BAR; PG8_MMA(0, 0, At, B0); PG8_MMA(0, 1, At, B1); PG8_BAR; PG8_SCHED;
;             PG8_LDA(At, 0, 1); PG8_STAGE(PG8_SB(0, 0), b2, voffB); PG8_STAGE(PG8_SB(0, 1), b2 + hstep, voffB); PG8_STAGE(PG8_SA(0, 0), a2, voffA);
;             PG8_WAIT_V(8); PG8_WAIT_L(0); PG8_BAR; PG8_MMA(1, 0, At, B0); PG8_MMA(1, 1, At, B1); PG8_BAR; PG8_SCHED;
.LBB0_2460:
	v_add_u32_e32 v151, s35, v149
	ds_read_b128 v[152:155], v151
	ds_read_b128 v[156:159], v151 offset:1024
	ds_read_b128 v[160:163], v151 offset:2048
	ds_read_b128 v[168:171], v151 offset:3072
	v_add_u32_e32 v151, s36, v149
	s_add_u32 s16, s8, s14
	ds_read_b128 v[172:175], v151
	ds_read_b128 v[178:181], v151 offset:1024
	ds_read_b128 v[182:185], v151 offset:2048
	ds_read_b128 v[186:189], v151 offset:3072
	s_addc_u32 s17, s9, s15
	s_add_u32 s16, s16, 0x100
	s_addc_u32 s17, s17, 0
	s_add_u32 s43, s40, s14
	s_addc_u32 s44, s41, s15
	s_cmpk_eq_i32 s14, 0x1500
	s_cselect_b32 s19, s13, s17
	s_cselect_b32 s18, s12, s16
	s_cselect_b32 s17, s5, s44
	s_cselect_b32 s16, s4, s43
	v_lshl_add_u64 v[222:223], v[144:145], 0, s[14:15]
	s_add_i32 m0, s26, 0xc000
	ds_read_b128 v[190:193], v150
	ds_read_b128 v[194:197], v150 offset:1024
	ds_read_b128 v[198:201], v150 offset:2048
	ds_read_b128 v[202:205], v150 offset:3072
	ds_read_b128 v[206:209], v150 offset:4096
	ds_read_b128 v[210:213], v150 offset:5120
	ds_read_b128 v[214:217], v150 offset:6144
	ds_read_b128 v[218:221], v150 offset:7168
	global_load_lds_dwordx4 v[222:223], off
	v_lshl_add_u64 v[222:223], v[146:147], 0, s[14:15]
	s_add_i32 m0, s26, 0xe000
	s_nop 0
	global_load_lds_dwordx4 v[222:223], off
	s_waitcnt vmcnt(8)
	s_waitcnt lgkmcnt(0)
	s_barrier
	s_setprio 1
	s_waitcnt lgkmcnt(0)
	v_mfma_f32_16x16x32_bf16 v[124:127], v[152:155], v[190:193], v[124:127]
	v_mfma_f32_16x16x32_bf16 v[120:123], v[160:163], v[190:193], v[120:123]
	v_mfma_f32_16x16x32_bf16 v[112:115], v[152:155], v[198:201], v[112:115]
	v_mfma_f32_16x16x32_bf16 v[104:107], v[160:163], v[198:201], v[104:107]
	v_mfma_f32_16x16x32_bf16 v[96:99], v[152:155], v[206:209], v[96:99]
	v_mfma_f32_16x16x32_bf16 v[88:91], v[160:163], v[206:209], v[88:91]
	v_mfma_f32_16x16x32_bf16 v[80:83], v[152:155], v[214:217], v[80:83]
	v_mfma_f32_16x16x32_bf16 v[72:75], v[160:163], v[214:217], v[72:75]
	v_mfma_f32_16x16x32_bf16 v[124:127], v[156:159], v[194:197], v[124:127]
	v_mfma_f32_16x16x32_bf16 v[120:123], v[168:171], v[194:197], v[120:123]
	v_mfma_f32_16x16x32_bf16 v[112:115], v[156:159], v[202:205], v[112:115]
	v_mfma_f32_16x16x32_bf16 v[104:107], v[168:171], v[202:205], v[104:107]
	v_mfma_f32_16x16x32_bf16 v[96:99], v[156:159], v[210:213], v[96:99]
	v_mfma_f32_16x16x32_bf16 v[88:91], v[168:171], v[210:213], v[88:91]
	v_mfma_f32_16x16x32_bf16 v[80:83], v[156:159], v[218:221], v[80:83]
	v_mfma_f32_16x16x32_bf16 v[72:75], v[168:171], v[218:221], v[72:75]
	s_setprio 0
	s_setprio 1
	v_mfma_f32_16x16x32_bf16 v[116:119], v[172:175], v[190:193], v[116:119]
	v_mfma_f32_16x16x32_bf16 v[108:111], v[182:185], v[190:193], v[108:111]
	v_mfma_f32_16x16x32_bf16 v[100:103], v[172:175], v[198:201], v[100:103]
	v_mfma_f32_16x16x32_bf16 v[92:95], v[182:185], v[198:201], v[92:95]
	v_mfma_f32_16x16x32_bf16 v[84:87], v[172:175], v[206:209], v[84:87]
	v_mfma_f32_16x16x32_bf16 v[76:79], v[182:185], v[206:209], v[76:79]
	v_mfma_f32_16x16x32_bf16 v[68:71], v[172:175], v[214:217], v[68:71]
	v_mfma_f32_16x16x32_bf16 v[64:67], v[182:185], v[214:217], v[64:67]
	v_mfma_f32_16x16x32_bf16 v[116:119], v[178:181], v[194:197], v[116:119]
	v_mfma_f32_16x16x32_bf16 v[108:111], v[186:189], v[194:197], v[108:111]
	v_mfma_f32_16x16x32_bf16 v[100:103], v[178:181], v[202:205], v[100:103]
	v_mfma_f32_16x16x32_bf16 v[92:95], v[186:189], v[202:205], v[92:95]
	v_mfma_f32_16x16x32_bf16 v[84:87], v[178:181], v[210:213], v[84:87]
	v_mfma_f32_16x16x32_bf16 v[76:79], v[186:189], v[210:213], v[76:79]
	v_mfma_f32_16x16x32_bf16 v[68:71], v[178:181], v[218:221], v[68:71]
	v_mfma_f32_16x16x32_bf16 v[64:67], v[186:189], v[218:221], v[64:67]
	s_setprio 0
	s_barrier
	s_add_i32 s43, s35, s24
	v_lshl_add_u64 v[222:223], s[16:17], 0, v[130:131]
	s_mov_b32 m0, s43
	ds_read_b128 v[190:193], v150 offset:16384
	ds_read_b128 v[194:197], v150 offset:17408
	ds_read_b128 v[198:201], v150 offset:18432
	ds_read_b128 v[202:205], v150 offset:19456
	ds_read_b128 v[206:209], v150 offset:20480
	ds_read_b128 v[210:213], v150 offset:21504
	ds_read_b128 v[214:217], v150 offset:22528
	ds_read_b128 v[218:221], v150 offset:23552
	global_load_lds_dwordx4 v[222:223], off
	s_add_i32 m0, s43, 0x2000
	s_add_u32 s44, s16, 0xb0000
	v_lshl_add_u64 v[224:225], s[16:17], 0, v[134:135]
	s_addc_u32 s45, s17, 0
	s_add_i32 s43, s36, s24
	global_load_lds_dwordx4 v[224:225], off
	v_lshl_add_u64 v[226:227], s[44:45], 0, v[130:131]
	s_mov_b32 m0, s43
	v_lshl_add_u64 v[228:229], s[18:19], 0, v[132:133]
	global_load_lds_dwordx4 v[226:227], off
	v_lshl_add_u64 v[226:227], s[44:45], 0, v[134:135]
	s_add_i32 m0, s43, 0x2000
	s_nop 0
	global_load_lds_dwordx4 v[226:227], off
	v_lshl_add_u64 v[226:227], s[18:19], 0, v[128:129]
	s_mov_b32 m0, s26
	s_nop 0
	global_load_lds_dwordx4 v[226:227], off
	s_mov_b32 m0, s27
	s_nop 0
	global_load_lds_dwordx4 v[228:229], off
	s_waitcnt vmcnt(8)
	s_waitcnt lgkmcnt(0)
	s_barrier
; #define PG8_STAGE(bufoff, gbase, voff) do { _Pragma("unroll") for (int _i = 0; _i < 2; ++_i) \
;         __builtin_amdgcn_global_load_lds((const unsigned*)((const char*)(gbase) + (voff)[_i]), (PG8_LAS unsigned*)(lds + (bufoff) + ldsw + _i * 8192), 16, 0, 0); } while (0)
; #define PG8_LDA(dst, b, h) do { _Pragma("unroll") for (int m = 0; m < 4; ++m) _Pragma("unroll") for (int k = 0; k < 2; ++k) dst[m][k] = *(const PG8_LAS bf16x8*)(lds + PG8_SA(b, h) + aoff + m * 2048 + k * 1024); } while (0)
; #define PG8_LDB(dst, b, h) do { _Pragma("unroll") for (int n = 0; n < 2; ++n) _Pragma("unroll") for (int k = 0; k < 2; ++k) dst[n][k] = *(const PG8_LAS bf16x8*)(lds + PG8_SB(b, h) + boff + n * 2048 + k * 1024); } while (0)
; #define PG8_MMA(ai, bj, At, Bt) do { __builtin_amdgcn_s_setprio(1); _Pragma("unroll") for (int m = 0; m < 4; ++m) _Pragma("unroll") for (int n = 0; n < 2; ++n) _Pragma("unroll") for (int k = 0; k < 2; ++k) \
;         acc[ai][bj][m][n] = __builtin_amdgcn_mfma_f32_16x16x32_bf16(Bt[n][k], At[m][k], acc[ai][bj][m][n], 0, 0, 0); __builtin_amdgcn_s_setprio(0); } while (0)
; #define PG8_WAIT_V(n) asm volatile("s_waitcnt vmcnt(" #n ")" ::: "memory")
; #define PG8_WAIT_L(n) asm volatile("s_waitcnt lgkmcnt(" #n ")" ::: "memory")
; #define PG8_BAR __builtin_amdgcn_s_barrier()
; #define PG8_SCHED __builtin_amdgcn_sched_barrier(0)
; template <class Epi, class Sched, bool ALIGN_EPI = false, bool SP2 = false>
; __device__ __forceinline__ void gemm_phase(PG8_LAS unsigned char* lds, const Gemm g, const Sched& S, const Epi& E, const int wid) {
;     ...
;             PG8_WAIT_V(8); PG8_WAIT_L(0); PG8_BAR; PG8_MMA(1, 0, At, B0); PG8_MMA(1, 1, At, B1); PG8_BAR; PG8_SCHED;
;             PG8_LDB(B0, 1, 0); PG8_LDB(B1, 1, 1); PG8_SCHED; PG8_LDA(At, 1, 0); PG8_STAGE(PG8_SA(0, 1), a2 + hstep, voffA);
;             PG8_WAIT_V(8); PG8_WAIT_L(0); PG8_BAR; PG8_MMA(0, 0, At, B0); PG8_MMA(0, 1, At, B1); PG8_BAR; PG8_SCHED;
	s_setprio 1
	s_waitcnt lgkmcnt(0)
	v_mfma_f32_16x16x32_bf16 v[60:63], v[152:155], v[190:193], v[60:63]
	v_mfma_f32_16x16x32_bf16 v[56:59], v[160:163], v[190:193], v[56:59]
	v_mfma_f32_16x16x32_bf16 v[44:47], v[152:155], v[198:201], v[44:47]
	v_mfma_f32_16x16x32_bf16 v[40:43], v[160:163], v[198:201], v[40:43]
	v_mfma_f32_16x16x32_bf16 v[28:31], v[152:155], v[206:209], v[28:31]
	v_mfma_f32_16x16x32_bf16 v[24:27], v[160:163], v[206:209], v[24:27]
	v_mfma_f32_16x16x32_bf16 v[12:15], v[152:155], v[214:217], v[12:15]
	v_mfma_f32_16x16x32_bf16 v[8:11], v[160:163], v[214:217], v[8:11]
	v_mfma_f32_16x16x32_bf16 v[60:63], v[156:159], v[194:197], v[60:63]
	v_mfma_f32_16x16x32_bf16 v[56:59], v[168:171], v[194:197], v[56:59]
	v_mfma_f32_16x16x32_bf16 v[44:47], v[156:159], v[202:205], v[44:47]
	v_mfma_f32_16x16x32_bf16 v[40:43], v[168:171], v[202:205], v[40:43]
	v_mfma_f32_16x16x32_bf16 v[28:31], v[156:159], v[210:213], v[28:31]
	v_mfma_f32_16x16x32_bf16 v[24:27], v[168:171], v[210:213], v[24:27]
	v_mfma_f32_16x16x32_bf16 v[12:15], v[156:159], v[218:221], v[12:15]
	v_mfma_f32_16x16x32_bf16 v[8:11], v[168:171], v[218:221], v[8:11]
	s_setprio 0
	s_setprio 1
	v_mfma_f32_16x16x32_bf16 v[52:55], v[172:175], v[190:193], v[52:55]
	v_mfma_f32_16x16x32_bf16 v[48:51], v[182:185], v[190:193], v[48:51]
	v_mfma_f32_16x16x32_bf16 v[36:39], v[172:175], v[198:201], v[36:39]
	v_mfma_f32_16x16x32_bf16 v[32:35], v[182:185], v[198:201], v[32:35]
	v_mfma_f32_16x16x32_bf16 v[20:23], v[172:175], v[206:209], v[20:23]
	v_mfma_f32_16x16x32_bf16 v[16:19], v[182:185], v[206:209], v[16:19]
	v_mfma_f32_16x16x32_bf16 v[4:7], v[172:175], v[214:217], v[4:7]
	v_mfma_f32_16x16x32_bf16 v[0:3], v[182:185], v[214:217], v[0:3]
	v_mfma_f32_16x16x32_bf16 v[52:55], v[178:181], v[194:197], v[52:55]
	v_mfma_f32_16x16x32_bf16 v[48:51], v[186:189], v[194:197], v[48:51]
	v_mfma_f32_16x16x32_bf16 v[36:39], v[178:181], v[202:205], v[36:39]
	v_mfma_f32_16x16x32_bf16 v[32:35], v[186:189], v[202:205], v[32:35]
	v_mfma_f32_16x16x32_bf16 v[20:23], v[178:181], v[210:213], v[20:23]
	v_mfma_f32_16x16x32_bf16 v[16:19], v[186:189], v[210:213], v[16:19]
	v_mfma_f32_16x16x32_bf16 v[4:7], v[178:181], v[218:221], v[4:7]
	v_mfma_f32_16x16x32_bf16 v[0:3], v[186:189], v[218:221], v[0:3]
	s_setprio 0
	s_barrier
	s_add_i32 s43, 0, 0x18000
	v_add_u32_e32 v151, s43, v149
	s_add_i32 s44, 0, 0x1c000
	ds_read_b128 v[152:155], v151
	ds_read_b128 v[156:159], v151 offset:1024
	ds_read_b128 v[160:163], v151 offset:2048
	ds_read_b128 v[168:171], v151 offset:3072
	v_add_u32_e32 v151, s44, v149
	ds_read_b128 v[172:175], v151
	ds_read_b128 v[178:181], v151 offset:1024
	ds_read_b128 v[182:185], v151 offset:2048
	ds_read_b128 v[186:189], v151 offset:3072
	s_add_u32 s18, s18, 0xb0000
	s_addc_u32 s19, s19, 0
	s_mov_b32 m0, s28
	v_lshl_add_u64 v[230:231], s[18:19], 0, v[128:129]
	ds_read_b128 v[190:193], v150 offset:32768
	ds_read_b128 v[194:197], v150 offset:33792
	ds_read_b128 v[198:201], v150 offset:34816
	ds_read_b128 v[202:205], v150 offset:35840
	ds_read_b128 v[206:209], v150 offset:36864
	ds_read_b128 v[210:213], v150 offset:37888
	ds_read_b128 v[214:217], v150 offset:38912
	ds_read_b128 v[218:221], v150 offset:39936
	global_load_lds_dwordx4 v[230:231], off
	v_lshl_add_u64 v[230:231], s[18:19], 0, v[132:133]
	s_mov_b32 m0, s29
	s_nop 0
	global_load_lds_dwordx4 v[230:231], off
	s_waitcnt vmcnt(8)
	s_waitcnt lgkmcnt(0)
	s_barrier
	s_setprio 1
	s_waitcnt lgkmcnt(0)
	v_mfma_f32_16x16x32_bf16 v[124:127], v[152:155], v[190:193], v[124:127]
	v_mfma_f32_16x16x32_bf16 v[120:123], v[160:163], v[190:193], v[120:123]
	v_mfma_f32_16x16x32_bf16 v[112:115], v[152:155], v[198:201], v[112:115]
	v_mfma_f32_16x16x32_bf16 v[104:107], v[160:163], v[198:201], v[104:107]
	v_mfma_f32_16x16x32_bf16 v[96:99], v[152:155], v[206:209], v[96:99]
	v_mfma_f32_16x16x32_bf16 v[88:91], v[160:163], v[206:209], v[88:91]
	v_mfma_f32_16x16x32_bf16 v[80:83], v[152:155], v[214:217], v[80:83]
	v_mfma_f32_16x16x32_bf16 v[72:75], v[160:163], v[214:217], v[72:75]
	v_mfma_f32_16x16x32_bf16 v[124:127], v[156:159], v[194:197], v[124:127]
	v_mfma_f32_16x16x32_bf16 v[120:123], v[168:171], v[194:197], v[120:123]
	v_mfma_f32_16x16x32_bf16 v[112:115], v[156:159], v[202:205], v[112:115]
	v_mfma_f32_16x16x32_bf16 v[104:107], v[168:171], v[202:205], v[104:107]
	v_mfma_f32_16x16x32_bf16 v[96:99], v[156:159], v[210:213], v[96:99]
	v_mfma_f32_16x16x32_bf16 v[88:91], v[168:171], v[210:213], v[88:91]
	v_mfma_f32_16x16x32_bf16 v[80:83], v[156:159], v[218:221], v[80:83]
	v_mfma_f32_16x16x32_bf16 v[72:75], v[168:171], v[218:221], v[72:75]
	s_setprio 0
	s_setprio 1
	v_mfma_f32_16x16x32_bf16 v[116:119], v[172:175], v[190:193], v[116:119]
	v_mfma_f32_16x16x32_bf16 v[108:111], v[182:185], v[190:193], v[108:111]
	v_mfma_f32_16x16x32_bf16 v[100:103], v[172:175], v[198:201], v[100:103]
	v_mfma_f32_16x16x32_bf16 v[92:95], v[182:185], v[198:201], v[92:95]
	v_mfma_f32_16x16x32_bf16 v[84:87], v[172:175], v[206:209], v[84:87]
	v_mfma_f32_16x16x32_bf16 v[76:79], v[182:185], v[206:209], v[76:79]
	v_mfma_f32_16x16x32_bf16 v[68:71], v[172:175], v[214:217], v[68:71]
	v_mfma_f32_16x16x32_bf16 v[64:67], v[182:185], v[214:217], v[64:67]
	v_mfma_f32_16x16x32_bf16 v[116:119], v[178:181], v[194:197], v[116:119]
	v_mfma_f32_16x16x32_bf16 v[108:111], v[186:189], v[194:197], v[108:111]
	v_mfma_f32_16x16x32_bf16 v[100:103], v[178:181], v[202:205], v[100:103]
	v_mfma_f32_16x16x32_bf16 v[92:95], v[186:189], v[202:205], v[92:95]
	v_mfma_f32_16x16x32_bf16 v[84:87], v[178:181], v[210:213], v[84:87]
	v_mfma_f32_16x16x32_bf16 v[76:79], v[186:189], v[210:213], v[76:79]
	v_mfma_f32_16x16x32_bf16 v[68:71], v[178:181], v[218:221], v[68:71]
	v_mfma_f32_16x16x32_bf16 v[64:67], v[186:189], v[218:221], v[64:67]
	s_setprio 0
	s_barrier
; #define PG8_STAGE(bufoff, gbase, voff) do { _Pragma("unroll") for (int _i = 0; _i < 2; ++_i) \
;         __builtin_amdgcn_global_load_lds((const unsigned*)((const char*)(gbase) + (voff)[_i]), (PG8_LAS unsigned*)(lds + (bufoff) + ldsw + _i * 8192), 16, 0, 0); } while (0)
; #define PG8_LDA(dst, b, h) do { _Pragma("unroll") for (int m = 0; m < 4; ++m) _Pragma("unroll") for (int k = 0; k < 2; ++k) dst[m][k] = *(const PG8_LAS bf16x8*)(lds + PG8_SA(b, h) + aoff + m * 2048 + k * 1024); } while (0)
; #define PG8_MMA(ai, bj, At, Bt) do { __builtin_amdgcn_s_setprio(1); _Pragma("unroll") for (int m = 0; m < 4; ++m) _Pragma("unroll") for (int n = 0; n < 2; ++n) _Pragma("unroll") for (int k = 0; k < 2; ++k) \
;         acc[ai][bj][m][n] = __builtin_amdgcn_mfma_f32_16x16x32_bf16(Bt[n][k], At[m][k], acc[ai][bj][m][n], 0, 0, 0); __builtin_amdgcn_s_setprio(0); } while (0)
; #define PG8_WAIT_V(n) asm volatile("s_waitcnt vmcnt(" #n ")" ::: "memory")
; #define PG8_WAIT_L(n) asm volatile("s_waitcnt lgkmcnt(" #n ")" ::: "memory")
; #define PG8_BAR __builtin_amdgcn_s_barrier()
; #define PG8_SCHED __builtin_amdgcn_sched_barrier(0)
; template <class Epi, class Sched, bool ALIGN_EPI = false, bool SP2 = false>
; __device__ __forceinline__ void gemm_phase(PG8_LAS unsigned char* lds, const Gemm g, const Sched& S, const Epi& E, const int wid) {
;     ...
;             PG8_LDA(At, 1, 1); PG8_STAGE(PG8_SB(1, 0), b3, voffB); PG8_STAGE(PG8_SB(1, 1), b3 + hstep, voffB); PG8_STAGE(PG8_SA(1, 0), a3, voffA);
;             PG8_WAIT_V(8); PG8_WAIT_L(0); PG8_BAR; PG8_MMA(1, 0, At, B0); PG8_MMA(1, 1, At, B1); PG8_BAR; PG8_SCHED;
;     ...
; #pragma unroll
;         for (int a = 0; a < 2; ++a)
; #pragma unroll
;             for (int b = 0; b < 2; ++b)
; #pragma unroll
;                 for (int m = 0; m < 4; ++m)
; #pragma unroll
;                     for (int n = 0; n < 2; ++n) acc[a][b][m][n] = (f32x4){0.f, 0.f, 0.f, 0.f};
	s_add_i32 s18, s43, s24
	v_lshl_add_u64 v[222:223], v[222:223], 0, s[10:11]
	s_mov_b32 m0, s18
	ds_read_b128 v[190:193], v150 offset:49152
	ds_read_b128 v[194:197], v150 offset:50176
	ds_read_b128 v[198:201], v150 offset:51200
	ds_read_b128 v[202:205], v150 offset:52224
	ds_read_b128 v[206:209], v150 offset:53248
	ds_read_b128 v[210:213], v150 offset:54272
	ds_read_b128 v[214:217], v150 offset:55296
	ds_read_b128 v[218:221], v150 offset:56320
	global_load_lds_dwordx4 v[222:223], off
	s_add_i32 m0, s18, 0x2000
	s_add_u32 s16, s16, 0xb0080
	v_lshl_add_u64 v[222:223], v[224:225], 0, s[10:11]
	s_addc_u32 s17, s17, 0
	s_add_i32 s18, s44, s24
	global_load_lds_dwordx4 v[222:223], off
	v_lshl_add_u64 v[222:223], s[16:17], 0, v[130:131]
	s_mov_b32 m0, s18
	s_nop 0
	global_load_lds_dwordx4 v[222:223], off
	v_lshl_add_u64 v[222:223], s[16:17], 0, v[134:135]
	s_add_i32 m0, s18, 0x2000
	s_nop 0
	global_load_lds_dwordx4 v[222:223], off
	v_lshl_add_u64 v[222:223], v[226:227], 0, s[10:11]
	s_mov_b32 m0, s31
	s_nop 0
	global_load_lds_dwordx4 v[222:223], off
	v_lshl_add_u64 v[222:223], v[228:229], 0, s[10:11]
	s_mov_b32 m0, s33
	s_nop 0
	global_load_lds_dwordx4 v[222:223], off
	s_waitcnt vmcnt(8)
	s_waitcnt lgkmcnt(0)
	s_barrier
	s_setprio 1
	s_waitcnt lgkmcnt(0)
	v_mfma_f32_16x16x32_bf16 v[60:63], v[152:155], v[190:193], v[60:63]
	v_mfma_f32_16x16x32_bf16 v[56:59], v[160:163], v[190:193], v[56:59]
	v_mfma_f32_16x16x32_bf16 v[44:47], v[152:155], v[198:201], v[44:47]
	v_mfma_f32_16x16x32_bf16 v[40:43], v[160:163], v[198:201], v[40:43]
	v_mfma_f32_16x16x32_bf16 v[28:31], v[152:155], v[206:209], v[28:31]
	v_mfma_f32_16x16x32_bf16 v[24:27], v[160:163], v[206:209], v[24:27]
	v_mfma_f32_16x16x32_bf16 v[12:15], v[152:155], v[214:217], v[12:15]
	v_mfma_f32_16x16x32_bf16 v[8:11], v[160:163], v[214:217], v[8:11]
	v_mfma_f32_16x16x32_bf16 v[60:63], v[156:159], v[194:197], v[60:63]
	v_mfma_f32_16x16x32_bf16 v[56:59], v[168:171], v[194:197], v[56:59]
	v_mfma_f32_16x16x32_bf16 v[44:47], v[156:159], v[202:205], v[44:47]
	v_mfma_f32_16x16x32_bf16 v[40:43], v[168:171], v[202:205], v[40:43]
	v_mfma_f32_16x16x32_bf16 v[28:31], v[156:159], v[210:213], v[28:31]
	v_mfma_f32_16x16x32_bf16 v[24:27], v[168:171], v[210:213], v[24:27]
	v_mfma_f32_16x16x32_bf16 v[12:15], v[156:159], v[218:221], v[12:15]
	v_mfma_f32_16x16x32_bf16 v[8:11], v[168:171], v[218:221], v[8:11]
	s_setprio 0
	s_setprio 1
	v_mfma_f32_16x16x32_bf16 v[52:55], v[172:175], v[190:193], v[52:55]
	v_mfma_f32_16x16x32_bf16 v[48:51], v[182:185], v[190:193], v[48:51]
	v_mfma_f32_16x16x32_bf16 v[36:39], v[172:175], v[198:201], v[36:39]
	v_mfma_f32_16x16x32_bf16 v[32:35], v[182:185], v[198:201], v[32:35]
	v_mfma_f32_16x16x32_bf16 v[20:23], v[172:175], v[206:209], v[20:23]
	v_mfma_f32_16x16x32_bf16 v[16:19], v[182:185], v[206:209], v[16:19]
	v_mfma_f32_16x16x32_bf16 v[4:7], v[172:175], v[214:217], v[4:7]
	v_mfma_f32_16x16x32_bf16 v[0:3], v[182:185], v[214:217], v[0:3]
	v_mfma_f32_16x16x32_bf16 v[52:55], v[178:181], v[194:197], v[52:55]
	v_mfma_f32_16x16x32_bf16 v[48:51], v[186:189], v[194:197], v[48:51]
	v_mfma_f32_16x16x32_bf16 v[36:39], v[178:181], v[202:205], v[36:39]
	v_mfma_f32_16x16x32_bf16 v[32:35], v[186:189], v[202:205], v[32:35]
	v_mfma_f32_16x16x32_bf16 v[20:23], v[178:181], v[210:213], v[20:23]
	v_mfma_f32_16x16x32_bf16 v[16:19], v[186:189], v[210:213], v[16:19]
	v_mfma_f32_16x16x32_bf16 v[4:7], v[178:181], v[218:221], v[4:7]
	v_mfma_f32_16x16x32_bf16 v[0:3], v[186:189], v[218:221], v[0:3]
	s_setprio 0
	s_add_i32 s42, s42, 2
	s_add_u32 s14, s14, 0x100
	s_addc_u32 s15, s15, 0
	s_cmp_gt_u32 s42, 41
	s_barrier
	s_cbranch_scc0 .LBB0_2460
	s_add_u32 s14, s40, 0xffffff00
	s_addc_u32 s15, s41, -1
	s_and_b64 vcc, exec, s[6:7]
	s_cbranch_vccnz .LBB0_2447
	v_mov_b32_e32 v0, 0
	s_mov_b32 s2, s37
	s_mov_b32 s20, s38
	s_mov_b64 s[8:9], s[12:13]
	s_mov_b32 s34, s39
	v_mov_b32_e32 v1, v0
	v_mov_b32_e32 v2, v0
	v_mov_b32_e32 v3, v0
	v_mov_b32_e32 v4, v0
	v_mov_b32_e32 v5, v0
	v_mov_b32_e32 v6, v0
	v_mov_b32_e32 v7, v0
	v_mov_b32_e32 v16, v0
	v_mov_b32_e32 v17, v0
	v_mov_b32_e32 v18, v0
	v_mov_b32_e32 v19, v0
	v_mov_b32_e32 v20, v0
	v_mov_b32_e32 v21, v0
	v_mov_b32_e32 v22, v0
	v_mov_b32_e32 v23, v0
	v_mov_b32_e32 v32, v0
	v_mov_b32_e32 v33, v0
	v_mov_b32_e32 v34, v0
	v_mov_b32_e32 v35, v0
	v_mov_b32_e32 v36, v0
	v_mov_b32_e32 v37, v0
	v_mov_b32_e32 v38, v0
	v_mov_b32_e32 v39, v0
	v_mov_b32_e32 v48, v0
	v_mov_b32_e32 v49, v0
	v_mov_b32_e32 v50, v0
	v_mov_b32_e32 v51, v0
	v_mov_b32_e32 v52, v0
	v_mov_b32_e32 v53, v0
	v_mov_b32_e32 v54, v0
	v_mov_b32_e32 v55, v0
	v_mov_b32_e32 v8, v0
	v_mov_b32_e32 v9, v0
	v_mov_b32_e32 v10, v0
	v_mov_b32_e32 v11, v0
	v_mov_b32_e32 v12, v0
	v_mov_b32_e32 v13, v0
	v_mov_b32_e32 v14, v0
	v_mov_b32_e32 v15, v0
	v_mov_b32_e32 v24, v0
	v_mov_b32_e32 v25, v0
	v_mov_b32_e32 v26, v0
	v_mov_b32_e32 v27, v0
	v_mov_b32_e32 v28, v0
	v_mov_b32_e32 v29, v0
	v_mov_b32_e32 v30, v0
	v_mov_b32_e32 v31, v0
	v_mov_b32_e32 v40, v0
	v_mov_b32_e32 v41, v0
	v_mov_b32_e32 v42, v0
	v_mov_b32_e32 v43, v0
	v_mov_b32_e32 v44, v0
	v_mov_b32_e32 v45, v0
	v_mov_b32_e32 v46, v0
	v_mov_b32_e32 v47, v0
	v_mov_b32_e32 v56, v0
	v_mov_b32_e32 v57, v0
	v_mov_b32_e32 v58, v0
	v_mov_b32_e32 v59, v0
	v_mov_b32_e32 v60, v0
	v_mov_b32_e32 v61, v0
	v_mov_b32_e32 v62, v0
	v_mov_b32_e32 v63, v0
	v_mov_b32_e32 v64, v0
	v_mov_b32_e32 v65, v0
	v_mov_b32_e32 v66, v0
	v_mov_b32_e32 v67, v0
	v_mov_b32_e32 v68, v0
	v_mov_b32_e32 v69, v0
	v_mov_b32_e32 v70, v0
	v_mov_b32_e32 v71, v0
	v_mov_b32_e32 v76, v0
	v_mov_b32_e32 v77, v0
	v_mov_b32_e32 v78, v0
	v_mov_b32_e32 v79, v0
	v_mov_b32_e32 v84, v0
	v_mov_b32_e32 v85, v0
	v_mov_b32_e32 v86, v0
	v_mov_b32_e32 v87, v0
	v_mov_b32_e32 v92, v0
	v_mov_b32_e32 v93, v0
	v_mov_b32_e32 v94, v0
	v_mov_b32_e32 v95, v0
	v_mov_b32_e32 v100, v0
	v_mov_b32_e32 v101, v0
	v_mov_b32_e32 v102, v0
	v_mov_b32_e32 v103, v0
	v_mov_b32_e32 v108, v0
	v_mov_b32_e32 v109, v0
	v_mov_b32_e32 v110, v0
	v_mov_b32_e32 v111, v0
	v_mov_b32_e32 v116, v0
	v_mov_b32_e32 v117, v0
	v_mov_b32_e32 v118, v0
	v_mov_b32_e32 v119, v0
	v_mov_b32_e32 v72, v0
	v_mov_b32_e32 v73, v0
	v_mov_b32_e32 v74, v0
	v_mov_b32_e32 v75, v0
	v_mov_b32_e32 v80, v0
	v_mov_b32_e32 v81, v0
	v_mov_b32_e32 v82, v0
	v_mov_b32_e32 v83, v0
	v_mov_b32_e32 v88, v0
	v_mov_b32_e32 v89, v0
	v_mov_b32_e32 v90, v0
	v_mov_b32_e32 v91, v0
	v_mov_b32_e32 v96, v0
	v_mov_b32_e32 v97, v0
	v_mov_b32_e32 v98, v0
	v_mov_b32_e32 v99, v0
	v_mov_b32_e32 v104, v0
	v_mov_b32_e32 v105, v0
	v_mov_b32_e32 v106, v0
	v_mov_b32_e32 v107, v0
	v_mov_b32_e32 v112, v0
	v_mov_b32_e32 v113, v0
	v_mov_b32_e32 v114, v0
	v_mov_b32_e32 v115, v0
	v_mov_b32_e32 v120, v0
	v_mov_b32_e32 v121, v0
	v_mov_b32_e32 v122, v0
	v_mov_b32_e32 v123, v0
	v_mov_b32_e32 v124, v0
	v_mov_b32_e32 v125, v0
	v_mov_b32_e32 v126, v0
	v_mov_b32_e32 v127, v0
	s_andn2_b64 vcc, exec, s[0:1]
	s_cbranch_vccnz .LBB0_2448
